# GEMM MMA blocks: removed the second (already satisfied) s_waitcnt lgkmcnt(0) after each pre-MMA barrier, 28 sites; on top of v40
# speedup vs baseline: 1.0048x; 1.0040x over previous
; #define PG8_STAGE(bufoff, gbase, voff) do { _Pragma("unroll") for (int _i = 0; _i < 2; ++_i) \
;         __builtin_amdgcn_global_load_lds((const unsigned*)((const char*)(gbase) + (voff)[_i]), (PG8_LAS unsigned*)(lds + (bufoff) + ldsw + _i * 8192), 16, 0, 0); } while (0)
; #define PG8_LDA(dst, b, h) do { _Pragma("unroll") for (int m = 0; m < 4; ++m) _Pragma("unroll") for (int k = 0; k < 2; ++k) dst[m][k] = *(const PG8_LAS bf16x8*)(lds + PG8_SA(b, h) + aoff + m * 2048 + k * 1024); } while (0)
; #define PG8_LDB(dst, b, h) do { _Pragma("unroll") for (int n = 0; n < 2; ++n) _Pragma("unroll") for (int k = 0; k < 2; ++k) dst[n][k] = *(const PG8_LAS bf16x8*)(lds + PG8_SB(b, h) + boff + n * 2048 + k * 1024); } while (0)
; #define PG8_MMA(ai, bj, At, Bt) do { __builtin_amdgcn_s_setprio(1); _Pragma("unroll") for (int m = 0; m < 4; ++m) _Pragma("unroll") for (int n = 0; n < 2; ++n) _Pragma("unroll") for (int k = 0; k < 2; ++k) \
;         acc[ai][bj][m][n] = __builtin_amdgcn_mfma_f32_16x16x32_bf16(Bt[n][k], At[m][k], acc[ai][bj][m][n], 0, 0, 0); __builtin_amdgcn_s_setprio(0); } while (0)
; #define PG8_WAIT_V(n) asm volatile("s_waitcnt vmcnt(" #n ")" ::: "memory")
; #define PG8_WAIT_L(n) asm volatile("s_waitcnt lgkmcnt(" #n ")" ::: "memory")
; #define PG8_BAR __builtin_amdgcn_s_barrier()
; #define PG8_SCHED __builtin_amdgcn_sched_barrier(0)
; template <class Epi, class Sched, bool ALIGN_EPI = false, bool SP2 = false>
; __device__ __forceinline__ void gemm_phase(PG8_LAS unsigned char* lds, const Gemm g, const Sched& S, const Epi& E) {
;     ...
;             PG8_LDB(B0, 0, 0); PG8_LDB(B1, 0, 1); PG8_SCHED; PG8_LDA(At, 0, 0); PG8_STAGE(PG8_SA(1, 1), a1 + hstep, voffA);
;             PG8_WAIT_V(8); PG8_WAIT_L(0); PG8_BAR; PG8_MMA(0, 0, At, B0); PG8_MMA(0, 1, At, B1); PG8_BAR; PG8_SCHED;
;             PG8_LDA(At, 0, 1); PG8_STAGE(PG8_SB(0, 0), b2, voffB); PG8_STAGE(PG8_SB(0, 1), b2 + hstep, voffB); PG8_STAGE(PG8_SA(0, 0), a2, voffA);
;             PG8_WAIT_V(8); PG8_WAIT_L(0); PG8_BAR; PG8_MMA(1, 0, At, B0); PG8_MMA(1, 1, At, B1); PG8_BAR; PG8_SCHED;
.LBB0_148:
	ds_read_b128 v[146:149], v164
	ds_read_b128 v[170:173], v164 offset:1024
	ds_read_b128 v[174:177], v164 offset:2048
	ds_read_b128 v[178:181], v164 offset:3072
	ds_read_b128 v[182:185], v165
	ds_read_b128 v[186:189], v165 offset:1024
	ds_read_b128 v[190:193], v165 offset:2048
	ds_read_b128 v[194:197], v165 offset:3072
	s_add_u32 s38, s6, 0xfffc0080
	s_addc_u32 s39, s7, -1
	s_cmp_eq_u32 s84, 12
	s_cselect_b32 s41, s9, s39
	s_cselect_b32 s40, s11, s38
	s_cselect_b32 s39, s29, s83
	s_cselect_b32 s38, s31, s82
	v_lshl_add_u64 v[150:151], s[6:7], 0, v[138:139]
	s_add_i32 m0, s44, 0xc000
	ds_read_b128 v[198:201], v166
	ds_read_b128 v[202:205], v166 offset:1024
	ds_read_b128 v[206:209], v166 offset:2048
	ds_read_b128 v[214:217], v166 offset:3072
	ds_read_b128 v[218:221], v166 offset:4096
	ds_read_b128 v[222:225], v166 offset:5120
	ds_read_b128 v[226:229], v166 offset:6144
	ds_read_b128 v[230:233], v166 offset:7168
	global_load_lds_dwordx4 v[150:151], off
	v_lshl_add_u64 v[150:151], s[6:7], 0, v[140:141]
	s_add_i32 m0, s44, 0xe000
	s_nop 0
	global_load_lds_dwordx4 v[150:151], off
	s_waitcnt vmcnt(8)
	s_waitcnt lgkmcnt(0)
	s_barrier
	s_setprio 1
	v_mfma_f32_16x16x32_bf16 v[124:127], v[146:149], v[198:201], v[124:127]
	v_mfma_f32_16x16x32_bf16 v[120:123], v[174:177], v[198:201], v[120:123]
	v_mfma_f32_16x16x32_bf16 v[108:111], v[146:149], v[206:209], v[108:111]
	v_mfma_f32_16x16x32_bf16 v[104:107], v[174:177], v[206:209], v[104:107]
	v_mfma_f32_16x16x32_bf16 v[92:95], v[146:149], v[218:221], v[92:95]
	v_mfma_f32_16x16x32_bf16 v[88:91], v[174:177], v[218:221], v[88:91]
	v_mfma_f32_16x16x32_bf16 v[76:79], v[146:149], v[226:229], v[76:79]
	v_mfma_f32_16x16x32_bf16 v[72:75], v[174:177], v[226:229], v[72:75]
	v_mfma_f32_16x16x32_bf16 v[124:127], v[170:173], v[202:205], v[124:127]
	v_mfma_f32_16x16x32_bf16 v[120:123], v[178:181], v[202:205], v[120:123]
	v_mfma_f32_16x16x32_bf16 v[108:111], v[170:173], v[214:217], v[108:111]
	v_mfma_f32_16x16x32_bf16 v[104:107], v[178:181], v[214:217], v[104:107]
	v_mfma_f32_16x16x32_bf16 v[92:95], v[170:173], v[222:225], v[92:95]
	v_mfma_f32_16x16x32_bf16 v[88:91], v[178:181], v[222:225], v[88:91]
	v_mfma_f32_16x16x32_bf16 v[76:79], v[170:173], v[230:233], v[76:79]
	v_mfma_f32_16x16x32_bf16 v[72:75], v[178:181], v[230:233], v[72:75]
	s_setprio 0
	s_setprio 1
	v_mfma_f32_16x16x32_bf16 v[116:119], v[182:185], v[198:201], v[116:119]
	v_mfma_f32_16x16x32_bf16 v[112:115], v[190:193], v[198:201], v[112:115]
	v_mfma_f32_16x16x32_bf16 v[100:103], v[182:185], v[206:209], v[100:103]
	v_mfma_f32_16x16x32_bf16 v[96:99], v[190:193], v[206:209], v[96:99]
	v_mfma_f32_16x16x32_bf16 v[84:87], v[182:185], v[218:221], v[84:87]
	v_mfma_f32_16x16x32_bf16 v[80:83], v[190:193], v[218:221], v[80:83]
	v_mfma_f32_16x16x32_bf16 v[68:71], v[182:185], v[226:229], v[68:71]
	v_mfma_f32_16x16x32_bf16 v[64:67], v[190:193], v[226:229], v[64:67]
	v_mfma_f32_16x16x32_bf16 v[116:119], v[186:189], v[202:205], v[116:119]
	v_mfma_f32_16x16x32_bf16 v[112:115], v[194:197], v[202:205], v[112:115]
	v_mfma_f32_16x16x32_bf16 v[100:103], v[186:189], v[214:217], v[100:103]
	v_mfma_f32_16x16x32_bf16 v[96:99], v[194:197], v[214:217], v[96:99]
	v_mfma_f32_16x16x32_bf16 v[84:87], v[186:189], v[222:225], v[84:87]
	v_mfma_f32_16x16x32_bf16 v[80:83], v[194:197], v[222:225], v[80:83]
	v_mfma_f32_16x16x32_bf16 v[68:71], v[186:189], v[230:233], v[68:71]
	v_mfma_f32_16x16x32_bf16 v[64:67], v[194:197], v[230:233], v[64:67]
	s_setprio 0
	s_barrier
	s_add_i32 s85, s79, s19
	v_lshl_add_u64 v[150:151], s[38:39], 0, v[130:131]
	s_mov_b32 m0, s85
	ds_read_b128 v[198:201], v166 offset:16384
	ds_read_b128 v[202:205], v166 offset:17408
	ds_read_b128 v[206:209], v166 offset:18432
	ds_read_b128 v[214:217], v166 offset:19456
	ds_read_b128 v[218:221], v166 offset:20480
	ds_read_b128 v[222:225], v166 offset:21504
	ds_read_b128 v[226:229], v166 offset:22528
	ds_read_b128 v[230:233], v166 offset:23552
	global_load_lds_dwordx4 v[150:151], off
	s_add_i32 m0, s85, 0x2000
	s_add_u32 s90, s38, 0x40000
	v_lshl_add_u64 v[154:155], s[38:39], 0, v[134:135]
	s_addc_u32 s91, s39, 0
	s_add_i32 s85, s80, s19
	global_load_lds_dwordx4 v[154:155], off
	v_lshl_add_u64 v[210:211], s[90:91], 0, v[130:131]
	s_mov_b32 m0, s85
	v_lshl_add_u64 v[234:235], s[40:41], 0, v[132:133]
	global_load_lds_dwordx4 v[210:211], off
	v_lshl_add_u64 v[210:211], s[90:91], 0, v[134:135]
	s_add_i32 m0, s85, 0x2000
	s_nop 0
	global_load_lds_dwordx4 v[210:211], off
	v_lshl_add_u64 v[210:211], s[40:41], 0, v[128:129]
	s_mov_b32 m0, s44
	s_nop 0
	global_load_lds_dwordx4 v[210:211], off
	s_mov_b32 m0, s45
	s_nop 0
	global_load_lds_dwordx4 v[234:235], off
	s_waitcnt vmcnt(8)
	s_waitcnt lgkmcnt(0)
	s_barrier
; #define PG8_STAGE(bufoff, gbase, voff) do { _Pragma("unroll") for (int _i = 0; _i < 2; ++_i) \
;         __builtin_amdgcn_global_load_lds((const unsigned*)((const char*)(gbase) + (voff)[_i]), (PG8_LAS unsigned*)(lds + (bufoff) + ldsw + _i * 8192), 16, 0, 0); } while (0)
; #define PG8_LDA(dst, b, h) do { _Pragma("unroll") for (int m = 0; m < 4; ++m) _Pragma("unroll") for (int k = 0; k < 2; ++k) dst[m][k] = *(const PG8_LAS bf16x8*)(lds + PG8_SA(b, h) + aoff + m * 2048 + k * 1024); } while (0)
; #define PG8_LDB(dst, b, h) do { _Pragma("unroll") for (int n = 0; n < 2; ++n) _Pragma("unroll") for (int k = 0; k < 2; ++k) dst[n][k] = *(const PG8_LAS bf16x8*)(lds + PG8_SB(b, h) + boff + n * 2048 + k * 1024); } while (0)
; #define PG8_MMA(ai, bj, At, Bt) do { __builtin_amdgcn_s_setprio(1); _Pragma("unroll") for (int m = 0; m < 4; ++m) _Pragma("unroll") for (int n = 0; n < 2; ++n) _Pragma("unroll") for (int k = 0; k < 2; ++k) \
;         acc[ai][bj][m][n] = __builtin_amdgcn_mfma_f32_16x16x32_bf16(Bt[n][k], At[m][k], acc[ai][bj][m][n], 0, 0, 0); __builtin_amdgcn_s_setprio(0); } while (0)
; #define PG8_WAIT_V(n) asm volatile("s_waitcnt vmcnt(" #n ")" ::: "memory")
; #define PG8_WAIT_L(n) asm volatile("s_waitcnt lgkmcnt(" #n ")" ::: "memory")
; #define PG8_BAR __builtin_amdgcn_s_barrier()
; #define PG8_SCHED __builtin_amdgcn_sched_barrier(0)
; template <class Epi, class Sched, bool ALIGN_EPI = false, bool SP2 = false>
; __device__ __forceinline__ void gemm_phase(PG8_LAS unsigned char* lds, const Gemm g, const Sched& S, const Epi& E) {
;     ...
;             PG8_WAIT_V(8); PG8_WAIT_L(0); PG8_BAR; PG8_MMA(1, 0, At, B0); PG8_MMA(1, 1, At, B1); PG8_BAR; PG8_SCHED;
;             PG8_LDB(B0, 1, 0); PG8_LDB(B1, 1, 1); PG8_SCHED; PG8_LDA(At, 1, 0); PG8_STAGE(PG8_SA(0, 1), a2 + hstep, voffA);
;             PG8_WAIT_V(8); PG8_WAIT_L(0); PG8_BAR; PG8_MMA(0, 0, At, B0); PG8_MMA(0, 1, At, B1); PG8_BAR; PG8_SCHED;
	s_setprio 1
	v_mfma_f32_16x16x32_bf16 v[60:63], v[146:149], v[198:201], v[60:63]
	v_mfma_f32_16x16x32_bf16 v[56:59], v[174:177], v[198:201], v[56:59]
	v_mfma_f32_16x16x32_bf16 v[44:47], v[146:149], v[206:209], v[44:47]
	v_mfma_f32_16x16x32_bf16 v[40:43], v[174:177], v[206:209], v[40:43]
	v_mfma_f32_16x16x32_bf16 v[28:31], v[146:149], v[218:221], v[28:31]
	v_mfma_f32_16x16x32_bf16 v[24:27], v[174:177], v[218:221], v[24:27]
	v_mfma_f32_16x16x32_bf16 v[12:15], v[146:149], v[226:229], v[12:15]
	v_mfma_f32_16x16x32_bf16 v[8:11], v[174:177], v[226:229], v[8:11]
	v_mfma_f32_16x16x32_bf16 v[60:63], v[170:173], v[202:205], v[60:63]
	v_mfma_f32_16x16x32_bf16 v[56:59], v[178:181], v[202:205], v[56:59]
	v_mfma_f32_16x16x32_bf16 v[44:47], v[170:173], v[214:217], v[44:47]
	v_mfma_f32_16x16x32_bf16 v[40:43], v[178:181], v[214:217], v[40:43]
	v_mfma_f32_16x16x32_bf16 v[28:31], v[170:173], v[222:225], v[28:31]
	v_mfma_f32_16x16x32_bf16 v[24:27], v[178:181], v[222:225], v[24:27]
	v_mfma_f32_16x16x32_bf16 v[12:15], v[170:173], v[230:233], v[12:15]
	v_mfma_f32_16x16x32_bf16 v[8:11], v[178:181], v[230:233], v[8:11]
	s_setprio 0
	s_setprio 1
	v_mfma_f32_16x16x32_bf16 v[52:55], v[182:185], v[198:201], v[52:55]
	v_mfma_f32_16x16x32_bf16 v[48:51], v[190:193], v[198:201], v[48:51]
	v_mfma_f32_16x16x32_bf16 v[36:39], v[182:185], v[206:209], v[36:39]
	v_mfma_f32_16x16x32_bf16 v[32:35], v[190:193], v[206:209], v[32:35]
	v_mfma_f32_16x16x32_bf16 v[20:23], v[182:185], v[218:221], v[20:23]
	v_mfma_f32_16x16x32_bf16 v[16:19], v[190:193], v[218:221], v[16:19]
	v_mfma_f32_16x16x32_bf16 v[4:7], v[182:185], v[226:229], v[4:7]
	v_mfma_f32_16x16x32_bf16 v[0:3], v[190:193], v[226:229], v[0:3]
	v_mfma_f32_16x16x32_bf16 v[52:55], v[186:189], v[202:205], v[52:55]
	v_mfma_f32_16x16x32_bf16 v[48:51], v[194:197], v[202:205], v[48:51]
	v_mfma_f32_16x16x32_bf16 v[36:39], v[186:189], v[214:217], v[36:39]
	v_mfma_f32_16x16x32_bf16 v[32:35], v[194:197], v[214:217], v[32:35]
	v_mfma_f32_16x16x32_bf16 v[20:23], v[186:189], v[222:225], v[20:23]
	v_mfma_f32_16x16x32_bf16 v[16:19], v[194:197], v[222:225], v[16:19]
	v_mfma_f32_16x16x32_bf16 v[4:7], v[186:189], v[230:233], v[4:7]
	v_mfma_f32_16x16x32_bf16 v[0:3], v[194:197], v[230:233], v[0:3]
	s_setprio 0
	s_barrier
	s_add_i32 s85, 0, 0x18000
	v_add_u32_e32 v136, s85, v159
	s_add_i32 s86, 0, 0x1c000
	ds_read_b128 v[146:149], v136
	ds_read_b128 v[170:173], v136 offset:1024
	ds_read_b128 v[174:177], v136 offset:2048
	ds_read_b128 v[178:181], v136 offset:3072
	v_add_u32_e32 v136, s86, v159
	ds_read_b128 v[182:185], v136
	ds_read_b128 v[186:189], v136 offset:1024
	ds_read_b128 v[190:193], v136 offset:2048
	ds_read_b128 v[194:197], v136 offset:3072
	s_add_u32 s40, s40, 0x40000
	s_addc_u32 s41, s41, 0
	s_mov_b32 m0, s46
	v_lshl_add_u64 v[236:237], s[40:41], 0, v[128:129]
	ds_read_b128 v[198:201], v166 offset:32768
	ds_read_b128 v[202:205], v166 offset:33792
	ds_read_b128 v[206:209], v166 offset:34816
	ds_read_b128 v[214:217], v166 offset:35840
	ds_read_b128 v[218:221], v166 offset:36864
	ds_read_b128 v[222:225], v166 offset:37888
	ds_read_b128 v[226:229], v166 offset:38912
	ds_read_b128 v[230:233], v166 offset:39936
	global_load_lds_dwordx4 v[236:237], off
	v_lshl_add_u64 v[236:237], s[40:41], 0, v[132:133]
	s_mov_b32 m0, s47
	s_nop 0
	global_load_lds_dwordx4 v[236:237], off
	s_waitcnt vmcnt(8)
	s_waitcnt lgkmcnt(0)
	s_barrier
	s_setprio 1
	v_mfma_f32_16x16x32_bf16 v[124:127], v[146:149], v[198:201], v[124:127]
	v_mfma_f32_16x16x32_bf16 v[120:123], v[174:177], v[198:201], v[120:123]
	v_mfma_f32_16x16x32_bf16 v[108:111], v[146:149], v[206:209], v[108:111]
	v_mfma_f32_16x16x32_bf16 v[104:107], v[174:177], v[206:209], v[104:107]
	v_mfma_f32_16x16x32_bf16 v[92:95], v[146:149], v[218:221], v[92:95]
	v_mfma_f32_16x16x32_bf16 v[88:91], v[174:177], v[218:221], v[88:91]
	v_mfma_f32_16x16x32_bf16 v[76:79], v[146:149], v[226:229], v[76:79]
	v_mfma_f32_16x16x32_bf16 v[72:75], v[174:177], v[226:229], v[72:75]
	v_mfma_f32_16x16x32_bf16 v[124:127], v[170:173], v[202:205], v[124:127]
	v_mfma_f32_16x16x32_bf16 v[120:123], v[178:181], v[202:205], v[120:123]
	v_mfma_f32_16x16x32_bf16 v[108:111], v[170:173], v[214:217], v[108:111]
	v_mfma_f32_16x16x32_bf16 v[104:107], v[178:181], v[214:217], v[104:107]
	v_mfma_f32_16x16x32_bf16 v[92:95], v[170:173], v[222:225], v[92:95]
	v_mfma_f32_16x16x32_bf16 v[88:91], v[178:181], v[222:225], v[88:91]
	v_mfma_f32_16x16x32_bf16 v[76:79], v[170:173], v[230:233], v[76:79]
	v_mfma_f32_16x16x32_bf16 v[72:75], v[178:181], v[230:233], v[72:75]
	s_setprio 0
	s_setprio 1
	v_mfma_f32_16x16x32_bf16 v[116:119], v[182:185], v[198:201], v[116:119]
	v_mfma_f32_16x16x32_bf16 v[112:115], v[190:193], v[198:201], v[112:115]
	v_mfma_f32_16x16x32_bf16 v[100:103], v[182:185], v[206:209], v[100:103]
	v_mfma_f32_16x16x32_bf16 v[96:99], v[190:193], v[206:209], v[96:99]
	v_mfma_f32_16x16x32_bf16 v[84:87], v[182:185], v[218:221], v[84:87]
	v_mfma_f32_16x16x32_bf16 v[80:83], v[190:193], v[218:221], v[80:83]
	v_mfma_f32_16x16x32_bf16 v[68:71], v[182:185], v[226:229], v[68:71]
	v_mfma_f32_16x16x32_bf16 v[64:67], v[190:193], v[226:229], v[64:67]
	v_mfma_f32_16x16x32_bf16 v[116:119], v[186:189], v[202:205], v[116:119]
	v_mfma_f32_16x16x32_bf16 v[112:115], v[194:197], v[202:205], v[112:115]
	v_mfma_f32_16x16x32_bf16 v[100:103], v[186:189], v[214:217], v[100:103]
	v_mfma_f32_16x16x32_bf16 v[96:99], v[194:197], v[214:217], v[96:99]
	v_mfma_f32_16x16x32_bf16 v[84:87], v[186:189], v[222:225], v[84:87]
	v_mfma_f32_16x16x32_bf16 v[80:83], v[194:197], v[222:225], v[80:83]
	v_mfma_f32_16x16x32_bf16 v[68:71], v[186:189], v[230:233], v[68:71]
	v_mfma_f32_16x16x32_bf16 v[64:67], v[194:197], v[230:233], v[64:67]
	s_setprio 0
	s_barrier
; #define PG8_STAGE(bufoff, gbase, voff) do { _Pragma("unroll") for (int _i = 0; _i < 2; ++_i) \
;         __builtin_amdgcn_global_load_lds((const unsigned*)((const char*)(gbase) + (voff)[_i]), (PG8_LAS unsigned*)(lds + (bufoff) + ldsw + _i * 8192), 16, 0, 0); } while (0)
; #define PG8_LDA(dst, b, h) do { _Pragma("unroll") for (int m = 0; m < 4; ++m) _Pragma("unroll") for (int k = 0; k < 2; ++k) dst[m][k] = *(const PG8_LAS bf16x8*)(lds + PG8_SA(b, h) + aoff + m * 2048 + k * 1024); } while (0)
; #define PG8_MMA(ai, bj, At, Bt) do { __builtin_amdgcn_s_setprio(1); _Pragma("unroll") for (int m = 0; m < 4; ++m) _Pragma("unroll") for (int n = 0; n < 2; ++n) _Pragma("unroll") for (int k = 0; k < 2; ++k) \
;         acc[ai][bj][m][n] = __builtin_amdgcn_mfma_f32_16x16x32_bf16(Bt[n][k], At[m][k], acc[ai][bj][m][n], 0, 0, 0); __builtin_amdgcn_s_setprio(0); } while (0)
; #define PG8_WAIT_V(n) asm volatile("s_waitcnt vmcnt(" #n ")" ::: "memory")
; #define PG8_WAIT_L(n) asm volatile("s_waitcnt lgkmcnt(" #n ")" ::: "memory")
; #define PG8_BAR __builtin_amdgcn_s_barrier()
; #define PG8_SCHED __builtin_amdgcn_sched_barrier(0)
; template <class Epi, class Sched, bool ALIGN_EPI = false, bool SP2 = false>
; __device__ __forceinline__ void gemm_phase(PG8_LAS unsigned char* lds, const Gemm g, const Sched& S, const Epi& E) {
;     ...
;             PG8_LDA(At, 1, 1); PG8_STAGE(PG8_SB(1, 0), b3, voffB); PG8_STAGE(PG8_SB(1, 1), b3 + hstep, voffB); PG8_STAGE(PG8_SA(1, 0), a3, voffA);
;             PG8_WAIT_V(8); PG8_WAIT_L(0); PG8_BAR; PG8_MMA(1, 0, At, B0); PG8_MMA(1, 1, At, B1); PG8_BAR; PG8_SCHED;
	s_add_i32 s40, s85, s19
	v_lshl_add_u64 v[150:151], v[150:151], 0, s[14:15]
	s_mov_b32 m0, s40
	ds_read_b128 v[198:201], v166 offset:49152
	ds_read_b128 v[202:205], v166 offset:50176
	ds_read_b128 v[206:209], v166 offset:51200
	ds_read_b128 v[214:217], v166 offset:52224
	ds_read_b128 v[218:221], v166 offset:53248
	ds_read_b128 v[222:225], v166 offset:54272
	ds_read_b128 v[226:229], v166 offset:55296
	ds_read_b128 v[230:233], v166 offset:56320
	global_load_lds_dwordx4 v[150:151], off
	s_add_i32 m0, s40, 0x2000
	s_add_u32 s38, s38, 0x40080
	v_lshl_add_u64 v[150:151], v[154:155], 0, s[14:15]
	s_addc_u32 s39, s39, 0
	s_add_i32 s40, s86, s19
	global_load_lds_dwordx4 v[150:151], off
	v_lshl_add_u64 v[150:151], s[38:39], 0, v[130:131]
	s_mov_b32 m0, s40
	s_nop 0
	global_load_lds_dwordx4 v[150:151], off
	v_lshl_add_u64 v[150:151], s[38:39], 0, v[134:135]
	s_add_i32 m0, s40, 0x2000
	s_nop 0
	global_load_lds_dwordx4 v[150:151], off
	v_lshl_add_u64 v[150:151], v[210:211], 0, s[14:15]
	s_mov_b32 m0, s53
	s_nop 0
	global_load_lds_dwordx4 v[150:151], off
	v_lshl_add_u64 v[150:151], v[234:235], 0, s[14:15]
	s_mov_b32 m0, s72
	s_nop 0
	global_load_lds_dwordx4 v[150:151], off
	s_waitcnt vmcnt(8)
	s_waitcnt lgkmcnt(0)
	s_barrier
	s_setprio 1
	v_mfma_f32_16x16x32_bf16 v[60:63], v[146:149], v[198:201], v[60:63]
	v_mfma_f32_16x16x32_bf16 v[56:59], v[174:177], v[198:201], v[56:59]
	v_mfma_f32_16x16x32_bf16 v[44:47], v[146:149], v[206:209], v[44:47]
	v_mfma_f32_16x16x32_bf16 v[40:43], v[174:177], v[206:209], v[40:43]
	v_mfma_f32_16x16x32_bf16 v[28:31], v[146:149], v[218:221], v[28:31]
	v_mfma_f32_16x16x32_bf16 v[24:27], v[174:177], v[218:221], v[24:27]
	v_mfma_f32_16x16x32_bf16 v[12:15], v[146:149], v[226:229], v[12:15]
	v_mfma_f32_16x16x32_bf16 v[8:11], v[174:177], v[226:229], v[8:11]
	v_mfma_f32_16x16x32_bf16 v[60:63], v[170:173], v[202:205], v[60:63]
	v_mfma_f32_16x16x32_bf16 v[56:59], v[178:181], v[202:205], v[56:59]
	v_mfma_f32_16x16x32_bf16 v[44:47], v[170:173], v[214:217], v[44:47]
	v_mfma_f32_16x16x32_bf16 v[40:43], v[178:181], v[214:217], v[40:43]
	v_mfma_f32_16x16x32_bf16 v[28:31], v[170:173], v[222:225], v[28:31]
	v_mfma_f32_16x16x32_bf16 v[24:27], v[178:181], v[222:225], v[24:27]
	v_mfma_f32_16x16x32_bf16 v[12:15], v[170:173], v[230:233], v[12:15]
	v_mfma_f32_16x16x32_bf16 v[8:11], v[178:181], v[230:233], v[8:11]
	s_setprio 0
	s_setprio 1
	v_mfma_f32_16x16x32_bf16 v[52:55], v[182:185], v[198:201], v[52:55]
	v_mfma_f32_16x16x32_bf16 v[48:51], v[190:193], v[198:201], v[48:51]
	v_mfma_f32_16x16x32_bf16 v[36:39], v[182:185], v[206:209], v[36:39]
	v_mfma_f32_16x16x32_bf16 v[32:35], v[190:193], v[206:209], v[32:35]
	v_mfma_f32_16x16x32_bf16 v[20:23], v[182:185], v[218:221], v[20:23]
	v_mfma_f32_16x16x32_bf16 v[16:19], v[190:193], v[218:221], v[16:19]
	v_mfma_f32_16x16x32_bf16 v[4:7], v[182:185], v[226:229], v[4:7]
	v_mfma_f32_16x16x32_bf16 v[0:3], v[190:193], v[226:229], v[0:3]
	v_mfma_f32_16x16x32_bf16 v[52:55], v[186:189], v[202:205], v[52:55]
	v_mfma_f32_16x16x32_bf16 v[48:51], v[194:197], v[202:205], v[48:51]
	v_mfma_f32_16x16x32_bf16 v[36:39], v[186:189], v[214:217], v[36:39]
	v_mfma_f32_16x16x32_bf16 v[32:35], v[194:197], v[214:217], v[32:35]
	v_mfma_f32_16x16x32_bf16 v[20:23], v[186:189], v[222:225], v[20:23]
	v_mfma_f32_16x16x32_bf16 v[16:19], v[194:197], v[222:225], v[16:19]
	v_mfma_f32_16x16x32_bf16 v[4:7], v[186:189], v[230:233], v[4:7]
	v_mfma_f32_16x16x32_bf16 v[0:3], v[194:197], v[230:233], v[0:3]
	s_setprio 0
	s_barrier
	s_add_i32 s84, s84, 2
	s_add_u32 s6, s6, 0x100
	s_addc_u32 s7, s7, 0
	s_add_u32 s82, s82, 0x100
	s_addc_u32 s83, s83, 0
	s_cmp_gt_u32 s84, 13
	s_cbranch_scc0 .LBB0_148
	s_and_b64 vcc, exec, s[16:17]
	s_cbranch_vccz .LBB0_151
	s_barrier

; #define PG8_STAGE(bufoff, gbase, voff) do { _Pragma("unroll") for (int _i = 0; _i < 2; ++_i) \
;         __builtin_amdgcn_global_load_lds((const unsigned*)((const char*)(gbase) + (voff)[_i]), (PG8_LAS unsigned*)(lds + (bufoff) + ldsw + _i * 8192), 16, 0, 0); } while (0)
; #define PG8_LDA(dst, b, h) do { _Pragma("unroll") for (int m = 0; m < 4; ++m) _Pragma("unroll") for (int k = 0; k < 2; ++k) dst[m][k] = *(const PG8_LAS bf16x8*)(lds + PG8_SA(b, h) + aoff + m * 2048 + k * 1024); } while (0)
; #define PG8_LDB(dst, b, h) do { _Pragma("unroll") for (int n = 0; n < 2; ++n) _Pragma("unroll") for (int k = 0; k < 2; ++k) dst[n][k] = *(const PG8_LAS bf16x8*)(lds + PG8_SB(b, h) + boff + n * 2048 + k * 1024); } while (0)
; #define PG8_MMA(ai, bj, At, Bt) do { __builtin_amdgcn_s_setprio(1); _Pragma("unroll") for (int m = 0; m < 4; ++m) _Pragma("unroll") for (int n = 0; n < 2; ++n) _Pragma("unroll") for (int k = 0; k < 2; ++k) \
;         acc[ai][bj][m][n] = __builtin_amdgcn_mfma_f32_16x16x32_bf16(Bt[n][k], At[m][k], acc[ai][bj][m][n], 0, 0, 0); __builtin_amdgcn_s_setprio(0); } while (0)
; #define PG8_WAIT_V(n) asm volatile("s_waitcnt vmcnt(" #n ")" ::: "memory")
; #define PG8_WAIT_L(n) asm volatile("s_waitcnt lgkmcnt(" #n ")" ::: "memory")
; #define PG8_BAR __builtin_amdgcn_s_barrier()
; #define PG8_SCHED __builtin_amdgcn_sched_barrier(0)
; template <class Epi, class Sched, bool ALIGN_EPI = false, bool SP2 = false>
; __device__ __forceinline__ void gemm_phase(PG8_LAS unsigned char* lds, const Gemm g, const Sched& S, const Epi& E) {
;     ...
;             PG8_LDB(B0, 0, 0); PG8_LDB(B1, 0, 1); PG8_SCHED; PG8_LDA(At, 0, 0); PG8_STAGE(PG8_SA(1, 1), a1 + hstep, voffA);
;             PG8_WAIT_V(8); PG8_WAIT_L(0); PG8_BAR; PG8_MMA(0, 0, At, B0); PG8_MMA(0, 1, At, B1); PG8_BAR; PG8_SCHED;
;             PG8_LDA(At, 0, 1); PG8_STAGE(PG8_SB(0, 0), b2, voffB); PG8_STAGE(PG8_SB(0, 1), b2 + hstep, voffB); PG8_STAGE(PG8_SA(0, 0), a2, voffA);
;             PG8_WAIT_V(8); PG8_WAIT_L(0); PG8_BAR; PG8_MMA(1, 0, At, B0); PG8_MMA(1, 1, At, B1); PG8_BAR; PG8_SCHED;
.LBB0_378:
	ds_read_b128 v[128:131], v178
	ds_read_b128 v[132:135], v178 offset:1024
	ds_read_b128 v[136:139], v178 offset:2048
	ds_read_b128 v[140:143], v178 offset:3072
	ds_read_b128 v[170:173], v179
	ds_read_b128 v[174:177], v179 offset:1024
	ds_read_b128 v[182:185], v179 offset:2048
	ds_read_b128 v[186:189], v179 offset:3072
	s_add_u32 s4, s44, 0xfffc0080
	s_addc_u32 s5, s45, -1
	s_cmp_eq_u32 s86, 12
	s_cselect_b32 s73, s35, s5
	s_cselect_b32 s72, s41, s4
	s_cselect_b32 s47, s31, s94
	s_cselect_b32 s46, s92, s93
	v_lshl_add_u64 v[210:211], s[44:45], 0, v[154:155]
	s_add_i32 m0, s53, 0xc000
	ds_read_b128 v[190:193], v180
	ds_read_b128 v[194:197], v180 offset:1024
	ds_read_b128 v[198:201], v180 offset:2048
	ds_read_b128 v[202:205], v180 offset:3072
	ds_read_b128 v[206:209], v180 offset:4096
	ds_read_b128 v[214:217], v180 offset:5120
	ds_read_b128 v[218:221], v180 offset:6144
	ds_read_b128 v[222:225], v180 offset:7168
	global_load_lds_dwordx4 v[210:211], off
	v_lshl_add_u64 v[210:211], s[44:45], 0, v[164:165]
	s_add_i32 m0, s53, 0xe000
	s_nop 0
	global_load_lds_dwordx4 v[210:211], off
	s_waitcnt vmcnt(8)
	s_waitcnt lgkmcnt(0)
	s_barrier
	s_setprio 1
	v_mfma_f32_16x16x32_bf16 v[124:127], v[128:131], v[190:193], v[124:127]
	v_mfma_f32_16x16x32_bf16 v[120:123], v[136:139], v[190:193], v[120:123]
	v_mfma_f32_16x16x32_bf16 v[108:111], v[128:131], v[198:201], v[108:111]
	v_mfma_f32_16x16x32_bf16 v[104:107], v[136:139], v[198:201], v[104:107]
	v_mfma_f32_16x16x32_bf16 v[92:95], v[128:131], v[206:209], v[92:95]
	v_mfma_f32_16x16x32_bf16 v[88:91], v[136:139], v[206:209], v[88:91]
	v_mfma_f32_16x16x32_bf16 v[76:79], v[128:131], v[218:221], v[76:79]
	v_mfma_f32_16x16x32_bf16 v[72:75], v[136:139], v[218:221], v[72:75]
	v_mfma_f32_16x16x32_bf16 v[124:127], v[132:135], v[194:197], v[124:127]
	v_mfma_f32_16x16x32_bf16 v[120:123], v[140:143], v[194:197], v[120:123]
	v_mfma_f32_16x16x32_bf16 v[108:111], v[132:135], v[202:205], v[108:111]
	v_mfma_f32_16x16x32_bf16 v[104:107], v[140:143], v[202:205], v[104:107]
	v_mfma_f32_16x16x32_bf16 v[92:95], v[132:135], v[214:217], v[92:95]
	v_mfma_f32_16x16x32_bf16 v[88:91], v[140:143], v[214:217], v[88:91]
	v_mfma_f32_16x16x32_bf16 v[76:79], v[132:135], v[222:225], v[76:79]
	v_mfma_f32_16x16x32_bf16 v[72:75], v[140:143], v[222:225], v[72:75]
	s_setprio 0
	s_setprio 1
	v_mfma_f32_16x16x32_bf16 v[116:119], v[170:173], v[190:193], v[116:119]
	v_mfma_f32_16x16x32_bf16 v[112:115], v[182:185], v[190:193], v[112:115]
	v_mfma_f32_16x16x32_bf16 v[100:103], v[170:173], v[198:201], v[100:103]
	v_mfma_f32_16x16x32_bf16 v[96:99], v[182:185], v[198:201], v[96:99]
	v_mfma_f32_16x16x32_bf16 v[84:87], v[170:173], v[206:209], v[84:87]
	v_mfma_f32_16x16x32_bf16 v[80:83], v[182:185], v[206:209], v[80:83]
	v_mfma_f32_16x16x32_bf16 v[68:71], v[170:173], v[218:221], v[68:71]
	v_mfma_f32_16x16x32_bf16 v[64:67], v[182:185], v[218:221], v[64:67]
	v_mfma_f32_16x16x32_bf16 v[116:119], v[174:177], v[194:197], v[116:119]
	v_mfma_f32_16x16x32_bf16 v[112:115], v[186:189], v[194:197], v[112:115]
	v_mfma_f32_16x16x32_bf16 v[100:103], v[174:177], v[202:205], v[100:103]
	v_mfma_f32_16x16x32_bf16 v[96:99], v[186:189], v[202:205], v[96:99]
	v_mfma_f32_16x16x32_bf16 v[84:87], v[174:177], v[214:217], v[84:87]
	v_mfma_f32_16x16x32_bf16 v[80:83], v[186:189], v[214:217], v[80:83]
	v_mfma_f32_16x16x32_bf16 v[68:71], v[174:177], v[222:225], v[68:71]
	v_mfma_f32_16x16x32_bf16 v[64:67], v[186:189], v[222:225], v[64:67]
	s_setprio 0
	s_barrier
	s_add_i32 s4, s85, s49
	v_lshl_add_u64 v[210:211], s[46:47], 0, v[146:147]
	s_mov_b32 m0, s4
	ds_read_b128 v[190:193], v180 offset:16384
	ds_read_b128 v[194:197], v180 offset:17408
	ds_read_b128 v[198:201], v180 offset:18432
	ds_read_b128 v[202:205], v180 offset:19456
	ds_read_b128 v[206:209], v180 offset:20480
	ds_read_b128 v[214:217], v180 offset:21504
	ds_read_b128 v[218:221], v180 offset:22528
	ds_read_b128 v[222:225], v180 offset:23552
	global_load_lds_dwordx4 v[210:211], off
	s_add_i32 m0, s4, 0x2000
	s_add_u32 s4, s46, 0x40000
	v_lshl_add_u64 v[226:227], s[46:47], 0, v[150:151]
	s_addc_u32 s5, s47, 0
	s_add_i32 s95, s89, s49
	global_load_lds_dwordx4 v[226:227], off
	v_lshl_add_u64 v[228:229], s[4:5], 0, v[146:147]
	s_mov_b32 m0, s95
	v_lshl_add_u64 v[230:231], s[72:73], 0, v[148:149]
	global_load_lds_dwordx4 v[228:229], off
	v_lshl_add_u64 v[228:229], s[4:5], 0, v[150:151]
	s_add_i32 m0, s95, 0x2000
	s_nop 0
	global_load_lds_dwordx4 v[228:229], off
	v_lshl_add_u64 v[228:229], s[72:73], 0, v[144:145]
	s_mov_b32 m0, s53
	s_nop 0
	global_load_lds_dwordx4 v[228:229], off
	s_mov_b32 m0, s74
	s_nop 0
	global_load_lds_dwordx4 v[230:231], off
	s_waitcnt vmcnt(8)
	s_waitcnt lgkmcnt(0)
	s_barrier
; #define PG8_STAGE(bufoff, gbase, voff) do { _Pragma("unroll") for (int _i = 0; _i < 2; ++_i) \
;         __builtin_amdgcn_global_load_lds((const unsigned*)((const char*)(gbase) + (voff)[_i]), (PG8_LAS unsigned*)(lds + (bufoff) + ldsw + _i * 8192), 16, 0, 0); } while (0)
; #define PG8_LDA(dst, b, h) do { _Pragma("unroll") for (int m = 0; m < 4; ++m) _Pragma("unroll") for (int k = 0; k < 2; ++k) dst[m][k] = *(const PG8_LAS bf16x8*)(lds + PG8_SA(b, h) + aoff + m * 2048 + k * 1024); } while (0)
; #define PG8_LDB(dst, b, h) do { _Pragma("unroll") for (int n = 0; n < 2; ++n) _Pragma("unroll") for (int k = 0; k < 2; ++k) dst[n][k] = *(const PG8_LAS bf16x8*)(lds + PG8_SB(b, h) + boff + n * 2048 + k * 1024); } while (0)
; #define PG8_MMA(ai, bj, At, Bt) do { __builtin_amdgcn_s_setprio(1); _Pragma("unroll") for (int m = 0; m < 4; ++m) _Pragma("unroll") for (int n = 0; n < 2; ++n) _Pragma("unroll") for (int k = 0; k < 2; ++k) \
;         acc[ai][bj][m][n] = __builtin_amdgcn_mfma_f32_16x16x32_bf16(Bt[n][k], At[m][k], acc[ai][bj][m][n], 0, 0, 0); __builtin_amdgcn_s_setprio(0); } while (0)
; #define PG8_WAIT_V(n) asm volatile("s_waitcnt vmcnt(" #n ")" ::: "memory")
; #define PG8_WAIT_L(n) asm volatile("s_waitcnt lgkmcnt(" #n ")" ::: "memory")
; #define PG8_BAR __builtin_amdgcn_s_barrier()
; #define PG8_SCHED __builtin_amdgcn_sched_barrier(0)
; template <class Epi, class Sched, bool ALIGN_EPI = false, bool SP2 = false>
; __device__ __forceinline__ void gemm_phase(PG8_LAS unsigned char* lds, const Gemm g, const Sched& S, const Epi& E) {
;     ...
;             PG8_WAIT_V(8); PG8_WAIT_L(0); PG8_BAR; PG8_MMA(1, 0, At, B0); PG8_MMA(1, 1, At, B1); PG8_BAR; PG8_SCHED;
;             PG8_LDB(B0, 1, 0); PG8_LDB(B1, 1, 1); PG8_SCHED; PG8_LDA(At, 1, 0); PG8_STAGE(PG8_SA(0, 1), a2 + hstep, voffA);
;             PG8_WAIT_V(8); PG8_WAIT_L(0); PG8_BAR; PG8_MMA(0, 0, At, B0); PG8_MMA(0, 1, At, B1); PG8_BAR; PG8_SCHED;
	s_setprio 1
	v_mfma_f32_16x16x32_bf16 v[60:63], v[128:131], v[190:193], v[60:63]
	v_mfma_f32_16x16x32_bf16 v[56:59], v[136:139], v[190:193], v[56:59]
	v_mfma_f32_16x16x32_bf16 v[44:47], v[128:131], v[198:201], v[44:47]
	v_mfma_f32_16x16x32_bf16 v[40:43], v[136:139], v[198:201], v[40:43]
	v_mfma_f32_16x16x32_bf16 v[28:31], v[128:131], v[206:209], v[28:31]
	v_mfma_f32_16x16x32_bf16 v[24:27], v[136:139], v[206:209], v[24:27]
	v_mfma_f32_16x16x32_bf16 v[12:15], v[128:131], v[218:221], v[12:15]
	v_mfma_f32_16x16x32_bf16 v[8:11], v[136:139], v[218:221], v[8:11]
	v_mfma_f32_16x16x32_bf16 v[60:63], v[132:135], v[194:197], v[60:63]
	v_mfma_f32_16x16x32_bf16 v[56:59], v[140:143], v[194:197], v[56:59]
	v_mfma_f32_16x16x32_bf16 v[44:47], v[132:135], v[202:205], v[44:47]
	v_mfma_f32_16x16x32_bf16 v[40:43], v[140:143], v[202:205], v[40:43]
	v_mfma_f32_16x16x32_bf16 v[28:31], v[132:135], v[214:217], v[28:31]
	v_mfma_f32_16x16x32_bf16 v[24:27], v[140:143], v[214:217], v[24:27]
	v_mfma_f32_16x16x32_bf16 v[12:15], v[132:135], v[222:225], v[12:15]
	v_mfma_f32_16x16x32_bf16 v[8:11], v[140:143], v[222:225], v[8:11]
	s_setprio 0
	s_setprio 1
	v_mfma_f32_16x16x32_bf16 v[52:55], v[170:173], v[190:193], v[52:55]
	v_mfma_f32_16x16x32_bf16 v[48:51], v[182:185], v[190:193], v[48:51]
	v_mfma_f32_16x16x32_bf16 v[36:39], v[170:173], v[198:201], v[36:39]
	v_mfma_f32_16x16x32_bf16 v[32:35], v[182:185], v[198:201], v[32:35]
	v_mfma_f32_16x16x32_bf16 v[20:23], v[170:173], v[206:209], v[20:23]
	v_mfma_f32_16x16x32_bf16 v[16:19], v[182:185], v[206:209], v[16:19]
	v_mfma_f32_16x16x32_bf16 v[4:7], v[170:173], v[218:221], v[4:7]
	v_mfma_f32_16x16x32_bf16 v[0:3], v[182:185], v[218:221], v[0:3]
	v_mfma_f32_16x16x32_bf16 v[52:55], v[174:177], v[194:197], v[52:55]
	v_mfma_f32_16x16x32_bf16 v[48:51], v[186:189], v[194:197], v[48:51]
	v_mfma_f32_16x16x32_bf16 v[36:39], v[174:177], v[202:205], v[36:39]
	v_mfma_f32_16x16x32_bf16 v[32:35], v[186:189], v[202:205], v[32:35]
	v_mfma_f32_16x16x32_bf16 v[20:23], v[174:177], v[214:217], v[20:23]
	v_mfma_f32_16x16x32_bf16 v[16:19], v[186:189], v[214:217], v[16:19]
	v_mfma_f32_16x16x32_bf16 v[4:7], v[174:177], v[222:225], v[4:7]
	v_mfma_f32_16x16x32_bf16 v[0:3], v[186:189], v[222:225], v[0:3]
	s_setprio 0
	s_barrier
	s_add_i32 s95, 0, 0x18000
	s_add_i32 s96, 0, 0x1c000
	v_add_u32_e32 v140, s95, v159
	v_add_u32_e32 v186, s96, v159
	ds_read_b128 v[128:131], v140
	ds_read_b128 v[132:135], v140 offset:1024
	ds_read_b128 v[136:139], v140 offset:2048
	ds_read_b128 v[140:143], v140 offset:3072
	ds_read_b128 v[170:173], v186
	ds_read_b128 v[174:177], v186 offset:1024
	ds_read_b128 v[182:185], v186 offset:2048
	ds_read_b128 v[186:189], v186 offset:3072
	s_add_u32 s4, s72, 0x40000
	s_addc_u32 s5, s73, 0
	s_mov_b32 m0, s75
	v_lshl_add_u64 v[232:233], s[4:5], 0, v[144:145]
	ds_read_b128 v[190:193], v180 offset:32768
	ds_read_b128 v[194:197], v180 offset:33792
	ds_read_b128 v[198:201], v180 offset:34816
	ds_read_b128 v[202:205], v180 offset:35840
	ds_read_b128 v[206:209], v180 offset:36864
	ds_read_b128 v[214:217], v180 offset:37888
	ds_read_b128 v[218:221], v180 offset:38912
	ds_read_b128 v[222:225], v180 offset:39936
	global_load_lds_dwordx4 v[232:233], off
	v_lshl_add_u64 v[232:233], s[4:5], 0, v[148:149]
	s_mov_b32 m0, s76
	s_nop 0
	global_load_lds_dwordx4 v[232:233], off
	s_waitcnt vmcnt(8)
	s_waitcnt lgkmcnt(0)
	s_barrier
	s_setprio 1
	v_mfma_f32_16x16x32_bf16 v[124:127], v[128:131], v[190:193], v[124:127]
	v_mfma_f32_16x16x32_bf16 v[120:123], v[136:139], v[190:193], v[120:123]
	v_mfma_f32_16x16x32_bf16 v[108:111], v[128:131], v[198:201], v[108:111]
	v_mfma_f32_16x16x32_bf16 v[104:107], v[136:139], v[198:201], v[104:107]
	v_mfma_f32_16x16x32_bf16 v[92:95], v[128:131], v[206:209], v[92:95]
	v_mfma_f32_16x16x32_bf16 v[88:91], v[136:139], v[206:209], v[88:91]
	v_mfma_f32_16x16x32_bf16 v[76:79], v[128:131], v[218:221], v[76:79]
	v_mfma_f32_16x16x32_bf16 v[72:75], v[136:139], v[218:221], v[72:75]
	v_mfma_f32_16x16x32_bf16 v[124:127], v[132:135], v[194:197], v[124:127]
	v_mfma_f32_16x16x32_bf16 v[120:123], v[140:143], v[194:197], v[120:123]
	v_mfma_f32_16x16x32_bf16 v[108:111], v[132:135], v[202:205], v[108:111]
	v_mfma_f32_16x16x32_bf16 v[104:107], v[140:143], v[202:205], v[104:107]
	v_mfma_f32_16x16x32_bf16 v[92:95], v[132:135], v[214:217], v[92:95]
	v_mfma_f32_16x16x32_bf16 v[88:91], v[140:143], v[214:217], v[88:91]
	v_mfma_f32_16x16x32_bf16 v[76:79], v[132:135], v[222:225], v[76:79]
	v_mfma_f32_16x16x32_bf16 v[72:75], v[140:143], v[222:225], v[72:75]
	s_setprio 0
	s_setprio 1
	v_mfma_f32_16x16x32_bf16 v[116:119], v[170:173], v[190:193], v[116:119]
	v_mfma_f32_16x16x32_bf16 v[112:115], v[182:185], v[190:193], v[112:115]
	v_mfma_f32_16x16x32_bf16 v[100:103], v[170:173], v[198:201], v[100:103]
	v_mfma_f32_16x16x32_bf16 v[96:99], v[182:185], v[198:201], v[96:99]
	v_mfma_f32_16x16x32_bf16 v[84:87], v[170:173], v[206:209], v[84:87]
	v_mfma_f32_16x16x32_bf16 v[80:83], v[182:185], v[206:209], v[80:83]
	v_mfma_f32_16x16x32_bf16 v[68:71], v[170:173], v[218:221], v[68:71]
	v_mfma_f32_16x16x32_bf16 v[64:67], v[182:185], v[218:221], v[64:67]
	v_mfma_f32_16x16x32_bf16 v[116:119], v[174:177], v[194:197], v[116:119]
	v_mfma_f32_16x16x32_bf16 v[112:115], v[186:189], v[194:197], v[112:115]
	v_mfma_f32_16x16x32_bf16 v[100:103], v[174:177], v[202:205], v[100:103]
	v_mfma_f32_16x16x32_bf16 v[96:99], v[186:189], v[202:205], v[96:99]
	v_mfma_f32_16x16x32_bf16 v[84:87], v[174:177], v[214:217], v[84:87]
	v_mfma_f32_16x16x32_bf16 v[80:83], v[186:189], v[214:217], v[80:83]
	v_mfma_f32_16x16x32_bf16 v[68:71], v[174:177], v[222:225], v[68:71]
	v_mfma_f32_16x16x32_bf16 v[64:67], v[186:189], v[222:225], v[64:67]
	s_setprio 0
	s_barrier
; #define PG8_STAGE(bufoff, gbase, voff) do { _Pragma("unroll") for (int _i = 0; _i < 2; ++_i) \
;         __builtin_amdgcn_global_load_lds((const unsigned*)((const char*)(gbase) + (voff)[_i]), (PG8_LAS unsigned*)(lds + (bufoff) + ldsw + _i * 8192), 16, 0, 0); } while (0)
; #define PG8_LDA(dst, b, h) do { _Pragma("unroll") for (int m = 0; m < 4; ++m) _Pragma("unroll") for (int k = 0; k < 2; ++k) dst[m][k] = *(const PG8_LAS bf16x8*)(lds + PG8_SA(b, h) + aoff + m * 2048 + k * 1024); } while (0)
; #define PG8_MMA(ai, bj, At, Bt) do { __builtin_amdgcn_s_setprio(1); _Pragma("unroll") for (int m = 0; m < 4; ++m) _Pragma("unroll") for (int n = 0; n < 2; ++n) _Pragma("unroll") for (int k = 0; k < 2; ++k) \
;         acc[ai][bj][m][n] = __builtin_amdgcn_mfma_f32_16x16x32_bf16(Bt[n][k], At[m][k], acc[ai][bj][m][n], 0, 0, 0); __builtin_amdgcn_s_setprio(0); } while (0)
; #define PG8_WAIT_V(n) asm volatile("s_waitcnt vmcnt(" #n ")" ::: "memory")
; #define PG8_WAIT_L(n) asm volatile("s_waitcnt lgkmcnt(" #n ")" ::: "memory")
; #define PG8_BAR __builtin_amdgcn_s_barrier()
; #define PG8_SCHED __builtin_amdgcn_sched_barrier(0)
; template <class Epi, class Sched, bool ALIGN_EPI = false, bool SP2 = false>
; __device__ __forceinline__ void gemm_phase(PG8_LAS unsigned char* lds, const Gemm g, const Sched& S, const Epi& E) {
;     ...
;             PG8_LDA(At, 1, 1); PG8_STAGE(PG8_SB(1, 0), b3, voffB); PG8_STAGE(PG8_SB(1, 1), b3 + hstep, voffB); PG8_STAGE(PG8_SA(1, 0), a3, voffA);
;             PG8_WAIT_V(8); PG8_WAIT_L(0); PG8_BAR; PG8_MMA(1, 0, At, B0); PG8_MMA(1, 1, At, B1); PG8_BAR; PG8_SCHED;
	s_add_i32 s4, s95, s49
	v_lshl_add_u64 v[210:211], v[210:211], 0, s[26:27]
	s_mov_b32 m0, s4
	ds_read_b128 v[190:193], v180 offset:49152
	ds_read_b128 v[194:197], v180 offset:50176
	ds_read_b128 v[198:201], v180 offset:51200
	ds_read_b128 v[202:205], v180 offset:52224
	ds_read_b128 v[206:209], v180 offset:53248
	ds_read_b128 v[214:217], v180 offset:54272
	ds_read_b128 v[218:221], v180 offset:55296
	ds_read_b128 v[222:225], v180 offset:56320
	global_load_lds_dwordx4 v[210:211], off
	s_add_i32 m0, s4, 0x2000
	s_add_u32 s4, s46, 0x40080
	v_lshl_add_u64 v[210:211], v[226:227], 0, s[26:27]
	s_addc_u32 s5, s47, 0
	s_add_i32 s46, s96, s49
	global_load_lds_dwordx4 v[210:211], off
	v_lshl_add_u64 v[210:211], s[4:5], 0, v[146:147]
	s_mov_b32 m0, s46
	s_nop 0
	global_load_lds_dwordx4 v[210:211], off
	v_lshl_add_u64 v[210:211], s[4:5], 0, v[150:151]
	s_add_i32 m0, s46, 0x2000
	s_nop 0
	global_load_lds_dwordx4 v[210:211], off
	v_lshl_add_u64 v[210:211], v[228:229], 0, s[26:27]
	s_mov_b32 m0, s78
	s_nop 0
	global_load_lds_dwordx4 v[210:211], off
	v_lshl_add_u64 v[210:211], v[230:231], 0, s[26:27]
	s_mov_b32 m0, s79
	s_nop 0
	global_load_lds_dwordx4 v[210:211], off
	s_waitcnt vmcnt(8)
	s_waitcnt lgkmcnt(0)
	s_barrier
	s_setprio 1
	v_mfma_f32_16x16x32_bf16 v[60:63], v[128:131], v[190:193], v[60:63]
	v_mfma_f32_16x16x32_bf16 v[56:59], v[136:139], v[190:193], v[56:59]
	v_mfma_f32_16x16x32_bf16 v[44:47], v[128:131], v[198:201], v[44:47]
	v_mfma_f32_16x16x32_bf16 v[40:43], v[136:139], v[198:201], v[40:43]
	v_mfma_f32_16x16x32_bf16 v[28:31], v[128:131], v[206:209], v[28:31]
	v_mfma_f32_16x16x32_bf16 v[24:27], v[136:139], v[206:209], v[24:27]
	v_mfma_f32_16x16x32_bf16 v[12:15], v[128:131], v[218:221], v[12:15]
	v_mfma_f32_16x16x32_bf16 v[8:11], v[136:139], v[218:221], v[8:11]
	v_mfma_f32_16x16x32_bf16 v[60:63], v[132:135], v[194:197], v[60:63]
	v_mfma_f32_16x16x32_bf16 v[56:59], v[140:143], v[194:197], v[56:59]
	v_mfma_f32_16x16x32_bf16 v[44:47], v[132:135], v[202:205], v[44:47]
	v_mfma_f32_16x16x32_bf16 v[40:43], v[140:143], v[202:205], v[40:43]
	v_mfma_f32_16x16x32_bf16 v[28:31], v[132:135], v[214:217], v[28:31]
	v_mfma_f32_16x16x32_bf16 v[24:27], v[140:143], v[214:217], v[24:27]
	v_mfma_f32_16x16x32_bf16 v[12:15], v[132:135], v[222:225], v[12:15]
	v_mfma_f32_16x16x32_bf16 v[8:11], v[140:143], v[222:225], v[8:11]
	s_setprio 0
	s_setprio 1
	v_mfma_f32_16x16x32_bf16 v[52:55], v[170:173], v[190:193], v[52:55]
	v_mfma_f32_16x16x32_bf16 v[48:51], v[182:185], v[190:193], v[48:51]
	v_mfma_f32_16x16x32_bf16 v[36:39], v[170:173], v[198:201], v[36:39]
	v_mfma_f32_16x16x32_bf16 v[32:35], v[182:185], v[198:201], v[32:35]
	v_mfma_f32_16x16x32_bf16 v[20:23], v[170:173], v[206:209], v[20:23]
	v_mfma_f32_16x16x32_bf16 v[16:19], v[182:185], v[206:209], v[16:19]
	v_mfma_f32_16x16x32_bf16 v[4:7], v[170:173], v[218:221], v[4:7]
	v_mfma_f32_16x16x32_bf16 v[0:3], v[182:185], v[218:221], v[0:3]
	v_mfma_f32_16x16x32_bf16 v[52:55], v[174:177], v[194:197], v[52:55]
	v_mfma_f32_16x16x32_bf16 v[48:51], v[186:189], v[194:197], v[48:51]
	v_mfma_f32_16x16x32_bf16 v[36:39], v[174:177], v[202:205], v[36:39]
	v_mfma_f32_16x16x32_bf16 v[32:35], v[186:189], v[202:205], v[32:35]
	v_mfma_f32_16x16x32_bf16 v[20:23], v[174:177], v[214:217], v[20:23]
	v_mfma_f32_16x16x32_bf16 v[16:19], v[186:189], v[214:217], v[16:19]
	v_mfma_f32_16x16x32_bf16 v[4:7], v[174:177], v[222:225], v[4:7]
	v_mfma_f32_16x16x32_bf16 v[0:3], v[186:189], v[222:225], v[0:3]
	s_setprio 0
	s_barrier
	s_add_i32 s86, s86, 2
	s_add_u32 s44, s44, 0x100
	s_addc_u32 s45, s45, 0
	s_add_u32 s93, s93, 0x100
	s_addc_u32 s94, s94, 0
	s_cmp_gt_u32 s86, 13
	s_cbranch_scc0 .LBB0_378
	s_and_b64 vcc, exec, s[28:29]
	s_cbranch_vccz .LBB0_381
	s_barrier

; #define PG8_STAGE(bufoff, gbase, voff) do { _Pragma("unroll") for (int _i = 0; _i < 2; ++_i) \
;         __builtin_amdgcn_global_load_lds((const unsigned*)((const char*)(gbase) + (voff)[_i]), (PG8_LAS unsigned*)(lds + (bufoff) + ldsw + _i * 8192), 16, 0, 0); } while (0)
; #define PG8_LDA(dst, b, h) do { _Pragma("unroll") for (int m = 0; m < 4; ++m) _Pragma("unroll") for (int k = 0; k < 2; ++k) dst[m][k] = *(const PG8_LAS bf16x8*)(lds + PG8_SA(b, h) + aoff + m * 2048 + k * 1024); } while (0)
; #define PG8_LDB(dst, b, h) do { _Pragma("unroll") for (int n = 0; n < 2; ++n) _Pragma("unroll") for (int k = 0; k < 2; ++k) dst[n][k] = *(const PG8_LAS bf16x8*)(lds + PG8_SB(b, h) + boff + n * 2048 + k * 1024); } while (0)
; #define PG8_MMA(ai, bj, At, Bt) do { __builtin_amdgcn_s_setprio(1); _Pragma("unroll") for (int m = 0; m < 4; ++m) _Pragma("unroll") for (int n = 0; n < 2; ++n) _Pragma("unroll") for (int k = 0; k < 2; ++k) \
;         acc[ai][bj][m][n] = __builtin_amdgcn_mfma_f32_16x16x32_bf16(Bt[n][k], At[m][k], acc[ai][bj][m][n], 0, 0, 0); __builtin_amdgcn_s_setprio(0); } while (0)
; #define PG8_WAIT_V(n) asm volatile("s_waitcnt vmcnt(" #n ")" ::: "memory")
; #define PG8_WAIT_L(n) asm volatile("s_waitcnt lgkmcnt(" #n ")" ::: "memory")
; #define PG8_BAR __builtin_amdgcn_s_barrier()
; #define PG8_SCHED __builtin_amdgcn_sched_barrier(0)
; template <class Epi, class Sched, bool ALIGN_EPI = false, bool SP2 = false>
; __device__ __forceinline__ void gemm_phase(PG8_LAS unsigned char* lds, const Gemm g, const Sched& S, const Epi& E) {
;     ...
;             PG8_LDB(B0, 0, 0); PG8_LDB(B1, 0, 1); PG8_SCHED; PG8_LDA(At, 0, 0); PG8_STAGE(PG8_SA(1, 1), a1 + hstep, voffA);
;             PG8_WAIT_V(8); PG8_WAIT_L(0); PG8_BAR; PG8_MMA(0, 0, At, B0); PG8_MMA(0, 1, At, B1); PG8_BAR; PG8_SCHED;
;             PG8_LDA(At, 0, 1); PG8_STAGE(PG8_SB(0, 0), b2, voffB); PG8_STAGE(PG8_SB(0, 1), b2 + hstep, voffB); PG8_STAGE(PG8_SA(0, 0), a2, voffA);
;             PG8_WAIT_V(8); PG8_WAIT_L(0); PG8_BAR; PG8_MMA(1, 0, At, B0); PG8_MMA(1, 1, At, B1); PG8_BAR; PG8_SCHED;
.LBB0_469:
	ds_read_b128 v[146:149], v179
	ds_read_b128 v[164:167], v179 offset:1024
	ds_read_b128 v[168:171], v179 offset:2048
	ds_read_b128 v[172:175], v179 offset:3072
	ds_read_b128 v[184:187], v180
	ds_read_b128 v[188:191], v180 offset:1024
	ds_read_b128 v[192:195], v180 offset:2048
	ds_read_b128 v[196:199], v180 offset:3072
	s_add_u32 s4, s34, 0xfffc0080
	s_addc_u32 s5, s35, -1
	s_cmp_eq_u32 s86, 12
	s_cselect_b32 s39, s9, s5
	s_cselect_b32 s38, s27, s4
	s_cselect_b32 s37, s25, s89
	s_cselect_b32 s36, s84, s85
	v_lshl_add_u64 v[150:151], s[34:35], 0, v[138:139]
	s_add_i32 m0, s47, 0xc000
	ds_read_b128 v[200:203], v181
	ds_read_b128 v[204:207], v181 offset:1024
	ds_read_b128 v[208:211], v181 offset:2048
	ds_read_b128 v[214:217], v181 offset:3072
	ds_read_b128 v[218:221], v181 offset:4096
	ds_read_b128 v[222:225], v181 offset:5120
	ds_read_b128 v[226:229], v181 offset:6144
	ds_read_b128 v[230:233], v181 offset:7168
	global_load_lds_dwordx4 v[150:151], off
	v_lshl_add_u64 v[150:151], s[34:35], 0, v[140:141]
	s_add_i32 m0, s47, 0xe000
	s_nop 0
	global_load_lds_dwordx4 v[150:151], off
	s_waitcnt vmcnt(8)
	s_waitcnt lgkmcnt(0)
	s_barrier
	s_setprio 1
	v_mfma_f32_16x16x32_bf16 v[124:127], v[146:149], v[200:203], v[124:127]
	v_mfma_f32_16x16x32_bf16 v[116:119], v[168:171], v[200:203], v[116:119]
	v_mfma_f32_16x16x32_bf16 v[108:111], v[146:149], v[208:211], v[108:111]
	v_mfma_f32_16x16x32_bf16 v[100:103], v[168:171], v[208:211], v[100:103]
	v_mfma_f32_16x16x32_bf16 v[92:95], v[146:149], v[218:221], v[92:95]
	v_mfma_f32_16x16x32_bf16 v[84:87], v[168:171], v[218:221], v[84:87]
	v_mfma_f32_16x16x32_bf16 v[76:79], v[146:149], v[226:229], v[76:79]
	v_mfma_f32_16x16x32_bf16 v[68:71], v[168:171], v[226:229], v[68:71]
	v_mfma_f32_16x16x32_bf16 v[124:127], v[164:167], v[204:207], v[124:127]
	v_mfma_f32_16x16x32_bf16 v[116:119], v[172:175], v[204:207], v[116:119]
	v_mfma_f32_16x16x32_bf16 v[108:111], v[164:167], v[214:217], v[108:111]
	v_mfma_f32_16x16x32_bf16 v[100:103], v[172:175], v[214:217], v[100:103]
	v_mfma_f32_16x16x32_bf16 v[92:95], v[164:167], v[222:225], v[92:95]
	v_mfma_f32_16x16x32_bf16 v[84:87], v[172:175], v[222:225], v[84:87]
	v_mfma_f32_16x16x32_bf16 v[76:79], v[164:167], v[230:233], v[76:79]
	v_mfma_f32_16x16x32_bf16 v[68:71], v[172:175], v[230:233], v[68:71]
	s_setprio 0
	s_setprio 1
	v_mfma_f32_16x16x32_bf16 v[120:123], v[184:187], v[200:203], v[120:123]
	v_mfma_f32_16x16x32_bf16 v[112:115], v[192:195], v[200:203], v[112:115]
	v_mfma_f32_16x16x32_bf16 v[104:107], v[184:187], v[208:211], v[104:107]
	v_mfma_f32_16x16x32_bf16 v[96:99], v[192:195], v[208:211], v[96:99]
	v_mfma_f32_16x16x32_bf16 v[88:91], v[184:187], v[218:221], v[88:91]
	v_mfma_f32_16x16x32_bf16 v[80:83], v[192:195], v[218:221], v[80:83]
	v_mfma_f32_16x16x32_bf16 v[72:75], v[184:187], v[226:229], v[72:75]
	v_mfma_f32_16x16x32_bf16 v[64:67], v[192:195], v[226:229], v[64:67]
	v_mfma_f32_16x16x32_bf16 v[120:123], v[188:191], v[204:207], v[120:123]
	v_mfma_f32_16x16x32_bf16 v[112:115], v[196:199], v[204:207], v[112:115]
	v_mfma_f32_16x16x32_bf16 v[104:107], v[188:191], v[214:217], v[104:107]
	v_mfma_f32_16x16x32_bf16 v[96:99], v[196:199], v[214:217], v[96:99]
	v_mfma_f32_16x16x32_bf16 v[88:91], v[188:191], v[222:225], v[88:91]
	v_mfma_f32_16x16x32_bf16 v[80:83], v[196:199], v[222:225], v[80:83]
	v_mfma_f32_16x16x32_bf16 v[72:75], v[188:191], v[230:233], v[72:75]
	v_mfma_f32_16x16x32_bf16 v[64:67], v[196:199], v[230:233], v[64:67]
	s_setprio 0
	s_barrier
	s_add_i32 s4, s79, s44
	v_lshl_add_u64 v[150:151], s[36:37], 0, v[132:133]
	s_mov_b32 m0, s4
	ds_read_b128 v[200:203], v181 offset:16384
	ds_read_b128 v[204:207], v181 offset:17408
	ds_read_b128 v[208:211], v181 offset:18432
	ds_read_b128 v[214:217], v181 offset:19456
	ds_read_b128 v[218:221], v181 offset:20480
	ds_read_b128 v[222:225], v181 offset:21504
	ds_read_b128 v[226:229], v181 offset:22528
	ds_read_b128 v[230:233], v181 offset:23552
	global_load_lds_dwordx4 v[150:151], off
	s_add_i32 m0, s4, 0x2000
	s_add_u32 s4, s36, 0x40000
	v_lshl_add_u64 v[154:155], s[36:37], 0, v[128:129]
	s_addc_u32 s5, s37, 0
	s_add_i32 s90, s80, s44
	global_load_lds_dwordx4 v[154:155], off
	v_lshl_add_u64 v[176:177], s[4:5], 0, v[132:133]
	s_mov_b32 m0, s90
	v_lshl_add_u64 v[234:235], s[38:39], 0, v[130:131]
	global_load_lds_dwordx4 v[176:177], off
	v_lshl_add_u64 v[176:177], s[4:5], 0, v[128:129]
	s_add_i32 m0, s90, 0x2000
	s_nop 0
	global_load_lds_dwordx4 v[176:177], off
	v_lshl_add_u64 v[176:177], s[38:39], 0, v[134:135]
	s_mov_b32 m0, s47
	s_nop 0
	global_load_lds_dwordx4 v[176:177], off
	s_mov_b32 m0, s49
	s_nop 0
	global_load_lds_dwordx4 v[234:235], off
	s_waitcnt vmcnt(8)
	s_waitcnt lgkmcnt(0)
	s_barrier
; #define PG8_STAGE(bufoff, gbase, voff) do { _Pragma("unroll") for (int _i = 0; _i < 2; ++_i) \
;         __builtin_amdgcn_global_load_lds((const unsigned*)((const char*)(gbase) + (voff)[_i]), (PG8_LAS unsigned*)(lds + (bufoff) + ldsw + _i * 8192), 16, 0, 0); } while (0)
; #define PG8_LDA(dst, b, h) do { _Pragma("unroll") for (int m = 0; m < 4; ++m) _Pragma("unroll") for (int k = 0; k < 2; ++k) dst[m][k] = *(const PG8_LAS bf16x8*)(lds + PG8_SA(b, h) + aoff + m * 2048 + k * 1024); } while (0)
; #define PG8_LDB(dst, b, h) do { _Pragma("unroll") for (int n = 0; n < 2; ++n) _Pragma("unroll") for (int k = 0; k < 2; ++k) dst[n][k] = *(const PG8_LAS bf16x8*)(lds + PG8_SB(b, h) + boff + n * 2048 + k * 1024); } while (0)
; #define PG8_MMA(ai, bj, At, Bt) do { __builtin_amdgcn_s_setprio(1); _Pragma("unroll") for (int m = 0; m < 4; ++m) _Pragma("unroll") for (int n = 0; n < 2; ++n) _Pragma("unroll") for (int k = 0; k < 2; ++k) \
;         acc[ai][bj][m][n] = __builtin_amdgcn_mfma_f32_16x16x32_bf16(Bt[n][k], At[m][k], acc[ai][bj][m][n], 0, 0, 0); __builtin_amdgcn_s_setprio(0); } while (0)
; #define PG8_WAIT_V(n) asm volatile("s_waitcnt vmcnt(" #n ")" ::: "memory")
; #define PG8_WAIT_L(n) asm volatile("s_waitcnt lgkmcnt(" #n ")" ::: "memory")
; #define PG8_BAR __builtin_amdgcn_s_barrier()
; #define PG8_SCHED __builtin_amdgcn_sched_barrier(0)
; template <class Epi, class Sched, bool ALIGN_EPI = false, bool SP2 = false>
; __device__ __forceinline__ void gemm_phase(PG8_LAS unsigned char* lds, const Gemm g, const Sched& S, const Epi& E) {
;     ...
;             PG8_WAIT_V(8); PG8_WAIT_L(0); PG8_BAR; PG8_MMA(1, 0, At, B0); PG8_MMA(1, 1, At, B1); PG8_BAR; PG8_SCHED;
;             PG8_LDB(B0, 1, 0); PG8_LDB(B1, 1, 1); PG8_SCHED; PG8_LDA(At, 1, 0); PG8_STAGE(PG8_SA(0, 1), a2 + hstep, voffA);
;             PG8_WAIT_V(8); PG8_WAIT_L(0); PG8_BAR; PG8_MMA(0, 0, At, B0); PG8_MMA(0, 1, At, B1); PG8_BAR; PG8_SCHED;
	s_setprio 1
	v_mfma_f32_16x16x32_bf16 v[60:63], v[146:149], v[200:203], v[60:63]
	v_mfma_f32_16x16x32_bf16 v[52:55], v[168:171], v[200:203], v[52:55]
	v_mfma_f32_16x16x32_bf16 v[44:47], v[146:149], v[208:211], v[44:47]
	v_mfma_f32_16x16x32_bf16 v[36:39], v[168:171], v[208:211], v[36:39]
	v_mfma_f32_16x16x32_bf16 v[28:31], v[146:149], v[218:221], v[28:31]
	v_mfma_f32_16x16x32_bf16 v[20:23], v[168:171], v[218:221], v[20:23]
	v_mfma_f32_16x16x32_bf16 v[12:15], v[146:149], v[226:229], v[12:15]
	v_mfma_f32_16x16x32_bf16 v[4:7], v[168:171], v[226:229], v[4:7]
	v_mfma_f32_16x16x32_bf16 v[60:63], v[164:167], v[204:207], v[60:63]
	v_mfma_f32_16x16x32_bf16 v[52:55], v[172:175], v[204:207], v[52:55]
	v_mfma_f32_16x16x32_bf16 v[44:47], v[164:167], v[214:217], v[44:47]
	v_mfma_f32_16x16x32_bf16 v[36:39], v[172:175], v[214:217], v[36:39]
	v_mfma_f32_16x16x32_bf16 v[28:31], v[164:167], v[222:225], v[28:31]
	v_mfma_f32_16x16x32_bf16 v[20:23], v[172:175], v[222:225], v[20:23]
	v_mfma_f32_16x16x32_bf16 v[12:15], v[164:167], v[230:233], v[12:15]
	v_mfma_f32_16x16x32_bf16 v[4:7], v[172:175], v[230:233], v[4:7]
	s_setprio 0
	s_setprio 1
	v_mfma_f32_16x16x32_bf16 v[56:59], v[184:187], v[200:203], v[56:59]
	v_mfma_f32_16x16x32_bf16 v[48:51], v[192:195], v[200:203], v[48:51]
	v_mfma_f32_16x16x32_bf16 v[40:43], v[184:187], v[208:211], v[40:43]
	v_mfma_f32_16x16x32_bf16 v[32:35], v[192:195], v[208:211], v[32:35]
	v_mfma_f32_16x16x32_bf16 v[24:27], v[184:187], v[218:221], v[24:27]
	v_mfma_f32_16x16x32_bf16 v[16:19], v[192:195], v[218:221], v[16:19]
	v_mfma_f32_16x16x32_bf16 v[8:11], v[184:187], v[226:229], v[8:11]
	v_mfma_f32_16x16x32_bf16 v[0:3], v[192:195], v[226:229], v[0:3]
	v_mfma_f32_16x16x32_bf16 v[56:59], v[188:191], v[204:207], v[56:59]
	v_mfma_f32_16x16x32_bf16 v[48:51], v[196:199], v[204:207], v[48:51]
	v_mfma_f32_16x16x32_bf16 v[40:43], v[188:191], v[214:217], v[40:43]
	v_mfma_f32_16x16x32_bf16 v[32:35], v[196:199], v[214:217], v[32:35]
	v_mfma_f32_16x16x32_bf16 v[24:27], v[188:191], v[222:225], v[24:27]
	v_mfma_f32_16x16x32_bf16 v[16:19], v[196:199], v[222:225], v[16:19]
	v_mfma_f32_16x16x32_bf16 v[8:11], v[188:191], v[230:233], v[8:11]
	v_mfma_f32_16x16x32_bf16 v[0:3], v[196:199], v[230:233], v[0:3]
	s_setprio 0
	s_barrier
	s_add_i32 s90, 0, 0x18000
	v_add_u32_e32 v136, s90, v163
	s_add_i32 s91, 0, 0x1c000
	ds_read_b128 v[146:149], v136
	ds_read_b128 v[164:167], v136 offset:1024
	ds_read_b128 v[168:171], v136 offset:2048
	ds_read_b128 v[172:175], v136 offset:3072
	v_add_u32_e32 v136, s91, v163
	ds_read_b128 v[184:187], v136
	ds_read_b128 v[188:191], v136 offset:1024
	ds_read_b128 v[192:195], v136 offset:2048
	ds_read_b128 v[196:199], v136 offset:3072
	s_add_u32 s4, s38, 0x40000
	s_addc_u32 s5, s39, 0
	s_mov_b32 m0, s53
	v_lshl_add_u64 v[236:237], s[4:5], 0, v[134:135]
	ds_read_b128 v[200:203], v181 offset:32768
	ds_read_b128 v[204:207], v181 offset:33792
	ds_read_b128 v[208:211], v181 offset:34816
	ds_read_b128 v[214:217], v181 offset:35840
	ds_read_b128 v[218:221], v181 offset:36864
	ds_read_b128 v[222:225], v181 offset:37888
	ds_read_b128 v[226:229], v181 offset:38912
	ds_read_b128 v[230:233], v181 offset:39936
	global_load_lds_dwordx4 v[236:237], off
	v_lshl_add_u64 v[236:237], s[4:5], 0, v[130:131]
	s_mov_b32 m0, s72
	s_nop 0
	global_load_lds_dwordx4 v[236:237], off
	s_waitcnt vmcnt(8)
	s_waitcnt lgkmcnt(0)
	s_barrier
	s_setprio 1
	v_mfma_f32_16x16x32_bf16 v[124:127], v[146:149], v[200:203], v[124:127]
	v_mfma_f32_16x16x32_bf16 v[116:119], v[168:171], v[200:203], v[116:119]
	v_mfma_f32_16x16x32_bf16 v[108:111], v[146:149], v[208:211], v[108:111]
	v_mfma_f32_16x16x32_bf16 v[100:103], v[168:171], v[208:211], v[100:103]
	v_mfma_f32_16x16x32_bf16 v[92:95], v[146:149], v[218:221], v[92:95]
	v_mfma_f32_16x16x32_bf16 v[84:87], v[168:171], v[218:221], v[84:87]
	v_mfma_f32_16x16x32_bf16 v[76:79], v[146:149], v[226:229], v[76:79]
	v_mfma_f32_16x16x32_bf16 v[68:71], v[168:171], v[226:229], v[68:71]
	v_mfma_f32_16x16x32_bf16 v[124:127], v[164:167], v[204:207], v[124:127]
	v_mfma_f32_16x16x32_bf16 v[116:119], v[172:175], v[204:207], v[116:119]
	v_mfma_f32_16x16x32_bf16 v[108:111], v[164:167], v[214:217], v[108:111]
	v_mfma_f32_16x16x32_bf16 v[100:103], v[172:175], v[214:217], v[100:103]
	v_mfma_f32_16x16x32_bf16 v[92:95], v[164:167], v[222:225], v[92:95]
	v_mfma_f32_16x16x32_bf16 v[84:87], v[172:175], v[222:225], v[84:87]
	v_mfma_f32_16x16x32_bf16 v[76:79], v[164:167], v[230:233], v[76:79]
	v_mfma_f32_16x16x32_bf16 v[68:71], v[172:175], v[230:233], v[68:71]
	s_setprio 0
	s_setprio 1
	v_mfma_f32_16x16x32_bf16 v[120:123], v[184:187], v[200:203], v[120:123]
	v_mfma_f32_16x16x32_bf16 v[112:115], v[192:195], v[200:203], v[112:115]
	v_mfma_f32_16x16x32_bf16 v[104:107], v[184:187], v[208:211], v[104:107]
	v_mfma_f32_16x16x32_bf16 v[96:99], v[192:195], v[208:211], v[96:99]
	v_mfma_f32_16x16x32_bf16 v[88:91], v[184:187], v[218:221], v[88:91]
	v_mfma_f32_16x16x32_bf16 v[80:83], v[192:195], v[218:221], v[80:83]
	v_mfma_f32_16x16x32_bf16 v[72:75], v[184:187], v[226:229], v[72:75]
	v_mfma_f32_16x16x32_bf16 v[64:67], v[192:195], v[226:229], v[64:67]
	v_mfma_f32_16x16x32_bf16 v[120:123], v[188:191], v[204:207], v[120:123]
	v_mfma_f32_16x16x32_bf16 v[112:115], v[196:199], v[204:207], v[112:115]
	v_mfma_f32_16x16x32_bf16 v[104:107], v[188:191], v[214:217], v[104:107]
	v_mfma_f32_16x16x32_bf16 v[96:99], v[196:199], v[214:217], v[96:99]
	v_mfma_f32_16x16x32_bf16 v[88:91], v[188:191], v[222:225], v[88:91]
	v_mfma_f32_16x16x32_bf16 v[80:83], v[196:199], v[222:225], v[80:83]
	v_mfma_f32_16x16x32_bf16 v[72:75], v[188:191], v[230:233], v[72:75]
	v_mfma_f32_16x16x32_bf16 v[64:67], v[196:199], v[230:233], v[64:67]
	s_setprio 0
	s_barrier
; #define PG8_STAGE(bufoff, gbase, voff) do { _Pragma("unroll") for (int _i = 0; _i < 2; ++_i) \
;         __builtin_amdgcn_global_load_lds((const unsigned*)((const char*)(gbase) + (voff)[_i]), (PG8_LAS unsigned*)(lds + (bufoff) + ldsw + _i * 8192), 16, 0, 0); } while (0)
; #define PG8_LDA(dst, b, h) do { _Pragma("unroll") for (int m = 0; m < 4; ++m) _Pragma("unroll") for (int k = 0; k < 2; ++k) dst[m][k] = *(const PG8_LAS bf16x8*)(lds + PG8_SA(b, h) + aoff + m * 2048 + k * 1024); } while (0)
; #define PG8_MMA(ai, bj, At, Bt) do { __builtin_amdgcn_s_setprio(1); _Pragma("unroll") for (int m = 0; m < 4; ++m) _Pragma("unroll") for (int n = 0; n < 2; ++n) _Pragma("unroll") for (int k = 0; k < 2; ++k) \
;         acc[ai][bj][m][n] = __builtin_amdgcn_mfma_f32_16x16x32_bf16(Bt[n][k], At[m][k], acc[ai][bj][m][n], 0, 0, 0); __builtin_amdgcn_s_setprio(0); } while (0)
; #define PG8_WAIT_V(n) asm volatile("s_waitcnt vmcnt(" #n ")" ::: "memory")
; #define PG8_WAIT_L(n) asm volatile("s_waitcnt lgkmcnt(" #n ")" ::: "memory")
; #define PG8_BAR __builtin_amdgcn_s_barrier()
; #define PG8_SCHED __builtin_amdgcn_sched_barrier(0)
; template <class Epi, class Sched, bool ALIGN_EPI = false, bool SP2 = false>
; __device__ __forceinline__ void gemm_phase(PG8_LAS unsigned char* lds, const Gemm g, const Sched& S, const Epi& E) {
;     ...
;             PG8_LDA(At, 1, 1); PG8_STAGE(PG8_SB(1, 0), b3, voffB); PG8_STAGE(PG8_SB(1, 1), b3 + hstep, voffB); PG8_STAGE(PG8_SA(1, 0), a3, voffA);
;             PG8_WAIT_V(8); PG8_WAIT_L(0); PG8_BAR; PG8_MMA(1, 0, At, B0); PG8_MMA(1, 1, At, B1); PG8_BAR; PG8_SCHED;
	s_add_i32 s4, s90, s44
	v_lshl_add_u64 v[150:151], v[150:151], 0, s[12:13]
	s_mov_b32 m0, s4
	ds_read_b128 v[200:203], v181 offset:49152
	ds_read_b128 v[204:207], v181 offset:50176
	ds_read_b128 v[208:211], v181 offset:51200
	ds_read_b128 v[214:217], v181 offset:52224
	ds_read_b128 v[218:221], v181 offset:53248
	ds_read_b128 v[222:225], v181 offset:54272
	ds_read_b128 v[226:229], v181 offset:55296
	ds_read_b128 v[230:233], v181 offset:56320
	global_load_lds_dwordx4 v[150:151], off
	s_add_i32 m0, s4, 0x2000
	s_add_u32 s4, s36, 0x40080
	v_lshl_add_u64 v[150:151], v[154:155], 0, s[12:13]
	s_addc_u32 s5, s37, 0
	s_add_i32 s36, s91, s44
	global_load_lds_dwordx4 v[150:151], off
	v_lshl_add_u64 v[150:151], s[4:5], 0, v[132:133]
	s_mov_b32 m0, s36
	s_nop 0
	global_load_lds_dwordx4 v[150:151], off
	v_lshl_add_u64 v[150:151], s[4:5], 0, v[128:129]
	s_add_i32 m0, s36, 0x2000
	s_nop 0
	global_load_lds_dwordx4 v[150:151], off
	v_lshl_add_u64 v[150:151], v[176:177], 0, s[12:13]
	s_mov_b32 m0, s75
	s_nop 0
	global_load_lds_dwordx4 v[150:151], off
	v_lshl_add_u64 v[150:151], v[234:235], 0, s[12:13]
	s_mov_b32 m0, s76
	s_nop 0
	global_load_lds_dwordx4 v[150:151], off
	s_waitcnt vmcnt(8)
	s_waitcnt lgkmcnt(0)
	s_barrier
	s_setprio 1
	v_mfma_f32_16x16x32_bf16 v[60:63], v[146:149], v[200:203], v[60:63]
	v_mfma_f32_16x16x32_bf16 v[52:55], v[168:171], v[200:203], v[52:55]
	v_mfma_f32_16x16x32_bf16 v[44:47], v[146:149], v[208:211], v[44:47]
	v_mfma_f32_16x16x32_bf16 v[36:39], v[168:171], v[208:211], v[36:39]
	v_mfma_f32_16x16x32_bf16 v[28:31], v[146:149], v[218:221], v[28:31]
	v_mfma_f32_16x16x32_bf16 v[20:23], v[168:171], v[218:221], v[20:23]
	v_mfma_f32_16x16x32_bf16 v[12:15], v[146:149], v[226:229], v[12:15]
	v_mfma_f32_16x16x32_bf16 v[4:7], v[168:171], v[226:229], v[4:7]
	v_mfma_f32_16x16x32_bf16 v[60:63], v[164:167], v[204:207], v[60:63]
	v_mfma_f32_16x16x32_bf16 v[52:55], v[172:175], v[204:207], v[52:55]
	v_mfma_f32_16x16x32_bf16 v[44:47], v[164:167], v[214:217], v[44:47]
	v_mfma_f32_16x16x32_bf16 v[36:39], v[172:175], v[214:217], v[36:39]
	v_mfma_f32_16x16x32_bf16 v[28:31], v[164:167], v[222:225], v[28:31]
	v_mfma_f32_16x16x32_bf16 v[20:23], v[172:175], v[222:225], v[20:23]
	v_mfma_f32_16x16x32_bf16 v[12:15], v[164:167], v[230:233], v[12:15]
	v_mfma_f32_16x16x32_bf16 v[4:7], v[172:175], v[230:233], v[4:7]
	s_setprio 0
	s_setprio 1
	v_mfma_f32_16x16x32_bf16 v[56:59], v[184:187], v[200:203], v[56:59]
	v_mfma_f32_16x16x32_bf16 v[48:51], v[192:195], v[200:203], v[48:51]
	v_mfma_f32_16x16x32_bf16 v[40:43], v[184:187], v[208:211], v[40:43]
	v_mfma_f32_16x16x32_bf16 v[32:35], v[192:195], v[208:211], v[32:35]
	v_mfma_f32_16x16x32_bf16 v[24:27], v[184:187], v[218:221], v[24:27]
	v_mfma_f32_16x16x32_bf16 v[16:19], v[192:195], v[218:221], v[16:19]
	v_mfma_f32_16x16x32_bf16 v[8:11], v[184:187], v[226:229], v[8:11]
	v_mfma_f32_16x16x32_bf16 v[0:3], v[192:195], v[226:229], v[0:3]
	v_mfma_f32_16x16x32_bf16 v[56:59], v[188:191], v[204:207], v[56:59]
	v_mfma_f32_16x16x32_bf16 v[48:51], v[196:199], v[204:207], v[48:51]
	v_mfma_f32_16x16x32_bf16 v[40:43], v[188:191], v[214:217], v[40:43]
	v_mfma_f32_16x16x32_bf16 v[32:35], v[196:199], v[214:217], v[32:35]
	v_mfma_f32_16x16x32_bf16 v[24:27], v[188:191], v[222:225], v[24:27]
	v_mfma_f32_16x16x32_bf16 v[16:19], v[196:199], v[222:225], v[16:19]
	v_mfma_f32_16x16x32_bf16 v[8:11], v[188:191], v[230:233], v[8:11]
	v_mfma_f32_16x16x32_bf16 v[0:3], v[196:199], v[230:233], v[0:3]
	s_setprio 0
	s_barrier
	s_add_i32 s86, s86, 2
	s_add_u32 s34, s34, 0x100
	s_addc_u32 s35, s35, 0
	s_add_u32 s85, s85, 0x100
	s_addc_u32 s89, s89, 0
	s_cmp_gt_u32 s86, 13
	s_cbranch_scc0 .LBB0_469
	s_and_b64 vcc, exec, s[22:23]
	s_cbranch_vccz .LBB0_472
	s_barrier

; #define PG8_STAGE(bufoff, gbase, voff) do { _Pragma("unroll") for (int _i = 0; _i < 2; ++_i) \
;         __builtin_amdgcn_global_load_lds((const unsigned*)((const char*)(gbase) + (voff)[_i]), (PG8_LAS unsigned*)(lds + (bufoff) + ldsw + _i * 8192), 16, 0, 0); } while (0)
; #define PG8_LDA(dst, b, h) do { _Pragma("unroll") for (int m = 0; m < 4; ++m) _Pragma("unroll") for (int k = 0; k < 2; ++k) dst[m][k] = *(const PG8_LAS bf16x8*)(lds + PG8_SA(b, h) + aoff + m * 2048 + k * 1024); } while (0)
; #define PG8_LDB(dst, b, h) do { _Pragma("unroll") for (int n = 0; n < 2; ++n) _Pragma("unroll") for (int k = 0; k < 2; ++k) dst[n][k] = *(const PG8_LAS bf16x8*)(lds + PG8_SB(b, h) + boff + n * 2048 + k * 1024); } while (0)
; #define PG8_MMA(ai, bj, At, Bt) do { __builtin_amdgcn_s_setprio(1); _Pragma("unroll") for (int m = 0; m < 4; ++m) _Pragma("unroll") for (int n = 0; n < 2; ++n) _Pragma("unroll") for (int k = 0; k < 2; ++k) \
;         acc[ai][bj][m][n] = __builtin_amdgcn_mfma_f32_16x16x32_bf16(Bt[n][k], At[m][k], acc[ai][bj][m][n], 0, 0, 0); __builtin_amdgcn_s_setprio(0); } while (0)
; #define PG8_WAIT_V(n) asm volatile("s_waitcnt vmcnt(" #n ")" ::: "memory")
; #define PG8_WAIT_L(n) asm volatile("s_waitcnt lgkmcnt(" #n ")" ::: "memory")
; #define PG8_BAR __builtin_amdgcn_s_barrier()
; #define PG8_SCHED __builtin_amdgcn_sched_barrier(0)
; template <class Epi, class Sched, bool ALIGN_EPI = false, bool SP2 = false>
; __device__ __forceinline__ void gemm_phase(PG8_LAS unsigned char* lds, const Gemm g, const Sched& S, const Epi& E) {
;     ...
;         const int nt = Sched::SPLITK ? cur.nt : ntf;
;     ...
;             PG8_LDB(B0, 0, 0); PG8_LDB(B1, 0, 1); PG8_SCHED; PG8_LDA(At, 0, 0); PG8_STAGE(PG8_SA(1, 1), a1 + hstep, voffA);
;             PG8_WAIT_V(8); PG8_WAIT_L(0); PG8_BAR; PG8_MMA(0, 0, At, B0); PG8_MMA(0, 1, At, B1); PG8_BAR; PG8_SCHED;
;             PG8_LDA(At, 0, 1); PG8_STAGE(PG8_SB(0, 0), b2, voffB); PG8_STAGE(PG8_SB(0, 1), b2 + hstep, voffB); PG8_STAGE(PG8_SA(0, 0), a2, voffA);
;             PG8_WAIT_V(8); PG8_WAIT_L(0); PG8_BAR; PG8_MMA(1, 0, At, B0); PG8_MMA(1, 1, At, B1); PG8_BAR; PG8_SCHED;
.LBB0_568:
	s_waitcnt lgkmcnt(0)
	ds_read_b128 v[128:131], v196
	ds_read_b128 v[132:135], v196 offset:1024
	ds_read_b128 v[136:139], v196 offset:2048
	ds_read_b128 v[140:143], v196 offset:3072
	ds_read_b128 v[144:147], v197
	ds_read_b128 v[148:151], v197 offset:1024
	ds_read_b128 v[176:179], v197 offset:2048
	ds_read_b128 v[180:183], v197 offset:3072
	s_add_i32 s4, s38, 2
	s_add_u32 s36, s34, 0x100
	s_addc_u32 s37, s35, 0
	s_cmp_eq_u32 vcc_lo, s38
	s_cselect_b32 s38, s30, vcc_hi
	s_cselect_b32 s41, s29, s37
	s_cselect_b32 s40, s28, s36
	s_cselect_b32 s39, s31, s86
	v_lshl_add_u64 v[222:223], s[34:35], 0, v[170:171]
	s_add_i32 m0, s47, 0xc000
	ds_read_b128 v[184:187], v198
	ds_read_b128 v[188:191], v198 offset:1024
	ds_read_b128 v[192:195], v198 offset:2048
	ds_read_b128 v[200:203], v198 offset:3072
	ds_read_b128 v[204:207], v198 offset:4096
	ds_read_b128 v[208:211], v198 offset:5120
	ds_read_b128 v[214:217], v198 offset:6144
	ds_read_b128 v[218:221], v198 offset:7168
	global_load_lds_dwordx4 v[222:223], off
	v_lshl_add_u64 v[222:223], s[34:35], 0, v[172:173]
	s_add_i32 m0, s47, 0xe000
	s_nop 0
	global_load_lds_dwordx4 v[222:223], off
	s_waitcnt vmcnt(8)
	s_waitcnt lgkmcnt(0)
	s_barrier
	s_setprio 1
	v_mfma_f32_16x16x32_bf16 v[124:127], v[128:131], v[184:187], v[124:127]
	v_mfma_f32_16x16x32_bf16 v[120:123], v[136:139], v[184:187], v[120:123]
	v_mfma_f32_16x16x32_bf16 v[116:119], v[128:131], v[192:195], v[116:119]
	v_mfma_f32_16x16x32_bf16 v[108:111], v[136:139], v[192:195], v[108:111]
	v_mfma_f32_16x16x32_bf16 v[100:103], v[128:131], v[204:207], v[100:103]
	v_mfma_f32_16x16x32_bf16 v[92:95], v[136:139], v[204:207], v[92:95]
	v_mfma_f32_16x16x32_bf16 v[84:87], v[128:131], v[214:217], v[84:87]
	v_mfma_f32_16x16x32_bf16 v[76:79], v[136:139], v[214:217], v[76:79]
	v_mfma_f32_16x16x32_bf16 v[124:127], v[132:135], v[188:191], v[124:127]
	v_mfma_f32_16x16x32_bf16 v[120:123], v[140:143], v[188:191], v[120:123]
	v_mfma_f32_16x16x32_bf16 v[116:119], v[132:135], v[200:203], v[116:119]
	v_mfma_f32_16x16x32_bf16 v[108:111], v[140:143], v[200:203], v[108:111]
	v_mfma_f32_16x16x32_bf16 v[100:103], v[132:135], v[208:211], v[100:103]
	v_mfma_f32_16x16x32_bf16 v[92:95], v[140:143], v[208:211], v[92:95]
	v_mfma_f32_16x16x32_bf16 v[84:87], v[132:135], v[218:221], v[84:87]
	v_mfma_f32_16x16x32_bf16 v[76:79], v[140:143], v[218:221], v[76:79]
	s_setprio 0
	s_setprio 1
	v_mfma_f32_16x16x32_bf16 v[112:115], v[144:147], v[184:187], v[112:115]
	v_mfma_f32_16x16x32_bf16 v[104:107], v[176:179], v[184:187], v[104:107]
	v_mfma_f32_16x16x32_bf16 v[96:99], v[144:147], v[192:195], v[96:99]
	v_mfma_f32_16x16x32_bf16 v[88:91], v[176:179], v[192:195], v[88:91]
	v_mfma_f32_16x16x32_bf16 v[80:83], v[144:147], v[204:207], v[80:83]
	v_mfma_f32_16x16x32_bf16 v[72:75], v[176:179], v[204:207], v[72:75]
	v_mfma_f32_16x16x32_bf16 v[68:71], v[144:147], v[214:217], v[68:71]
	v_mfma_f32_16x16x32_bf16 v[64:67], v[176:179], v[214:217], v[64:67]
	v_mfma_f32_16x16x32_bf16 v[112:115], v[148:151], v[188:191], v[112:115]
	v_mfma_f32_16x16x32_bf16 v[104:107], v[180:183], v[188:191], v[104:107]
	v_mfma_f32_16x16x32_bf16 v[96:99], v[148:151], v[200:203], v[96:99]
	v_mfma_f32_16x16x32_bf16 v[88:91], v[180:183], v[200:203], v[88:91]
	v_mfma_f32_16x16x32_bf16 v[80:83], v[148:151], v[208:211], v[80:83]
	v_mfma_f32_16x16x32_bf16 v[72:75], v[180:183], v[208:211], v[72:75]
	v_mfma_f32_16x16x32_bf16 v[68:71], v[148:151], v[218:221], v[68:71]
	v_mfma_f32_16x16x32_bf16 v[64:67], v[180:183], v[218:221], v[64:67]
	s_setprio 0
	s_barrier
	s_add_i32 s5, s79, s46
	v_lshl_add_u64 v[222:223], s[38:39], 0, v[164:165]
	s_mov_b32 m0, s5
	ds_read_b128 v[184:187], v198 offset:16384
	ds_read_b128 v[188:191], v198 offset:17408
	ds_read_b128 v[192:195], v198 offset:18432
	ds_read_b128 v[200:203], v198 offset:19456
	ds_read_b128 v[204:207], v198 offset:20480
	ds_read_b128 v[208:211], v198 offset:21504
	ds_read_b128 v[214:217], v198 offset:22528
	ds_read_b128 v[218:221], v198 offset:23552
	global_load_lds_dwordx4 v[222:223], off
	s_add_i32 m0, s5, 0x2000
	s_add_u32 s34, s38, 0xb0000
	v_lshl_add_u64 v[224:225], s[38:39], 0, v[168:169]
	s_addc_u32 s35, s39, 0
	s_add_i32 s5, s80, s46
	global_load_lds_dwordx4 v[224:225], off
	v_lshl_add_u64 v[226:227], s[34:35], 0, v[164:165]
	s_mov_b32 m0, s5
	v_lshl_add_u64 v[228:229], s[40:41], 0, v[166:167]
	global_load_lds_dwordx4 v[226:227], off
	v_lshl_add_u64 v[226:227], s[34:35], 0, v[168:169]
	s_add_i32 m0, s5, 0x2000
	s_nop 0
	global_load_lds_dwordx4 v[226:227], off
	v_lshl_add_u64 v[226:227], s[40:41], 0, v[154:155]
	s_mov_b32 m0, s47
	s_nop 0
	global_load_lds_dwordx4 v[226:227], off
	s_mov_b32 m0, s49
	s_nop 0
	global_load_lds_dwordx4 v[228:229], off
	s_waitcnt vmcnt(8)
	s_waitcnt lgkmcnt(0)
	s_barrier
; #define PG8_STAGE(bufoff, gbase, voff) do { _Pragma("unroll") for (int _i = 0; _i < 2; ++_i) \
;         __builtin_amdgcn_global_load_lds((const unsigned*)((const char*)(gbase) + (voff)[_i]), (PG8_LAS unsigned*)(lds + (bufoff) + ldsw + _i * 8192), 16, 0, 0); } while (0)
; #define PG8_LDA(dst, b, h) do { _Pragma("unroll") for (int m = 0; m < 4; ++m) _Pragma("unroll") for (int k = 0; k < 2; ++k) dst[m][k] = *(const PG8_LAS bf16x8*)(lds + PG8_SA(b, h) + aoff + m * 2048 + k * 1024); } while (0)
; #define PG8_LDB(dst, b, h) do { _Pragma("unroll") for (int n = 0; n < 2; ++n) _Pragma("unroll") for (int k = 0; k < 2; ++k) dst[n][k] = *(const PG8_LAS bf16x8*)(lds + PG8_SB(b, h) + boff + n * 2048 + k * 1024); } while (0)
; #define PG8_MMA(ai, bj, At, Bt) do { __builtin_amdgcn_s_setprio(1); _Pragma("unroll") for (int m = 0; m < 4; ++m) _Pragma("unroll") for (int n = 0; n < 2; ++n) _Pragma("unroll") for (int k = 0; k < 2; ++k) \
;         acc[ai][bj][m][n] = __builtin_amdgcn_mfma_f32_16x16x32_bf16(Bt[n][k], At[m][k], acc[ai][bj][m][n], 0, 0, 0); __builtin_amdgcn_s_setprio(0); } while (0)
; #define PG8_WAIT_V(n) asm volatile("s_waitcnt vmcnt(" #n ")" ::: "memory")
; #define PG8_WAIT_L(n) asm volatile("s_waitcnt lgkmcnt(" #n ")" ::: "memory")
; #define PG8_BAR __builtin_amdgcn_s_barrier()
; #define PG8_SCHED __builtin_amdgcn_sched_barrier(0)
; template <class Epi, class Sched, bool ALIGN_EPI = false, bool SP2 = false>
; __device__ __forceinline__ void gemm_phase(PG8_LAS unsigned char* lds, const Gemm g, const Sched& S, const Epi& E) {
;     ...
;             PG8_WAIT_V(8); PG8_WAIT_L(0); PG8_BAR; PG8_MMA(1, 0, At, B0); PG8_MMA(1, 1, At, B1); PG8_BAR; PG8_SCHED;
;             PG8_LDB(B0, 1, 0); PG8_LDB(B1, 1, 1); PG8_SCHED; PG8_LDA(At, 1, 0); PG8_STAGE(PG8_SA(0, 1), a2 + hstep, voffA);
;             PG8_WAIT_V(8); PG8_WAIT_L(0); PG8_BAR; PG8_MMA(0, 0, At, B0); PG8_MMA(0, 1, At, B1); PG8_BAR; PG8_SCHED;
	s_setprio 1
	v_mfma_f32_16x16x32_bf16 v[60:63], v[128:131], v[184:187], v[60:63]
	v_mfma_f32_16x16x32_bf16 v[56:59], v[136:139], v[184:187], v[56:59]
	v_mfma_f32_16x16x32_bf16 v[52:55], v[128:131], v[192:195], v[52:55]
	v_mfma_f32_16x16x32_bf16 v[44:47], v[136:139], v[192:195], v[44:47]
	v_mfma_f32_16x16x32_bf16 v[36:39], v[128:131], v[204:207], v[36:39]
	v_mfma_f32_16x16x32_bf16 v[28:31], v[136:139], v[204:207], v[28:31]
	v_mfma_f32_16x16x32_bf16 v[20:23], v[128:131], v[214:217], v[20:23]
	v_mfma_f32_16x16x32_bf16 v[12:15], v[136:139], v[214:217], v[12:15]
	v_mfma_f32_16x16x32_bf16 v[60:63], v[132:135], v[188:191], v[60:63]
	v_mfma_f32_16x16x32_bf16 v[56:59], v[140:143], v[188:191], v[56:59]
	v_mfma_f32_16x16x32_bf16 v[52:55], v[132:135], v[200:203], v[52:55]
	v_mfma_f32_16x16x32_bf16 v[44:47], v[140:143], v[200:203], v[44:47]
	v_mfma_f32_16x16x32_bf16 v[36:39], v[132:135], v[208:211], v[36:39]
	v_mfma_f32_16x16x32_bf16 v[28:31], v[140:143], v[208:211], v[28:31]
	v_mfma_f32_16x16x32_bf16 v[20:23], v[132:135], v[218:221], v[20:23]
	v_mfma_f32_16x16x32_bf16 v[12:15], v[140:143], v[218:221], v[12:15]
	s_setprio 0
	s_setprio 1
	v_mfma_f32_16x16x32_bf16 v[48:51], v[144:147], v[184:187], v[48:51]
	v_mfma_f32_16x16x32_bf16 v[40:43], v[176:179], v[184:187], v[40:43]
	v_mfma_f32_16x16x32_bf16 v[32:35], v[144:147], v[192:195], v[32:35]
	v_mfma_f32_16x16x32_bf16 v[24:27], v[176:179], v[192:195], v[24:27]
	v_mfma_f32_16x16x32_bf16 v[16:19], v[144:147], v[204:207], v[16:19]
	v_mfma_f32_16x16x32_bf16 v[8:11], v[176:179], v[204:207], v[8:11]
	v_mfma_f32_16x16x32_bf16 v[4:7], v[144:147], v[214:217], v[4:7]
	v_mfma_f32_16x16x32_bf16 v[0:3], v[176:179], v[214:217], v[0:3]
	v_mfma_f32_16x16x32_bf16 v[48:51], v[148:151], v[188:191], v[48:51]
	v_mfma_f32_16x16x32_bf16 v[40:43], v[180:183], v[188:191], v[40:43]
	v_mfma_f32_16x16x32_bf16 v[32:35], v[148:151], v[200:203], v[32:35]
	v_mfma_f32_16x16x32_bf16 v[24:27], v[180:183], v[200:203], v[24:27]
	v_mfma_f32_16x16x32_bf16 v[16:19], v[148:151], v[208:211], v[16:19]
	v_mfma_f32_16x16x32_bf16 v[8:11], v[180:183], v[208:211], v[8:11]
	v_mfma_f32_16x16x32_bf16 v[4:7], v[148:151], v[218:221], v[4:7]
	v_mfma_f32_16x16x32_bf16 v[0:3], v[180:183], v[218:221], v[0:3]
	s_setprio 0
	s_barrier
	s_add_i32 s5, 0, 0x18000
	s_add_i32 s14, 0, 0x1c000
	v_add_u32_e32 v140, s5, v159
	v_add_u32_e32 v180, s14, v159
	ds_read_b128 v[128:131], v140
	ds_read_b128 v[132:135], v140 offset:1024
	ds_read_b128 v[136:139], v140 offset:2048
	ds_read_b128 v[140:143], v140 offset:3072
	ds_read_b128 v[144:147], v180
	ds_read_b128 v[148:151], v180 offset:1024
	ds_read_b128 v[176:179], v180 offset:2048
	ds_read_b128 v[180:183], v180 offset:3072
	s_add_u32 s34, s40, 0xb0000
	s_addc_u32 s35, s41, 0
	s_mov_b32 m0, s53
	v_lshl_add_u64 v[230:231], s[34:35], 0, v[154:155]
	ds_read_b128 v[184:187], v198 offset:32768
	ds_read_b128 v[188:191], v198 offset:33792
	ds_read_b128 v[192:195], v198 offset:34816
	ds_read_b128 v[200:203], v198 offset:35840
	ds_read_b128 v[204:207], v198 offset:36864
	ds_read_b128 v[208:211], v198 offset:37888
	ds_read_b128 v[214:217], v198 offset:38912
	ds_read_b128 v[218:221], v198 offset:39936
	global_load_lds_dwordx4 v[230:231], off
	v_lshl_add_u64 v[230:231], s[34:35], 0, v[166:167]
	s_mov_b32 m0, s72
	s_nop 0
	global_load_lds_dwordx4 v[230:231], off
	s_waitcnt vmcnt(8)
	s_waitcnt lgkmcnt(0)
	s_barrier
	s_setprio 1
	v_mfma_f32_16x16x32_bf16 v[124:127], v[128:131], v[184:187], v[124:127]
	v_mfma_f32_16x16x32_bf16 v[120:123], v[136:139], v[184:187], v[120:123]
	v_mfma_f32_16x16x32_bf16 v[116:119], v[128:131], v[192:195], v[116:119]
	v_mfma_f32_16x16x32_bf16 v[108:111], v[136:139], v[192:195], v[108:111]
	v_mfma_f32_16x16x32_bf16 v[100:103], v[128:131], v[204:207], v[100:103]
	v_mfma_f32_16x16x32_bf16 v[92:95], v[136:139], v[204:207], v[92:95]
	v_mfma_f32_16x16x32_bf16 v[84:87], v[128:131], v[214:217], v[84:87]
	v_mfma_f32_16x16x32_bf16 v[76:79], v[136:139], v[214:217], v[76:79]
	v_mfma_f32_16x16x32_bf16 v[124:127], v[132:135], v[188:191], v[124:127]
	v_mfma_f32_16x16x32_bf16 v[120:123], v[140:143], v[188:191], v[120:123]
	v_mfma_f32_16x16x32_bf16 v[116:119], v[132:135], v[200:203], v[116:119]
	v_mfma_f32_16x16x32_bf16 v[108:111], v[140:143], v[200:203], v[108:111]
	v_mfma_f32_16x16x32_bf16 v[100:103], v[132:135], v[208:211], v[100:103]
	v_mfma_f32_16x16x32_bf16 v[92:95], v[140:143], v[208:211], v[92:95]
	v_mfma_f32_16x16x32_bf16 v[84:87], v[132:135], v[218:221], v[84:87]
	v_mfma_f32_16x16x32_bf16 v[76:79], v[140:143], v[218:221], v[76:79]
	s_setprio 0
	s_setprio 1
	v_mfma_f32_16x16x32_bf16 v[112:115], v[144:147], v[184:187], v[112:115]
	v_mfma_f32_16x16x32_bf16 v[104:107], v[176:179], v[184:187], v[104:107]
	v_mfma_f32_16x16x32_bf16 v[96:99], v[144:147], v[192:195], v[96:99]
	v_mfma_f32_16x16x32_bf16 v[88:91], v[176:179], v[192:195], v[88:91]
	v_mfma_f32_16x16x32_bf16 v[80:83], v[144:147], v[204:207], v[80:83]
	v_mfma_f32_16x16x32_bf16 v[72:75], v[176:179], v[204:207], v[72:75]
	v_mfma_f32_16x16x32_bf16 v[68:71], v[144:147], v[214:217], v[68:71]
	v_mfma_f32_16x16x32_bf16 v[64:67], v[176:179], v[214:217], v[64:67]
	v_mfma_f32_16x16x32_bf16 v[112:115], v[148:151], v[188:191], v[112:115]
	v_mfma_f32_16x16x32_bf16 v[104:107], v[180:183], v[188:191], v[104:107]
	v_mfma_f32_16x16x32_bf16 v[96:99], v[148:151], v[200:203], v[96:99]
	v_mfma_f32_16x16x32_bf16 v[88:91], v[180:183], v[200:203], v[88:91]
	v_mfma_f32_16x16x32_bf16 v[80:83], v[148:151], v[208:211], v[80:83]
	v_mfma_f32_16x16x32_bf16 v[72:75], v[180:183], v[208:211], v[72:75]
	v_mfma_f32_16x16x32_bf16 v[68:71], v[148:151], v[218:221], v[68:71]
	v_mfma_f32_16x16x32_bf16 v[64:67], v[180:183], v[218:221], v[64:67]
	s_setprio 0
	s_barrier
; #define PG8_STAGE(bufoff, gbase, voff) do { _Pragma("unroll") for (int _i = 0; _i < 2; ++_i) \
;         __builtin_amdgcn_global_load_lds((const unsigned*)((const char*)(gbase) + (voff)[_i]), (PG8_LAS unsigned*)(lds + (bufoff) + ldsw + _i * 8192), 16, 0, 0); } while (0)
; #define PG8_LDA(dst, b, h) do { _Pragma("unroll") for (int m = 0; m < 4; ++m) _Pragma("unroll") for (int k = 0; k < 2; ++k) dst[m][k] = *(const PG8_LAS bf16x8*)(lds + PG8_SA(b, h) + aoff + m * 2048 + k * 1024); } while (0)
; #define PG8_MMA(ai, bj, At, Bt) do { __builtin_amdgcn_s_setprio(1); _Pragma("unroll") for (int m = 0; m < 4; ++m) _Pragma("unroll") for (int n = 0; n < 2; ++n) _Pragma("unroll") for (int k = 0; k < 2; ++k) \
;         acc[ai][bj][m][n] = __builtin_amdgcn_mfma_f32_16x16x32_bf16(Bt[n][k], At[m][k], acc[ai][bj][m][n], 0, 0, 0); __builtin_amdgcn_s_setprio(0); } while (0)
; #define PG8_WAIT_V(n) asm volatile("s_waitcnt vmcnt(" #n ")" ::: "memory")
; #define PG8_WAIT_L(n) asm volatile("s_waitcnt lgkmcnt(" #n ")" ::: "memory")
; #define PG8_BAR __builtin_amdgcn_s_barrier()
; #define PG8_SCHED __builtin_amdgcn_sched_barrier(0)
; template <class Epi, class Sched, bool ALIGN_EPI = false, bool SP2 = false>
; __device__ __forceinline__ void gemm_phase(PG8_LAS unsigned char* lds, const Gemm g, const Sched& S, const Epi& E) {
;     ...
;             PG8_LDA(At, 1, 1); PG8_STAGE(PG8_SB(1, 0), b3, voffB); PG8_STAGE(PG8_SB(1, 1), b3 + hstep, voffB); PG8_STAGE(PG8_SA(1, 0), a3, voffA);
;             PG8_WAIT_V(8); PG8_WAIT_L(0); PG8_BAR; PG8_MMA(1, 0, At, B0); PG8_MMA(1, 1, At, B1); PG8_BAR; PG8_SCHED;
	s_add_i32 s5, s5, s46
	v_lshl_add_u64 v[222:223], v[222:223], 0, s[24:25]
	s_mov_b32 m0, s5
	ds_read_b128 v[184:187], v198 offset:49152
	ds_read_b128 v[188:191], v198 offset:50176
	ds_read_b128 v[192:195], v198 offset:51200
	ds_read_b128 v[200:203], v198 offset:52224
	ds_read_b128 v[204:207], v198 offset:53248
	ds_read_b128 v[208:211], v198 offset:54272
	ds_read_b128 v[214:217], v198 offset:55296
	ds_read_b128 v[218:221], v198 offset:56320
	global_load_lds_dwordx4 v[222:223], off
	s_add_i32 m0, s5, 0x2000
	s_add_u32 s34, s38, 0xb0080
	v_lshl_add_u64 v[222:223], v[224:225], 0, s[24:25]
	s_addc_u32 s35, s39, 0
	s_add_i32 s5, s14, s46
	global_load_lds_dwordx4 v[222:223], off
	v_lshl_add_u64 v[222:223], s[34:35], 0, v[164:165]
	s_mov_b32 m0, s5
	s_nop 0
	global_load_lds_dwordx4 v[222:223], off
	v_lshl_add_u64 v[222:223], s[34:35], 0, v[168:169]
	s_add_i32 m0, s5, 0x2000
	s_nop 0
	global_load_lds_dwordx4 v[222:223], off
	v_lshl_add_u64 v[222:223], v[226:227], 0, s[24:25]
	s_mov_b32 m0, s74
	s_nop 0
	global_load_lds_dwordx4 v[222:223], off
	v_lshl_add_u64 v[222:223], v[228:229], 0, s[24:25]
	s_mov_b32 m0, s75
	s_nop 0
	global_load_lds_dwordx4 v[222:223], off
	s_waitcnt vmcnt(8)
	s_waitcnt lgkmcnt(0)
	s_barrier
	s_setprio 1
	v_mfma_f32_16x16x32_bf16 v[60:63], v[128:131], v[184:187], v[60:63]
	v_mfma_f32_16x16x32_bf16 v[56:59], v[136:139], v[184:187], v[56:59]
	v_mfma_f32_16x16x32_bf16 v[52:55], v[128:131], v[192:195], v[52:55]
	v_mfma_f32_16x16x32_bf16 v[44:47], v[136:139], v[192:195], v[44:47]
	v_mfma_f32_16x16x32_bf16 v[36:39], v[128:131], v[204:207], v[36:39]
	v_mfma_f32_16x16x32_bf16 v[28:31], v[136:139], v[204:207], v[28:31]
	v_mfma_f32_16x16x32_bf16 v[20:23], v[128:131], v[214:217], v[20:23]
	v_mfma_f32_16x16x32_bf16 v[12:15], v[136:139], v[214:217], v[12:15]
	v_mfma_f32_16x16x32_bf16 v[60:63], v[132:135], v[188:191], v[60:63]
	v_mfma_f32_16x16x32_bf16 v[56:59], v[140:143], v[188:191], v[56:59]
	v_mfma_f32_16x16x32_bf16 v[52:55], v[132:135], v[200:203], v[52:55]
	v_mfma_f32_16x16x32_bf16 v[44:47], v[140:143], v[200:203], v[44:47]
	v_mfma_f32_16x16x32_bf16 v[36:39], v[132:135], v[208:211], v[36:39]
	v_mfma_f32_16x16x32_bf16 v[28:31], v[140:143], v[208:211], v[28:31]
	v_mfma_f32_16x16x32_bf16 v[20:23], v[132:135], v[218:221], v[20:23]
	v_mfma_f32_16x16x32_bf16 v[12:15], v[140:143], v[218:221], v[12:15]
	s_setprio 0
	s_setprio 1
	v_mfma_f32_16x16x32_bf16 v[48:51], v[144:147], v[184:187], v[48:51]
	v_mfma_f32_16x16x32_bf16 v[40:43], v[176:179], v[184:187], v[40:43]
	v_mfma_f32_16x16x32_bf16 v[32:35], v[144:147], v[192:195], v[32:35]
	v_mfma_f32_16x16x32_bf16 v[24:27], v[176:179], v[192:195], v[24:27]
	v_mfma_f32_16x16x32_bf16 v[16:19], v[144:147], v[204:207], v[16:19]
	v_mfma_f32_16x16x32_bf16 v[8:11], v[176:179], v[204:207], v[8:11]
	v_mfma_f32_16x16x32_bf16 v[4:7], v[144:147], v[214:217], v[4:7]
	v_mfma_f32_16x16x32_bf16 v[0:3], v[176:179], v[214:217], v[0:3]
	v_mfma_f32_16x16x32_bf16 v[48:51], v[148:151], v[188:191], v[48:51]
	v_mfma_f32_16x16x32_bf16 v[40:43], v[180:183], v[188:191], v[40:43]
	v_mfma_f32_16x16x32_bf16 v[32:35], v[148:151], v[200:203], v[32:35]
	v_mfma_f32_16x16x32_bf16 v[24:27], v[180:183], v[200:203], v[24:27]
	v_mfma_f32_16x16x32_bf16 v[16:19], v[148:151], v[208:211], v[16:19]
	v_mfma_f32_16x16x32_bf16 v[8:11], v[180:183], v[208:211], v[8:11]
	v_mfma_f32_16x16x32_bf16 v[4:7], v[148:151], v[218:221], v[4:7]
	v_mfma_f32_16x16x32_bf16 v[0:3], v[180:183], v[218:221], v[0:3]
	s_setprio 0
	s_barrier
	s_add_u32 vcc_hi, vcc_hi, 0x100
	s_addc_u32 s86, s86, 0
	s_cmp_ge_i32 s4, s97
	s_mov_b64 s[34:35], s[36:37]
	s_mov_b32 s38, s4
	s_cbranch_scc0 .LBB0_568
	s_and_b64 vcc, exec, s[26:27]
	s_cbranch_vccz .LBB0_571
	s_barrier

; #define PG8_STAGE(bufoff, gbase, voff) do { _Pragma("unroll") for (int _i = 0; _i < 2; ++_i) \
;         __builtin_amdgcn_global_load_lds((const unsigned*)((const char*)(gbase) + (voff)[_i]), (PG8_LAS unsigned*)(lds + (bufoff) + ldsw + _i * 8192), 16, 0, 0); } while (0)
; #define PG8_LDA(dst, b, h) do { _Pragma("unroll") for (int m = 0; m < 4; ++m) _Pragma("unroll") for (int k = 0; k < 2; ++k) dst[m][k] = *(const PG8_LAS bf16x8*)(lds + PG8_SA(b, h) + aoff + m * 2048 + k * 1024); } while (0)
; #define PG8_LDB(dst, b, h) do { _Pragma("unroll") for (int n = 0; n < 2; ++n) _Pragma("unroll") for (int k = 0; k < 2; ++k) dst[n][k] = *(const PG8_LAS bf16x8*)(lds + PG8_SB(b, h) + boff + n * 2048 + k * 1024); } while (0)
; #define PG8_MMA(ai, bj, At, Bt) do { __builtin_amdgcn_s_setprio(1); _Pragma("unroll") for (int m = 0; m < 4; ++m) _Pragma("unroll") for (int n = 0; n < 2; ++n) _Pragma("unroll") for (int k = 0; k < 2; ++k) \
;         acc[ai][bj][m][n] = __builtin_amdgcn_mfma_f32_16x16x32_bf16(Bt[n][k], At[m][k], acc[ai][bj][m][n], 0, 0, 0); __builtin_amdgcn_s_setprio(0); } while (0)
; #define PG8_WAIT_V(n) asm volatile("s_waitcnt vmcnt(" #n ")" ::: "memory")
; #define PG8_WAIT_L(n) asm volatile("s_waitcnt lgkmcnt(" #n ")" ::: "memory")
; #define PG8_BAR __builtin_amdgcn_s_barrier()
; #define PG8_SCHED __builtin_amdgcn_sched_barrier(0)
; template <class Epi, class Sched, bool ALIGN_EPI = false, bool SP2 = false>
; __device__ __forceinline__ void gemm_phase(PG8_LAS unsigned char* lds, const Gemm g, const Sched& S, const Epi& E) {
;     ...
;             PG8_LDB(B0, 0, 0); PG8_LDB(B1, 0, 1); PG8_SCHED; PG8_LDA(At, 0, 0); PG8_STAGE(PG8_SA(1, 1), a1 + hstep, voffA);
;             PG8_WAIT_V(8); PG8_WAIT_L(0); PG8_BAR; PG8_MMA(0, 0, At, B0); PG8_MMA(0, 1, At, B1); PG8_BAR; PG8_SCHED;
;             PG8_LDA(At, 0, 1); PG8_STAGE(PG8_SB(0, 0), b2, voffB); PG8_STAGE(PG8_SB(0, 1), b2 + hstep, voffB); PG8_STAGE(PG8_SA(0, 0), a2, voffA);
;             PG8_WAIT_V(8); PG8_WAIT_L(0); PG8_BAR; PG8_MMA(1, 0, At, B0); PG8_MMA(1, 1, At, B1); PG8_BAR; PG8_SCHED;
.LBB0_817:
	ds_read_b128 v[108:111], v214
	ds_read_b128 v[124:127], v214 offset:1024
	ds_read_b128 v[136:139], v214 offset:2048
	ds_read_b128 v[140:143], v214 offset:3072
	ds_read_b128 v[144:147], v215
	ds_read_b128 v[148:151], v215 offset:1024
	ds_read_b128 v[152:155], v215 offset:2048
	ds_read_b128 v[180:183], v215 offset:3072
	s_add_u32 s4, s46, 0xfffc0080
	s_addc_u32 s5, s47, -1
	s_cmp_eq_u32 s83, 12
	s_cselect_b32 s67, s37, s5
	s_cselect_b32 s66, s45, s4
	s_cselect_b32 s65, s35, s82
	s_cselect_b32 s64, s80, s81
	v_lshl_add_u64 v[222:223], s[46:47], 0, v[172:173]
	s_add_i32 m0, s53, 0xc000
	ds_read_b128 v[184:187], v216
	ds_read_b128 v[188:191], v216 offset:1024
	ds_read_b128 v[192:195], v216 offset:2048
	ds_read_b128 v[196:199], v216 offset:3072
	ds_read_b128 v[200:203], v216 offset:4096
	ds_read_b128 v[204:207], v216 offset:5120
	ds_read_b128 v[208:211], v216 offset:6144
	ds_read_b128 v[218:221], v216 offset:7168
	global_load_lds_dwordx4 v[222:223], off
	v_lshl_add_u64 v[222:223], s[46:47], 0, v[174:175]
	s_add_i32 m0, s53, 0xe000
	s_nop 0
	global_load_lds_dwordx4 v[222:223], off
	s_waitcnt vmcnt(8)
	s_waitcnt lgkmcnt(0)
	s_barrier
	s_setprio 1
	v_mfma_f32_16x16x32_bf16 v[128:131], v[108:111], v[184:187], v[128:131]
	v_mfma_f32_16x16x32_bf16 v[120:123], v[136:139], v[184:187], v[120:123]
	v_mfma_f32_16x16x32_bf16 v[112:115], v[108:111], v[192:195], v[112:115]
	v_mfma_f32_16x16x32_bf16 v[100:103], v[136:139], v[192:195], v[100:103]
	v_mfma_f32_16x16x32_bf16 v[92:95], v[108:111], v[200:203], v[92:95]
	v_mfma_f32_16x16x32_bf16 v[84:87], v[136:139], v[200:203], v[84:87]
	v_mfma_f32_16x16x32_bf16 v[76:79], v[108:111], v[208:211], v[76:79]
	v_mfma_f32_16x16x32_bf16 v[68:71], v[136:139], v[208:211], v[68:71]
	v_mfma_f32_16x16x32_bf16 v[128:131], v[124:127], v[188:191], v[128:131]
	v_mfma_f32_16x16x32_bf16 v[120:123], v[140:143], v[188:191], v[120:123]
	v_mfma_f32_16x16x32_bf16 v[112:115], v[124:127], v[196:199], v[112:115]
	v_mfma_f32_16x16x32_bf16 v[100:103], v[140:143], v[196:199], v[100:103]
	v_mfma_f32_16x16x32_bf16 v[92:95], v[124:127], v[204:207], v[92:95]
	v_mfma_f32_16x16x32_bf16 v[84:87], v[140:143], v[204:207], v[84:87]
	v_mfma_f32_16x16x32_bf16 v[76:79], v[124:127], v[218:221], v[76:79]
	v_mfma_f32_16x16x32_bf16 v[68:71], v[140:143], v[218:221], v[68:71]
	s_setprio 0
	s_setprio 1
	v_mfma_f32_16x16x32_bf16 v[132:135], v[144:147], v[184:187], v[132:135]
	v_mfma_f32_16x16x32_bf16 v[116:119], v[152:155], v[184:187], v[116:119]
	v_mfma_f32_16x16x32_bf16 v[104:107], v[144:147], v[192:195], v[104:107]
	v_mfma_f32_16x16x32_bf16 v[96:99], v[152:155], v[192:195], v[96:99]
	v_mfma_f32_16x16x32_bf16 v[88:91], v[144:147], v[200:203], v[88:91]
	v_mfma_f32_16x16x32_bf16 v[80:83], v[152:155], v[200:203], v[80:83]
	v_mfma_f32_16x16x32_bf16 v[72:75], v[144:147], v[208:211], v[72:75]
	v_mfma_f32_16x16x32_bf16 v[64:67], v[152:155], v[208:211], v[64:67]
	v_mfma_f32_16x16x32_bf16 v[132:135], v[148:151], v[188:191], v[132:135]
	v_mfma_f32_16x16x32_bf16 v[116:119], v[180:183], v[188:191], v[116:119]
	v_mfma_f32_16x16x32_bf16 v[104:107], v[148:151], v[196:199], v[104:107]
	v_mfma_f32_16x16x32_bf16 v[96:99], v[180:183], v[196:199], v[96:99]
	v_mfma_f32_16x16x32_bf16 v[88:91], v[148:151], v[204:207], v[88:91]
	v_mfma_f32_16x16x32_bf16 v[80:83], v[180:183], v[204:207], v[80:83]
	v_mfma_f32_16x16x32_bf16 v[72:75], v[148:151], v[218:221], v[72:75]
	v_mfma_f32_16x16x32_bf16 v[64:67], v[180:183], v[218:221], v[64:67]
	s_setprio 0
	s_barrier
	s_add_i32 s4, s77, s49
	v_lshl_add_u64 v[222:223], s[64:65], 0, v[166:167]
	s_mov_b32 m0, s4
	ds_read_b128 v[184:187], v216 offset:16384
	ds_read_b128 v[188:191], v216 offset:17408
	ds_read_b128 v[192:195], v216 offset:18432
	ds_read_b128 v[196:199], v216 offset:19456
	ds_read_b128 v[200:203], v216 offset:20480
	ds_read_b128 v[204:207], v216 offset:21504
	ds_read_b128 v[208:211], v216 offset:22528
	ds_read_b128 v[218:221], v216 offset:23552
	global_load_lds_dwordx4 v[222:223], off
	s_add_i32 m0, s4, 0x2000
	s_add_u32 s4, s64, 0x40000
	v_lshl_add_u64 v[224:225], s[64:65], 0, v[170:171]
	s_addc_u32 s5, s65, 0
	s_add_i32 s14, s78, s49
	global_load_lds_dwordx4 v[224:225], off
	v_lshl_add_u64 v[226:227], s[4:5], 0, v[166:167]
	s_mov_b32 m0, s14
	v_lshl_add_u64 v[228:229], s[66:67], 0, v[168:169]
	global_load_lds_dwordx4 v[226:227], off
	v_lshl_add_u64 v[226:227], s[4:5], 0, v[170:171]
	s_add_i32 m0, s14, 0x2000
	s_nop 0
	global_load_lds_dwordx4 v[226:227], off
	v_lshl_add_u64 v[226:227], s[66:67], 0, v[164:165]
	s_mov_b32 m0, s53
	s_nop 0
	global_load_lds_dwordx4 v[226:227], off
	s_mov_b32 m0, s68
	s_nop 0
	global_load_lds_dwordx4 v[228:229], off
	s_waitcnt vmcnt(8)
	s_waitcnt lgkmcnt(0)
	s_barrier
; #define PG8_STAGE(bufoff, gbase, voff) do { _Pragma("unroll") for (int _i = 0; _i < 2; ++_i) \
;         __builtin_amdgcn_global_load_lds((const unsigned*)((const char*)(gbase) + (voff)[_i]), (PG8_LAS unsigned*)(lds + (bufoff) + ldsw + _i * 8192), 16, 0, 0); } while (0)
; #define PG8_LDA(dst, b, h) do { _Pragma("unroll") for (int m = 0; m < 4; ++m) _Pragma("unroll") for (int k = 0; k < 2; ++k) dst[m][k] = *(const PG8_LAS bf16x8*)(lds + PG8_SA(b, h) + aoff + m * 2048 + k * 1024); } while (0)
; #define PG8_LDB(dst, b, h) do { _Pragma("unroll") for (int n = 0; n < 2; ++n) _Pragma("unroll") for (int k = 0; k < 2; ++k) dst[n][k] = *(const PG8_LAS bf16x8*)(lds + PG8_SB(b, h) + boff + n * 2048 + k * 1024); } while (0)
; #define PG8_MMA(ai, bj, At, Bt) do { __builtin_amdgcn_s_setprio(1); _Pragma("unroll") for (int m = 0; m < 4; ++m) _Pragma("unroll") for (int n = 0; n < 2; ++n) _Pragma("unroll") for (int k = 0; k < 2; ++k) \
;         acc[ai][bj][m][n] = __builtin_amdgcn_mfma_f32_16x16x32_bf16(Bt[n][k], At[m][k], acc[ai][bj][m][n], 0, 0, 0); __builtin_amdgcn_s_setprio(0); } while (0)
; #define PG8_WAIT_V(n) asm volatile("s_waitcnt vmcnt(" #n ")" ::: "memory")
; #define PG8_WAIT_L(n) asm volatile("s_waitcnt lgkmcnt(" #n ")" ::: "memory")
; #define PG8_BAR __builtin_amdgcn_s_barrier()
; #define PG8_SCHED __builtin_amdgcn_sched_barrier(0)
; template <class Epi, class Sched, bool ALIGN_EPI = false, bool SP2 = false>
; __device__ __forceinline__ void gemm_phase(PG8_LAS unsigned char* lds, const Gemm g, const Sched& S, const Epi& E) {
;     ...
;             PG8_WAIT_V(8); PG8_WAIT_L(0); PG8_BAR; PG8_MMA(1, 0, At, B0); PG8_MMA(1, 1, At, B1); PG8_BAR; PG8_SCHED;
;             PG8_LDB(B0, 1, 0); PG8_LDB(B1, 1, 1); PG8_SCHED; PG8_LDA(At, 1, 0); PG8_STAGE(PG8_SA(0, 1), a2 + hstep, voffA);
;             PG8_WAIT_V(8); PG8_WAIT_L(0); PG8_BAR; PG8_MMA(0, 0, At, B0); PG8_MMA(0, 1, At, B1); PG8_BAR; PG8_SCHED;
	s_setprio 1
	v_mfma_f32_16x16x32_bf16 v[60:63], v[108:111], v[184:187], v[60:63]
	v_mfma_f32_16x16x32_bf16 v[52:55], v[136:139], v[184:187], v[52:55]
	v_mfma_f32_16x16x32_bf16 v[44:47], v[108:111], v[192:195], v[44:47]
	v_mfma_f32_16x16x32_bf16 v[36:39], v[136:139], v[192:195], v[36:39]
	v_mfma_f32_16x16x32_bf16 v[28:31], v[108:111], v[200:203], v[28:31]
	v_mfma_f32_16x16x32_bf16 v[20:23], v[136:139], v[200:203], v[20:23]
	v_mfma_f32_16x16x32_bf16 v[12:15], v[108:111], v[208:211], v[12:15]
	v_mfma_f32_16x16x32_bf16 v[4:7], v[136:139], v[208:211], v[4:7]
	v_mfma_f32_16x16x32_bf16 v[60:63], v[124:127], v[188:191], v[60:63]
	v_mfma_f32_16x16x32_bf16 v[52:55], v[140:143], v[188:191], v[52:55]
	v_mfma_f32_16x16x32_bf16 v[44:47], v[124:127], v[196:199], v[44:47]
	v_mfma_f32_16x16x32_bf16 v[36:39], v[140:143], v[196:199], v[36:39]
	v_mfma_f32_16x16x32_bf16 v[28:31], v[124:127], v[204:207], v[28:31]
	v_mfma_f32_16x16x32_bf16 v[20:23], v[140:143], v[204:207], v[20:23]
	v_mfma_f32_16x16x32_bf16 v[12:15], v[124:127], v[218:221], v[12:15]
	v_mfma_f32_16x16x32_bf16 v[4:7], v[140:143], v[218:221], v[4:7]
	s_setprio 0
	s_setprio 1
	v_mfma_f32_16x16x32_bf16 v[56:59], v[144:147], v[184:187], v[56:59]
	v_mfma_f32_16x16x32_bf16 v[48:51], v[152:155], v[184:187], v[48:51]
	v_mfma_f32_16x16x32_bf16 v[40:43], v[144:147], v[192:195], v[40:43]
	v_mfma_f32_16x16x32_bf16 v[32:35], v[152:155], v[192:195], v[32:35]
	v_mfma_f32_16x16x32_bf16 v[24:27], v[144:147], v[200:203], v[24:27]
	v_mfma_f32_16x16x32_bf16 v[16:19], v[152:155], v[200:203], v[16:19]
	v_mfma_f32_16x16x32_bf16 v[8:11], v[144:147], v[208:211], v[8:11]
	v_mfma_f32_16x16x32_bf16 v[0:3], v[152:155], v[208:211], v[0:3]
	v_mfma_f32_16x16x32_bf16 v[56:59], v[148:151], v[188:191], v[56:59]
	v_mfma_f32_16x16x32_bf16 v[48:51], v[180:183], v[188:191], v[48:51]
	v_mfma_f32_16x16x32_bf16 v[40:43], v[148:151], v[196:199], v[40:43]
	v_mfma_f32_16x16x32_bf16 v[32:35], v[180:183], v[196:199], v[32:35]
	v_mfma_f32_16x16x32_bf16 v[24:27], v[148:151], v[204:207], v[24:27]
	v_mfma_f32_16x16x32_bf16 v[16:19], v[180:183], v[204:207], v[16:19]
	v_mfma_f32_16x16x32_bf16 v[8:11], v[148:151], v[218:221], v[8:11]
	v_mfma_f32_16x16x32_bf16 v[0:3], v[180:183], v[218:221], v[0:3]
	s_setprio 0
	s_barrier
	s_add_i32 s14, 0, 0x18000
	s_add_i32 s15, 0, 0x1c000
	v_add_u32_e32 v140, s14, v159
	v_add_u32_e32 v180, s15, v159
	ds_read_b128 v[108:111], v140
	ds_read_b128 v[124:127], v140 offset:1024
	ds_read_b128 v[136:139], v140 offset:2048
	ds_read_b128 v[140:143], v140 offset:3072
	ds_read_b128 v[144:147], v180
	ds_read_b128 v[148:151], v180 offset:1024
	ds_read_b128 v[152:155], v180 offset:2048
	ds_read_b128 v[180:183], v180 offset:3072
	s_add_u32 s4, s66, 0x40000
	s_addc_u32 s5, s67, 0
	s_mov_b32 m0, s69
	v_lshl_add_u64 v[230:231], s[4:5], 0, v[164:165]
	ds_read_b128 v[184:187], v216 offset:32768
	ds_read_b128 v[188:191], v216 offset:33792
	ds_read_b128 v[192:195], v216 offset:34816
	ds_read_b128 v[196:199], v216 offset:35840
	ds_read_b128 v[200:203], v216 offset:36864
	ds_read_b128 v[204:207], v216 offset:37888
	ds_read_b128 v[208:211], v216 offset:38912
	ds_read_b128 v[218:221], v216 offset:39936
	global_load_lds_dwordx4 v[230:231], off
	v_lshl_add_u64 v[230:231], s[4:5], 0, v[168:169]
	s_mov_b32 m0, s70
	s_nop 0
	global_load_lds_dwordx4 v[230:231], off
	s_waitcnt vmcnt(8)
	s_waitcnt lgkmcnt(0)
	s_barrier
	s_setprio 1
	v_mfma_f32_16x16x32_bf16 v[128:131], v[108:111], v[184:187], v[128:131]
	v_mfma_f32_16x16x32_bf16 v[120:123], v[136:139], v[184:187], v[120:123]
	v_mfma_f32_16x16x32_bf16 v[112:115], v[108:111], v[192:195], v[112:115]
	v_mfma_f32_16x16x32_bf16 v[100:103], v[136:139], v[192:195], v[100:103]
	v_mfma_f32_16x16x32_bf16 v[92:95], v[108:111], v[200:203], v[92:95]
	v_mfma_f32_16x16x32_bf16 v[84:87], v[136:139], v[200:203], v[84:87]
	v_mfma_f32_16x16x32_bf16 v[76:79], v[108:111], v[208:211], v[76:79]
	v_mfma_f32_16x16x32_bf16 v[68:71], v[136:139], v[208:211], v[68:71]
	v_mfma_f32_16x16x32_bf16 v[128:131], v[124:127], v[188:191], v[128:131]
	v_mfma_f32_16x16x32_bf16 v[120:123], v[140:143], v[188:191], v[120:123]
	v_mfma_f32_16x16x32_bf16 v[112:115], v[124:127], v[196:199], v[112:115]
	v_mfma_f32_16x16x32_bf16 v[100:103], v[140:143], v[196:199], v[100:103]
	v_mfma_f32_16x16x32_bf16 v[92:95], v[124:127], v[204:207], v[92:95]
	v_mfma_f32_16x16x32_bf16 v[84:87], v[140:143], v[204:207], v[84:87]
	v_mfma_f32_16x16x32_bf16 v[76:79], v[124:127], v[218:221], v[76:79]
	v_mfma_f32_16x16x32_bf16 v[68:71], v[140:143], v[218:221], v[68:71]
	s_setprio 0
	s_setprio 1
	v_mfma_f32_16x16x32_bf16 v[132:135], v[144:147], v[184:187], v[132:135]
	v_mfma_f32_16x16x32_bf16 v[116:119], v[152:155], v[184:187], v[116:119]
	v_mfma_f32_16x16x32_bf16 v[104:107], v[144:147], v[192:195], v[104:107]
	v_mfma_f32_16x16x32_bf16 v[96:99], v[152:155], v[192:195], v[96:99]
	v_mfma_f32_16x16x32_bf16 v[88:91], v[144:147], v[200:203], v[88:91]
	v_mfma_f32_16x16x32_bf16 v[80:83], v[152:155], v[200:203], v[80:83]
	v_mfma_f32_16x16x32_bf16 v[72:75], v[144:147], v[208:211], v[72:75]
	v_mfma_f32_16x16x32_bf16 v[64:67], v[152:155], v[208:211], v[64:67]
	v_mfma_f32_16x16x32_bf16 v[132:135], v[148:151], v[188:191], v[132:135]
	v_mfma_f32_16x16x32_bf16 v[116:119], v[180:183], v[188:191], v[116:119]
	v_mfma_f32_16x16x32_bf16 v[104:107], v[148:151], v[196:199], v[104:107]
	v_mfma_f32_16x16x32_bf16 v[96:99], v[180:183], v[196:199], v[96:99]
	v_mfma_f32_16x16x32_bf16 v[88:91], v[148:151], v[204:207], v[88:91]
	v_mfma_f32_16x16x32_bf16 v[80:83], v[180:183], v[204:207], v[80:83]
	v_mfma_f32_16x16x32_bf16 v[72:75], v[148:151], v[218:221], v[72:75]
	v_mfma_f32_16x16x32_bf16 v[64:67], v[180:183], v[218:221], v[64:67]
	s_setprio 0
	s_barrier
; #define PG8_STAGE(bufoff, gbase, voff) do { _Pragma("unroll") for (int _i = 0; _i < 2; ++_i) \
;         __builtin_amdgcn_global_load_lds((const unsigned*)((const char*)(gbase) + (voff)[_i]), (PG8_LAS unsigned*)(lds + (bufoff) + ldsw + _i * 8192), 16, 0, 0); } while (0)
; #define PG8_LDA(dst, b, h) do { _Pragma("unroll") for (int m = 0; m < 4; ++m) _Pragma("unroll") for (int k = 0; k < 2; ++k) dst[m][k] = *(const PG8_LAS bf16x8*)(lds + PG8_SA(b, h) + aoff + m * 2048 + k * 1024); } while (0)
; #define PG8_MMA(ai, bj, At, Bt) do { __builtin_amdgcn_s_setprio(1); _Pragma("unroll") for (int m = 0; m < 4; ++m) _Pragma("unroll") for (int n = 0; n < 2; ++n) _Pragma("unroll") for (int k = 0; k < 2; ++k) \
;         acc[ai][bj][m][n] = __builtin_amdgcn_mfma_f32_16x16x32_bf16(Bt[n][k], At[m][k], acc[ai][bj][m][n], 0, 0, 0); __builtin_amdgcn_s_setprio(0); } while (0)
; #define PG8_WAIT_V(n) asm volatile("s_waitcnt vmcnt(" #n ")" ::: "memory")
; #define PG8_WAIT_L(n) asm volatile("s_waitcnt lgkmcnt(" #n ")" ::: "memory")
; #define PG8_BAR __builtin_amdgcn_s_barrier()
; #define PG8_SCHED __builtin_amdgcn_sched_barrier(0)
; template <class Epi, class Sched, bool ALIGN_EPI = false, bool SP2 = false>
; __device__ __forceinline__ void gemm_phase(PG8_LAS unsigned char* lds, const Gemm g, const Sched& S, const Epi& E) {
;     ...
;             PG8_LDA(At, 1, 1); PG8_STAGE(PG8_SB(1, 0), b3, voffB); PG8_STAGE(PG8_SB(1, 1), b3 + hstep, voffB); PG8_STAGE(PG8_SA(1, 0), a3, voffA);
;             PG8_WAIT_V(8); PG8_WAIT_L(0); PG8_BAR; PG8_MMA(1, 0, At, B0); PG8_MMA(1, 1, At, B1); PG8_BAR; PG8_SCHED;
	s_add_i32 s4, s14, s49
	v_lshl_add_u64 v[222:223], v[222:223], 0, s[28:29]
	s_mov_b32 m0, s4
	ds_read_b128 v[184:187], v216 offset:49152
	ds_read_b128 v[188:191], v216 offset:50176
	ds_read_b128 v[192:195], v216 offset:51200
	ds_read_b128 v[196:199], v216 offset:52224
	ds_read_b128 v[200:203], v216 offset:53248
	ds_read_b128 v[204:207], v216 offset:54272
	ds_read_b128 v[208:211], v216 offset:55296
	ds_read_b128 v[218:221], v216 offset:56320
	global_load_lds_dwordx4 v[222:223], off
	s_add_i32 m0, s4, 0x2000
	s_add_u32 s4, s64, 0x40080
	v_lshl_add_u64 v[222:223], v[224:225], 0, s[28:29]
	s_addc_u32 s5, s65, 0
	s_add_i32 s14, s15, s49
	global_load_lds_dwordx4 v[222:223], off
	v_lshl_add_u64 v[222:223], s[4:5], 0, v[166:167]
	s_mov_b32 m0, s14
	s_nop 0
	global_load_lds_dwordx4 v[222:223], off
	v_lshl_add_u64 v[222:223], s[4:5], 0, v[170:171]
	s_add_i32 m0, s14, 0x2000
	s_nop 0
	global_load_lds_dwordx4 v[222:223], off
	v_lshl_add_u64 v[222:223], v[226:227], 0, s[28:29]
	s_mov_b32 m0, s72
	s_nop 0
	global_load_lds_dwordx4 v[222:223], off
	v_lshl_add_u64 v[222:223], v[228:229], 0, s[28:29]
	s_mov_b32 m0, s73
	s_nop 0
	global_load_lds_dwordx4 v[222:223], off
	s_waitcnt vmcnt(8)
	s_waitcnt lgkmcnt(0)
	s_barrier
	s_setprio 1
	v_mfma_f32_16x16x32_bf16 v[60:63], v[108:111], v[184:187], v[60:63]
	v_mfma_f32_16x16x32_bf16 v[52:55], v[136:139], v[184:187], v[52:55]
	v_mfma_f32_16x16x32_bf16 v[44:47], v[108:111], v[192:195], v[44:47]
	v_mfma_f32_16x16x32_bf16 v[36:39], v[136:139], v[192:195], v[36:39]
	v_mfma_f32_16x16x32_bf16 v[28:31], v[108:111], v[200:203], v[28:31]
	v_mfma_f32_16x16x32_bf16 v[20:23], v[136:139], v[200:203], v[20:23]
	v_mfma_f32_16x16x32_bf16 v[12:15], v[108:111], v[208:211], v[12:15]
	v_mfma_f32_16x16x32_bf16 v[4:7], v[136:139], v[208:211], v[4:7]
	v_mfma_f32_16x16x32_bf16 v[60:63], v[124:127], v[188:191], v[60:63]
	v_mfma_f32_16x16x32_bf16 v[52:55], v[140:143], v[188:191], v[52:55]
	v_mfma_f32_16x16x32_bf16 v[44:47], v[124:127], v[196:199], v[44:47]
	v_mfma_f32_16x16x32_bf16 v[36:39], v[140:143], v[196:199], v[36:39]
	v_mfma_f32_16x16x32_bf16 v[28:31], v[124:127], v[204:207], v[28:31]
	v_mfma_f32_16x16x32_bf16 v[20:23], v[140:143], v[204:207], v[20:23]
	v_mfma_f32_16x16x32_bf16 v[12:15], v[124:127], v[218:221], v[12:15]
	v_mfma_f32_16x16x32_bf16 v[4:7], v[140:143], v[218:221], v[4:7]
	s_setprio 0
	s_setprio 1
	v_mfma_f32_16x16x32_bf16 v[56:59], v[144:147], v[184:187], v[56:59]
	v_mfma_f32_16x16x32_bf16 v[48:51], v[152:155], v[184:187], v[48:51]
	v_mfma_f32_16x16x32_bf16 v[40:43], v[144:147], v[192:195], v[40:43]
	v_mfma_f32_16x16x32_bf16 v[32:35], v[152:155], v[192:195], v[32:35]
	v_mfma_f32_16x16x32_bf16 v[24:27], v[144:147], v[200:203], v[24:27]
	v_mfma_f32_16x16x32_bf16 v[16:19], v[152:155], v[200:203], v[16:19]
	v_mfma_f32_16x16x32_bf16 v[8:11], v[144:147], v[208:211], v[8:11]
	v_mfma_f32_16x16x32_bf16 v[0:3], v[152:155], v[208:211], v[0:3]
	v_mfma_f32_16x16x32_bf16 v[56:59], v[148:151], v[188:191], v[56:59]
	v_mfma_f32_16x16x32_bf16 v[48:51], v[180:183], v[188:191], v[48:51]
	v_mfma_f32_16x16x32_bf16 v[40:43], v[148:151], v[196:199], v[40:43]
	v_mfma_f32_16x16x32_bf16 v[32:35], v[180:183], v[196:199], v[32:35]
	v_mfma_f32_16x16x32_bf16 v[24:27], v[148:151], v[204:207], v[24:27]
	v_mfma_f32_16x16x32_bf16 v[16:19], v[180:183], v[204:207], v[16:19]
	v_mfma_f32_16x16x32_bf16 v[8:11], v[148:151], v[218:221], v[8:11]
	v_mfma_f32_16x16x32_bf16 v[0:3], v[180:183], v[218:221], v[0:3]
	s_setprio 0
	s_barrier
	s_add_i32 s83, s83, 2
	s_add_u32 s46, s46, 0x100
	s_addc_u32 s47, s47, 0
	s_add_u32 s81, s81, 0x100
	s_addc_u32 s82, s82, 0
	s_cmp_gt_u32 s83, 13
	s_cbranch_scc0 .LBB0_817
	s_and_b64 vcc, exec, s[30:31]
	s_cbranch_vccz .LBB0_820
	s_barrier

; #define PG8_STAGE(bufoff, gbase, voff) do { _Pragma("unroll") for (int _i = 0; _i < 2; ++_i) \
;         __builtin_amdgcn_global_load_lds((const unsigned*)((const char*)(gbase) + (voff)[_i]), (PG8_LAS unsigned*)(lds + (bufoff) + ldsw + _i * 8192), 16, 0, 0); } while (0)
; #define PG8_LDA(dst, b, h) do { _Pragma("unroll") for (int m = 0; m < 4; ++m) _Pragma("unroll") for (int k = 0; k < 2; ++k) dst[m][k] = *(const PG8_LAS bf16x8*)(lds + PG8_SA(b, h) + aoff + m * 2048 + k * 1024); } while (0)
; #define PG8_LDB(dst, b, h) do { _Pragma("unroll") for (int n = 0; n < 2; ++n) _Pragma("unroll") for (int k = 0; k < 2; ++k) dst[n][k] = *(const PG8_LAS bf16x8*)(lds + PG8_SB(b, h) + boff + n * 2048 + k * 1024); } while (0)
; #define PG8_MMA(ai, bj, At, Bt) do { __builtin_amdgcn_s_setprio(1); _Pragma("unroll") for (int m = 0; m < 4; ++m) _Pragma("unroll") for (int n = 0; n < 2; ++n) _Pragma("unroll") for (int k = 0; k < 2; ++k) \
;         acc[ai][bj][m][n] = __builtin_amdgcn_mfma_f32_16x16x32_bf16(Bt[n][k], At[m][k], acc[ai][bj][m][n], 0, 0, 0); __builtin_amdgcn_s_setprio(0); } while (0)
; #define PG8_WAIT_V(n) asm volatile("s_waitcnt vmcnt(" #n ")" ::: "memory")
; #define PG8_WAIT_L(n) asm volatile("s_waitcnt lgkmcnt(" #n ")" ::: "memory")
; #define PG8_BAR __builtin_amdgcn_s_barrier()
; #define PG8_SCHED __builtin_amdgcn_sched_barrier(0)
; template <class Epi, class Sched, bool ALIGN_EPI = false, bool SP2 = false>
; __device__ __forceinline__ void gemm_phase(PG8_LAS unsigned char* lds, const Gemm g, const Sched& S, const Epi& E) {
;     ...
;             PG8_LDB(B0, 0, 0); PG8_LDB(B1, 0, 1); PG8_SCHED; PG8_LDA(At, 0, 0); PG8_STAGE(PG8_SA(1, 1), a1 + hstep, voffA);
;             PG8_WAIT_V(8); PG8_WAIT_L(0); PG8_BAR; PG8_MMA(0, 0, At, B0); PG8_MMA(0, 1, At, B1); PG8_BAR; PG8_SCHED;
;             PG8_LDA(At, 0, 1); PG8_STAGE(PG8_SB(0, 0), b2, voffB); PG8_STAGE(PG8_SB(0, 1), b2 + hstep, voffB); PG8_STAGE(PG8_SA(0, 0), a2, voffA);
;             PG8_WAIT_V(8); PG8_WAIT_L(0); PG8_BAR; PG8_MMA(1, 0, At, B0); PG8_MMA(1, 1, At, B1); PG8_BAR; PG8_SCHED;
.LBB0_910:
	ds_read_b128 v[146:149], v159
	ds_read_b128 v[150:153], v159 offset:1024
	ds_read_b128 v[164:167], v159 offset:2048
	ds_read_b128 v[168:171], v159 offset:3072
	ds_read_b128 v[172:175], v160
	ds_read_b128 v[176:179], v160 offset:1024
	ds_read_b128 v[180:183], v160 offset:2048
	ds_read_b128 v[184:187], v160 offset:3072
	s_add_u32 s28, s26, 0xfffc0080
	s_addc_u32 s29, s27, -1
	s_cmp_eq_u32 s70, 12
	s_cselect_b32 s31, s19, s29
	s_cselect_b32 s30, s66, s28
	s_cselect_b32 s29, s11, s69
	s_cselect_b32 s28, s67, s68
	v_lshl_add_u64 v[222:223], s[26:27], 0, v[138:139]
	s_add_i32 m0, s25, 0xc000
	ds_read_b128 v[188:191], v161
	ds_read_b128 v[192:195], v161 offset:1024
	ds_read_b128 v[196:199], v161 offset:2048
	ds_read_b128 v[200:203], v161 offset:3072
	ds_read_b128 v[204:207], v161 offset:4096
	ds_read_b128 v[208:211], v161 offset:5120
	ds_read_b128 v[214:217], v161 offset:6144
	ds_read_b128 v[218:221], v161 offset:7168
	global_load_lds_dwordx4 v[222:223], off
	v_lshl_add_u64 v[222:223], s[26:27], 0, v[140:141]
	s_add_i32 m0, s25, 0xe000
	s_nop 0
	global_load_lds_dwordx4 v[222:223], off
	s_waitcnt vmcnt(8)
	s_waitcnt lgkmcnt(0)
	s_barrier
	s_setprio 1
	v_mfma_f32_16x16x32_bf16 v[124:127], v[146:149], v[188:191], v[124:127]
	v_mfma_f32_16x16x32_bf16 v[116:119], v[164:167], v[188:191], v[116:119]
	v_mfma_f32_16x16x32_bf16 v[108:111], v[146:149], v[196:199], v[108:111]
	v_mfma_f32_16x16x32_bf16 v[100:103], v[164:167], v[196:199], v[100:103]
	v_mfma_f32_16x16x32_bf16 v[92:95], v[146:149], v[204:207], v[92:95]
	v_mfma_f32_16x16x32_bf16 v[84:87], v[164:167], v[204:207], v[84:87]
	v_mfma_f32_16x16x32_bf16 v[76:79], v[146:149], v[214:217], v[76:79]
	v_mfma_f32_16x16x32_bf16 v[68:71], v[164:167], v[214:217], v[68:71]
	v_mfma_f32_16x16x32_bf16 v[124:127], v[150:153], v[192:195], v[124:127]
	v_mfma_f32_16x16x32_bf16 v[116:119], v[168:171], v[192:195], v[116:119]
	v_mfma_f32_16x16x32_bf16 v[108:111], v[150:153], v[200:203], v[108:111]
	v_mfma_f32_16x16x32_bf16 v[100:103], v[168:171], v[200:203], v[100:103]
	v_mfma_f32_16x16x32_bf16 v[92:95], v[150:153], v[208:211], v[92:95]
	v_mfma_f32_16x16x32_bf16 v[84:87], v[168:171], v[208:211], v[84:87]
	v_mfma_f32_16x16x32_bf16 v[76:79], v[150:153], v[218:221], v[76:79]
	v_mfma_f32_16x16x32_bf16 v[68:71], v[168:171], v[218:221], v[68:71]
	s_setprio 0
	s_setprio 1
	v_mfma_f32_16x16x32_bf16 v[120:123], v[172:175], v[188:191], v[120:123]
	v_mfma_f32_16x16x32_bf16 v[112:115], v[180:183], v[188:191], v[112:115]
	v_mfma_f32_16x16x32_bf16 v[104:107], v[172:175], v[196:199], v[104:107]
	v_mfma_f32_16x16x32_bf16 v[96:99], v[180:183], v[196:199], v[96:99]
	v_mfma_f32_16x16x32_bf16 v[88:91], v[172:175], v[204:207], v[88:91]
	v_mfma_f32_16x16x32_bf16 v[80:83], v[180:183], v[204:207], v[80:83]
	v_mfma_f32_16x16x32_bf16 v[72:75], v[172:175], v[214:217], v[72:75]
	v_mfma_f32_16x16x32_bf16 v[64:67], v[180:183], v[214:217], v[64:67]
	v_mfma_f32_16x16x32_bf16 v[120:123], v[176:179], v[192:195], v[120:123]
	v_mfma_f32_16x16x32_bf16 v[112:115], v[184:187], v[192:195], v[112:115]
	v_mfma_f32_16x16x32_bf16 v[104:107], v[176:179], v[200:203], v[104:107]
	v_mfma_f32_16x16x32_bf16 v[96:99], v[184:187], v[200:203], v[96:99]
	v_mfma_f32_16x16x32_bf16 v[88:91], v[176:179], v[208:211], v[88:91]
	v_mfma_f32_16x16x32_bf16 v[80:83], v[184:187], v[208:211], v[80:83]
	v_mfma_f32_16x16x32_bf16 v[72:75], v[176:179], v[218:221], v[72:75]
	v_mfma_f32_16x16x32_bf16 v[64:67], v[184:187], v[218:221], v[64:67]
	s_setprio 0
	s_barrier
	s_add_i32 s71, s49, s35
	v_lshl_add_u64 v[222:223], s[28:29], 0, v[132:133]
	s_mov_b32 m0, s71
	ds_read_b128 v[188:191], v161 offset:16384
	ds_read_b128 v[192:195], v161 offset:17408
	ds_read_b128 v[196:199], v161 offset:18432
	ds_read_b128 v[200:203], v161 offset:19456
	ds_read_b128 v[204:207], v161 offset:20480
	ds_read_b128 v[208:211], v161 offset:21504
	ds_read_b128 v[214:217], v161 offset:22528
	ds_read_b128 v[218:221], v161 offset:23552
	global_load_lds_dwordx4 v[222:223], off
	s_add_i32 m0, s71, 0x2000
	s_add_u32 s72, s28, 0x40000
	v_lshl_add_u64 v[224:225], s[28:29], 0, v[128:129]
	s_addc_u32 s73, s29, 0
	s_add_i32 s71, s53, s35
	global_load_lds_dwordx4 v[224:225], off
	v_lshl_add_u64 v[226:227], s[72:73], 0, v[132:133]
	s_mov_b32 m0, s71
	v_lshl_add_u64 v[228:229], s[30:31], 0, v[130:131]
	global_load_lds_dwordx4 v[226:227], off
	v_lshl_add_u64 v[226:227], s[72:73], 0, v[128:129]
	s_add_i32 m0, s71, 0x2000
	s_nop 0
	global_load_lds_dwordx4 v[226:227], off
	v_lshl_add_u64 v[226:227], s[30:31], 0, v[134:135]
	s_mov_b32 m0, s25
	s_nop 0
	global_load_lds_dwordx4 v[226:227], off
	s_mov_b32 m0, s38
	s_nop 0
	global_load_lds_dwordx4 v[228:229], off
	s_waitcnt vmcnt(8)
	s_waitcnt lgkmcnt(0)
	s_barrier
; #define PG8_STAGE(bufoff, gbase, voff) do { _Pragma("unroll") for (int _i = 0; _i < 2; ++_i) \
;         __builtin_amdgcn_global_load_lds((const unsigned*)((const char*)(gbase) + (voff)[_i]), (PG8_LAS unsigned*)(lds + (bufoff) + ldsw + _i * 8192), 16, 0, 0); } while (0)
; #define PG8_LDA(dst, b, h) do { _Pragma("unroll") for (int m = 0; m < 4; ++m) _Pragma("unroll") for (int k = 0; k < 2; ++k) dst[m][k] = *(const PG8_LAS bf16x8*)(lds + PG8_SA(b, h) + aoff + m * 2048 + k * 1024); } while (0)
; #define PG8_LDB(dst, b, h) do { _Pragma("unroll") for (int n = 0; n < 2; ++n) _Pragma("unroll") for (int k = 0; k < 2; ++k) dst[n][k] = *(const PG8_LAS bf16x8*)(lds + PG8_SB(b, h) + boff + n * 2048 + k * 1024); } while (0)
; #define PG8_MMA(ai, bj, At, Bt) do { __builtin_amdgcn_s_setprio(1); _Pragma("unroll") for (int m = 0; m < 4; ++m) _Pragma("unroll") for (int n = 0; n < 2; ++n) _Pragma("unroll") for (int k = 0; k < 2; ++k) \
;         acc[ai][bj][m][n] = __builtin_amdgcn_mfma_f32_16x16x32_bf16(Bt[n][k], At[m][k], acc[ai][bj][m][n], 0, 0, 0); __builtin_amdgcn_s_setprio(0); } while (0)
; #define PG8_WAIT_V(n) asm volatile("s_waitcnt vmcnt(" #n ")" ::: "memory")
; #define PG8_WAIT_L(n) asm volatile("s_waitcnt lgkmcnt(" #n ")" ::: "memory")
; #define PG8_BAR __builtin_amdgcn_s_barrier()
; #define PG8_SCHED __builtin_amdgcn_sched_barrier(0)
; template <class Epi, class Sched, bool ALIGN_EPI = false, bool SP2 = false>
; __device__ __forceinline__ void gemm_phase(PG8_LAS unsigned char* lds, const Gemm g, const Sched& S, const Epi& E) {
;     ...
;             PG8_WAIT_V(8); PG8_WAIT_L(0); PG8_BAR; PG8_MMA(1, 0, At, B0); PG8_MMA(1, 1, At, B1); PG8_BAR; PG8_SCHED;
;             PG8_LDB(B0, 1, 0); PG8_LDB(B1, 1, 1); PG8_SCHED; PG8_LDA(At, 1, 0); PG8_STAGE(PG8_SA(0, 1), a2 + hstep, voffA);
;             PG8_WAIT_V(8); PG8_WAIT_L(0); PG8_BAR; PG8_MMA(0, 0, At, B0); PG8_MMA(0, 1, At, B1); PG8_BAR; PG8_SCHED;
	s_setprio 1
	v_mfma_f32_16x16x32_bf16 v[60:63], v[146:149], v[188:191], v[60:63]
	v_mfma_f32_16x16x32_bf16 v[52:55], v[164:167], v[188:191], v[52:55]
	v_mfma_f32_16x16x32_bf16 v[44:47], v[146:149], v[196:199], v[44:47]
	v_mfma_f32_16x16x32_bf16 v[36:39], v[164:167], v[196:199], v[36:39]
	v_mfma_f32_16x16x32_bf16 v[28:31], v[146:149], v[204:207], v[28:31]
	v_mfma_f32_16x16x32_bf16 v[20:23], v[164:167], v[204:207], v[20:23]
	v_mfma_f32_16x16x32_bf16 v[12:15], v[146:149], v[214:217], v[12:15]
	v_mfma_f32_16x16x32_bf16 v[4:7], v[164:167], v[214:217], v[4:7]
	v_mfma_f32_16x16x32_bf16 v[60:63], v[150:153], v[192:195], v[60:63]
	v_mfma_f32_16x16x32_bf16 v[52:55], v[168:171], v[192:195], v[52:55]
	v_mfma_f32_16x16x32_bf16 v[44:47], v[150:153], v[200:203], v[44:47]
	v_mfma_f32_16x16x32_bf16 v[36:39], v[168:171], v[200:203], v[36:39]
	v_mfma_f32_16x16x32_bf16 v[28:31], v[150:153], v[208:211], v[28:31]
	v_mfma_f32_16x16x32_bf16 v[20:23], v[168:171], v[208:211], v[20:23]
	v_mfma_f32_16x16x32_bf16 v[12:15], v[150:153], v[218:221], v[12:15]
	v_mfma_f32_16x16x32_bf16 v[4:7], v[168:171], v[218:221], v[4:7]
	s_setprio 0
	s_setprio 1
	v_mfma_f32_16x16x32_bf16 v[56:59], v[172:175], v[188:191], v[56:59]
	v_mfma_f32_16x16x32_bf16 v[48:51], v[180:183], v[188:191], v[48:51]
	v_mfma_f32_16x16x32_bf16 v[40:43], v[172:175], v[196:199], v[40:43]
	v_mfma_f32_16x16x32_bf16 v[32:35], v[180:183], v[196:199], v[32:35]
	v_mfma_f32_16x16x32_bf16 v[24:27], v[172:175], v[204:207], v[24:27]
	v_mfma_f32_16x16x32_bf16 v[16:19], v[180:183], v[204:207], v[16:19]
	v_mfma_f32_16x16x32_bf16 v[8:11], v[172:175], v[214:217], v[8:11]
	v_mfma_f32_16x16x32_bf16 v[0:3], v[180:183], v[214:217], v[0:3]
	v_mfma_f32_16x16x32_bf16 v[56:59], v[176:179], v[192:195], v[56:59]
	v_mfma_f32_16x16x32_bf16 v[48:51], v[184:187], v[192:195], v[48:51]
	v_mfma_f32_16x16x32_bf16 v[40:43], v[176:179], v[200:203], v[40:43]
	v_mfma_f32_16x16x32_bf16 v[32:35], v[184:187], v[200:203], v[32:35]
	v_mfma_f32_16x16x32_bf16 v[24:27], v[176:179], v[208:211], v[24:27]
	v_mfma_f32_16x16x32_bf16 v[16:19], v[184:187], v[208:211], v[16:19]
	v_mfma_f32_16x16x32_bf16 v[8:11], v[176:179], v[218:221], v[8:11]
	v_mfma_f32_16x16x32_bf16 v[0:3], v[184:187], v[218:221], v[0:3]
	s_setprio 0
	s_barrier
	s_add_i32 s71, 0, 0x18000
	s_add_i32 s72, 0, 0x1c000
	v_add_u32_e32 v168, s71, v155
	v_add_u32_e32 v184, s72, v155
	ds_read_b128 v[146:149], v168
	ds_read_b128 v[150:153], v168 offset:1024
	ds_read_b128 v[164:167], v168 offset:2048
	ds_read_b128 v[168:171], v168 offset:3072
	ds_read_b128 v[172:175], v184
	ds_read_b128 v[176:179], v184 offset:1024
	ds_read_b128 v[180:183], v184 offset:2048
	ds_read_b128 v[184:187], v184 offset:3072
	s_add_u32 s30, s30, 0x40000
	s_addc_u32 s31, s31, 0
	s_mov_b32 m0, s39
	v_lshl_add_u64 v[230:231], s[30:31], 0, v[134:135]
	ds_read_b128 v[188:191], v161 offset:32768
	ds_read_b128 v[192:195], v161 offset:33792
	ds_read_b128 v[196:199], v161 offset:34816
	ds_read_b128 v[200:203], v161 offset:35840
	ds_read_b128 v[204:207], v161 offset:36864
	ds_read_b128 v[208:211], v161 offset:37888
	ds_read_b128 v[214:217], v161 offset:38912
	ds_read_b128 v[218:221], v161 offset:39936
	global_load_lds_dwordx4 v[230:231], off
	v_lshl_add_u64 v[230:231], s[30:31], 0, v[130:131]
	s_mov_b32 m0, s40
	s_nop 0
	global_load_lds_dwordx4 v[230:231], off
	s_waitcnt vmcnt(8)
	s_waitcnt lgkmcnt(0)
	s_barrier
	s_setprio 1
	v_mfma_f32_16x16x32_bf16 v[124:127], v[146:149], v[188:191], v[124:127]
	v_mfma_f32_16x16x32_bf16 v[116:119], v[164:167], v[188:191], v[116:119]
	v_mfma_f32_16x16x32_bf16 v[108:111], v[146:149], v[196:199], v[108:111]
	v_mfma_f32_16x16x32_bf16 v[100:103], v[164:167], v[196:199], v[100:103]
	v_mfma_f32_16x16x32_bf16 v[92:95], v[146:149], v[204:207], v[92:95]
	v_mfma_f32_16x16x32_bf16 v[84:87], v[164:167], v[204:207], v[84:87]
	v_mfma_f32_16x16x32_bf16 v[76:79], v[146:149], v[214:217], v[76:79]
	v_mfma_f32_16x16x32_bf16 v[68:71], v[164:167], v[214:217], v[68:71]
	v_mfma_f32_16x16x32_bf16 v[124:127], v[150:153], v[192:195], v[124:127]
	v_mfma_f32_16x16x32_bf16 v[116:119], v[168:171], v[192:195], v[116:119]
	v_mfma_f32_16x16x32_bf16 v[108:111], v[150:153], v[200:203], v[108:111]
	v_mfma_f32_16x16x32_bf16 v[100:103], v[168:171], v[200:203], v[100:103]
	v_mfma_f32_16x16x32_bf16 v[92:95], v[150:153], v[208:211], v[92:95]
	v_mfma_f32_16x16x32_bf16 v[84:87], v[168:171], v[208:211], v[84:87]
	v_mfma_f32_16x16x32_bf16 v[76:79], v[150:153], v[218:221], v[76:79]
	v_mfma_f32_16x16x32_bf16 v[68:71], v[168:171], v[218:221], v[68:71]
	s_setprio 0
	s_setprio 1
	v_mfma_f32_16x16x32_bf16 v[120:123], v[172:175], v[188:191], v[120:123]
	v_mfma_f32_16x16x32_bf16 v[112:115], v[180:183], v[188:191], v[112:115]
	v_mfma_f32_16x16x32_bf16 v[104:107], v[172:175], v[196:199], v[104:107]
	v_mfma_f32_16x16x32_bf16 v[96:99], v[180:183], v[196:199], v[96:99]
	v_mfma_f32_16x16x32_bf16 v[88:91], v[172:175], v[204:207], v[88:91]
	v_mfma_f32_16x16x32_bf16 v[80:83], v[180:183], v[204:207], v[80:83]
	v_mfma_f32_16x16x32_bf16 v[72:75], v[172:175], v[214:217], v[72:75]
	v_mfma_f32_16x16x32_bf16 v[64:67], v[180:183], v[214:217], v[64:67]
	v_mfma_f32_16x16x32_bf16 v[120:123], v[176:179], v[192:195], v[120:123]
	v_mfma_f32_16x16x32_bf16 v[112:115], v[184:187], v[192:195], v[112:115]
	v_mfma_f32_16x16x32_bf16 v[104:107], v[176:179], v[200:203], v[104:107]
	v_mfma_f32_16x16x32_bf16 v[96:99], v[184:187], v[200:203], v[96:99]
	v_mfma_f32_16x16x32_bf16 v[88:91], v[176:179], v[208:211], v[88:91]
	v_mfma_f32_16x16x32_bf16 v[80:83], v[184:187], v[208:211], v[80:83]
	v_mfma_f32_16x16x32_bf16 v[72:75], v[176:179], v[218:221], v[72:75]
	v_mfma_f32_16x16x32_bf16 v[64:67], v[184:187], v[218:221], v[64:67]
	s_setprio 0
	s_barrier
; #define PG8_STAGE(bufoff, gbase, voff) do { _Pragma("unroll") for (int _i = 0; _i < 2; ++_i) \
;         __builtin_amdgcn_global_load_lds((const unsigned*)((const char*)(gbase) + (voff)[_i]), (PG8_LAS unsigned*)(lds + (bufoff) + ldsw + _i * 8192), 16, 0, 0); } while (0)
; #define PG8_LDA(dst, b, h) do { _Pragma("unroll") for (int m = 0; m < 4; ++m) _Pragma("unroll") for (int k = 0; k < 2; ++k) dst[m][k] = *(const PG8_LAS bf16x8*)(lds + PG8_SA(b, h) + aoff + m * 2048 + k * 1024); } while (0)
; #define PG8_MMA(ai, bj, At, Bt) do { __builtin_amdgcn_s_setprio(1); _Pragma("unroll") for (int m = 0; m < 4; ++m) _Pragma("unroll") for (int n = 0; n < 2; ++n) _Pragma("unroll") for (int k = 0; k < 2; ++k) \
;         acc[ai][bj][m][n] = __builtin_amdgcn_mfma_f32_16x16x32_bf16(Bt[n][k], At[m][k], acc[ai][bj][m][n], 0, 0, 0); __builtin_amdgcn_s_setprio(0); } while (0)
; #define PG8_WAIT_V(n) asm volatile("s_waitcnt vmcnt(" #n ")" ::: "memory")
; #define PG8_WAIT_L(n) asm volatile("s_waitcnt lgkmcnt(" #n ")" ::: "memory")
; #define PG8_BAR __builtin_amdgcn_s_barrier()
; #define PG8_SCHED __builtin_amdgcn_sched_barrier(0)
; template <class Epi, class Sched, bool ALIGN_EPI = false, bool SP2 = false>
; __device__ __forceinline__ void gemm_phase(PG8_LAS unsigned char* lds, const Gemm g, const Sched& S, const Epi& E) {
;     ...
;             PG8_LDA(At, 1, 1); PG8_STAGE(PG8_SB(1, 0), b3, voffB); PG8_STAGE(PG8_SB(1, 1), b3 + hstep, voffB); PG8_STAGE(PG8_SA(1, 0), a3, voffA);
;             PG8_WAIT_V(8); PG8_WAIT_L(0); PG8_BAR; PG8_MMA(1, 0, At, B0); PG8_MMA(1, 1, At, B1); PG8_BAR; PG8_SCHED;
;     ...
;         if constexpr (ALIGN_EPI) { if (wr == 0) PG8_BAR; }
	s_add_i32 s30, s71, s35
	v_lshl_add_u64 v[222:223], v[222:223], 0, s[8:9]
	s_mov_b32 m0, s30
	ds_read_b128 v[188:191], v161 offset:49152
	ds_read_b128 v[192:195], v161 offset:50176
	ds_read_b128 v[196:199], v161 offset:51200
	ds_read_b128 v[200:203], v161 offset:52224
	ds_read_b128 v[204:207], v161 offset:53248
	ds_read_b128 v[208:211], v161 offset:54272
	ds_read_b128 v[214:217], v161 offset:55296
	ds_read_b128 v[218:221], v161 offset:56320
	global_load_lds_dwordx4 v[222:223], off
	s_add_i32 m0, s30, 0x2000
	s_add_u32 s28, s28, 0x40080
	v_lshl_add_u64 v[222:223], v[224:225], 0, s[8:9]
	s_addc_u32 s29, s29, 0
	s_add_i32 s30, s72, s35
	global_load_lds_dwordx4 v[222:223], off
	v_lshl_add_u64 v[222:223], s[28:29], 0, v[132:133]
	s_mov_b32 m0, s30
	s_nop 0
	global_load_lds_dwordx4 v[222:223], off
	v_lshl_add_u64 v[222:223], s[28:29], 0, v[128:129]
	s_add_i32 m0, s30, 0x2000
	s_nop 0
	global_load_lds_dwordx4 v[222:223], off
	v_lshl_add_u64 v[222:223], v[226:227], 0, s[8:9]
	s_mov_b32 m0, s44
	s_nop 0
	global_load_lds_dwordx4 v[222:223], off
	v_lshl_add_u64 v[222:223], v[228:229], 0, s[8:9]
	s_mov_b32 m0, s45
	s_nop 0
	global_load_lds_dwordx4 v[222:223], off
	s_waitcnt vmcnt(8)
	s_waitcnt lgkmcnt(0)
	s_barrier
	s_setprio 1
	v_mfma_f32_16x16x32_bf16 v[60:63], v[146:149], v[188:191], v[60:63]
	v_mfma_f32_16x16x32_bf16 v[52:55], v[164:167], v[188:191], v[52:55]
	v_mfma_f32_16x16x32_bf16 v[44:47], v[146:149], v[196:199], v[44:47]
	v_mfma_f32_16x16x32_bf16 v[36:39], v[164:167], v[196:199], v[36:39]
	v_mfma_f32_16x16x32_bf16 v[28:31], v[146:149], v[204:207], v[28:31]
	v_mfma_f32_16x16x32_bf16 v[20:23], v[164:167], v[204:207], v[20:23]
	v_mfma_f32_16x16x32_bf16 v[12:15], v[146:149], v[214:217], v[12:15]
	v_mfma_f32_16x16x32_bf16 v[4:7], v[164:167], v[214:217], v[4:7]
	v_mfma_f32_16x16x32_bf16 v[60:63], v[150:153], v[192:195], v[60:63]
	v_mfma_f32_16x16x32_bf16 v[52:55], v[168:171], v[192:195], v[52:55]
	v_mfma_f32_16x16x32_bf16 v[44:47], v[150:153], v[200:203], v[44:47]
	v_mfma_f32_16x16x32_bf16 v[36:39], v[168:171], v[200:203], v[36:39]
	v_mfma_f32_16x16x32_bf16 v[28:31], v[150:153], v[208:211], v[28:31]
	v_mfma_f32_16x16x32_bf16 v[20:23], v[168:171], v[208:211], v[20:23]
	v_mfma_f32_16x16x32_bf16 v[12:15], v[150:153], v[218:221], v[12:15]
	v_mfma_f32_16x16x32_bf16 v[4:7], v[168:171], v[218:221], v[4:7]
	s_setprio 0
	s_setprio 1
	v_mfma_f32_16x16x32_bf16 v[56:59], v[172:175], v[188:191], v[56:59]
	v_mfma_f32_16x16x32_bf16 v[48:51], v[180:183], v[188:191], v[48:51]
	v_mfma_f32_16x16x32_bf16 v[40:43], v[172:175], v[196:199], v[40:43]
	v_mfma_f32_16x16x32_bf16 v[32:35], v[180:183], v[196:199], v[32:35]
	v_mfma_f32_16x16x32_bf16 v[24:27], v[172:175], v[204:207], v[24:27]
	v_mfma_f32_16x16x32_bf16 v[16:19], v[180:183], v[204:207], v[16:19]
	v_mfma_f32_16x16x32_bf16 v[8:11], v[172:175], v[214:217], v[8:11]
	v_mfma_f32_16x16x32_bf16 v[0:3], v[180:183], v[214:217], v[0:3]
	v_mfma_f32_16x16x32_bf16 v[56:59], v[176:179], v[192:195], v[56:59]
	v_mfma_f32_16x16x32_bf16 v[48:51], v[184:187], v[192:195], v[48:51]
	v_mfma_f32_16x16x32_bf16 v[40:43], v[176:179], v[200:203], v[40:43]
	v_mfma_f32_16x16x32_bf16 v[32:35], v[184:187], v[200:203], v[32:35]
	v_mfma_f32_16x16x32_bf16 v[24:27], v[176:179], v[208:211], v[24:27]
	v_mfma_f32_16x16x32_bf16 v[16:19], v[184:187], v[208:211], v[16:19]
	v_mfma_f32_16x16x32_bf16 v[8:11], v[176:179], v[218:221], v[8:11]
	v_mfma_f32_16x16x32_bf16 v[0:3], v[184:187], v[218:221], v[0:3]
	s_setprio 0
	s_barrier
	s_add_i32 s70, s70, 2
	s_add_u32 s26, s26, 0x100
	s_addc_u32 s27, s27, 0
	s_add_u32 s68, s68, 0x100
	s_addc_u32 s69, s69, 0
	s_cmp_gt_u32 s70, 13
	s_cbranch_scc0 .LBB0_910
	s_and_b64 vcc, exec, s[14:15]
	s_cbranch_vccz .LBB0_913
	s_barrier

; #define PG8_STAGE(bufoff, gbase, voff) do { _Pragma("unroll") for (int _i = 0; _i < 2; ++_i) \
;         __builtin_amdgcn_global_load_lds((const unsigned*)((const char*)(gbase) + (voff)[_i]), (PG8_LAS unsigned*)(lds + (bufoff) + ldsw + _i * 8192), 16, 0, 0); } while (0)
; #define PG8_LDA(dst, b, h) do { _Pragma("unroll") for (int m = 0; m < 4; ++m) _Pragma("unroll") for (int k = 0; k < 2; ++k) dst[m][k] = *(const PG8_LAS bf16x8*)(lds + PG8_SA(b, h) + aoff + m * 2048 + k * 1024); } while (0)
; #define PG8_LDB(dst, b, h) do { _Pragma("unroll") for (int n = 0; n < 2; ++n) _Pragma("unroll") for (int k = 0; k < 2; ++k) dst[n][k] = *(const PG8_LAS bf16x8*)(lds + PG8_SB(b, h) + boff + n * 2048 + k * 1024); } while (0)
; #define PG8_MMA(ai, bj, At, Bt) do { __builtin_amdgcn_s_setprio(1); _Pragma("unroll") for (int m = 0; m < 4; ++m) _Pragma("unroll") for (int n = 0; n < 2; ++n) _Pragma("unroll") for (int k = 0; k < 2; ++k) \
;         acc[ai][bj][m][n] = __builtin_amdgcn_mfma_f32_16x16x32_bf16(Bt[n][k], At[m][k], acc[ai][bj][m][n], 0, 0, 0); __builtin_amdgcn_s_setprio(0); } while (0)
; #define PG8_WAIT_V(n) asm volatile("s_waitcnt vmcnt(" #n ")" ::: "memory")
; #define PG8_WAIT_L(n) asm volatile("s_waitcnt lgkmcnt(" #n ")" ::: "memory")
; #define PG8_BAR __builtin_amdgcn_s_barrier()
; #define PG8_SCHED __builtin_amdgcn_sched_barrier(0)
; template <class Epi, class Sched, bool ALIGN_EPI = false, bool SP2 = false>
; __device__ __forceinline__ void gemm_phase(PG8_LAS unsigned char* lds, const Gemm g, const Sched& S, const Epi& E) {
;     ...
;             const char* a1 = cA + (size_t)(t + 1) * kstep;
;             const char* a2 = last ? nA : cA + (size_t)(t + 2) * kstep; const char* b2 = last ? nB : cB + (size_t)(t + 2) * kstep;
;             const char* a3 = a2 + kstep; const char* b3 = b2 + kstep;
;             if (last && has_next) S.a_ready(nxt);
;             if constexpr (SP2) {
;             PG8_LDB(B0, 0, 0); PG8_LDB(B1, 0, 1); PG8_SCHED; PG8_LDA(At, 0, 0); PG8_STAGE(PG8_SA(1, 1), a1 + hstep, voffA);
;             PG8_WAIT_V(8); PG8_WAIT_L(0); PG8_BAR; PG8_MMA(0, 0, At, B0); PG8_MMA(0, 1, At, B1); PG8_BAR; PG8_SCHED;
;             PG8_LDA(At, 0, 1); PG8_STAGE(PG8_SB(0, 0), b2, voffB); PG8_STAGE(PG8_SB(0, 1), b2 + hstep, voffB); PG8_STAGE(PG8_SA(0, 0), a2, voffA);
.LBB0_1001:
	s_waitcnt lgkmcnt(0)
	ds_read_b128 v[128:131], v191
	ds_read_b128 v[132:135], v191 offset:1024
	ds_read_b128 v[136:139], v191 offset:2048
	ds_read_b128 v[140:143], v191 offset:3072
	ds_read_b128 v[144:147], v192
	ds_read_b128 v[148:151], v192 offset:1024
	ds_read_b128 v[170:173], v192 offset:2048
	ds_read_b128 v[174:177], v192 offset:3072
	s_add_i32 s95, s34, 2
	s_add_u32 s30, s28, 0x100
	s_addc_u32 s31, s29, 0
	s_cmp_eq_u32 s93, s34
	s_cselect_b32 s34, s26, s94
	s_cselect_b32 s37, s25, s31
	s_cselect_b32 s36, s24, s30
	s_cselect_b32 s35, s27, s86
	v_lshl_add_u64 v[218:219], s[28:29], 0, v[164:165]
	s_add_i32 m0, s40, 0xc000
	ds_read_b128 v[178:181], v193
	ds_read_b128 v[182:185], v193 offset:1024
	ds_read_b128 v[186:189], v193 offset:2048
	ds_read_b128 v[196:199], v193 offset:3072
	ds_read_b128 v[200:203], v193 offset:4096
	ds_read_b128 v[204:207], v193 offset:5120
	ds_read_b128 v[208:211], v193 offset:6144
	ds_read_b128 v[214:217], v193 offset:7168
	global_load_lds_dwordx4 v[218:219], off
	v_lshl_add_u64 v[218:219], s[28:29], 0, v[166:167]
	s_add_i32 m0, s40, 0xe000
	s_nop 0
	global_load_lds_dwordx4 v[218:219], off
	s_waitcnt vmcnt(8)
	s_waitcnt lgkmcnt(0)
	s_barrier
	s_setprio 1
	v_mfma_f32_16x16x32_bf16 v[124:127], v[128:131], v[178:181], v[124:127]
	v_mfma_f32_16x16x32_bf16 v[120:123], v[136:139], v[178:181], v[120:123]
	v_mfma_f32_16x16x32_bf16 v[116:119], v[128:131], v[186:189], v[116:119]
	v_mfma_f32_16x16x32_bf16 v[108:111], v[136:139], v[186:189], v[108:111]
	v_mfma_f32_16x16x32_bf16 v[100:103], v[128:131], v[200:203], v[100:103]
	v_mfma_f32_16x16x32_bf16 v[92:95], v[136:139], v[200:203], v[92:95]
	v_mfma_f32_16x16x32_bf16 v[84:87], v[128:131], v[208:211], v[84:87]
	v_mfma_f32_16x16x32_bf16 v[76:79], v[136:139], v[208:211], v[76:79]
	v_mfma_f32_16x16x32_bf16 v[124:127], v[132:135], v[182:185], v[124:127]
	v_mfma_f32_16x16x32_bf16 v[120:123], v[140:143], v[182:185], v[120:123]
	v_mfma_f32_16x16x32_bf16 v[116:119], v[132:135], v[196:199], v[116:119]
	v_mfma_f32_16x16x32_bf16 v[108:111], v[140:143], v[196:199], v[108:111]
	v_mfma_f32_16x16x32_bf16 v[100:103], v[132:135], v[204:207], v[100:103]
	v_mfma_f32_16x16x32_bf16 v[92:95], v[140:143], v[204:207], v[92:95]
	v_mfma_f32_16x16x32_bf16 v[84:87], v[132:135], v[214:217], v[84:87]
	v_mfma_f32_16x16x32_bf16 v[76:79], v[140:143], v[214:217], v[76:79]
	s_setprio 0
	s_setprio 1
	v_mfma_f32_16x16x32_bf16 v[112:115], v[144:147], v[178:181], v[112:115]
	v_mfma_f32_16x16x32_bf16 v[104:107], v[170:173], v[178:181], v[104:107]
	v_mfma_f32_16x16x32_bf16 v[96:99], v[144:147], v[186:189], v[96:99]
	v_mfma_f32_16x16x32_bf16 v[88:91], v[170:173], v[186:189], v[88:91]
	v_mfma_f32_16x16x32_bf16 v[80:83], v[144:147], v[200:203], v[80:83]
	v_mfma_f32_16x16x32_bf16 v[72:75], v[170:173], v[200:203], v[72:75]
	v_mfma_f32_16x16x32_bf16 v[68:71], v[144:147], v[208:211], v[68:71]
	v_mfma_f32_16x16x32_bf16 v[64:67], v[170:173], v[208:211], v[64:67]
	v_mfma_f32_16x16x32_bf16 v[112:115], v[148:151], v[182:185], v[112:115]
	v_mfma_f32_16x16x32_bf16 v[104:107], v[174:177], v[182:185], v[104:107]
	v_mfma_f32_16x16x32_bf16 v[96:99], v[148:151], v[196:199], v[96:99]
	v_mfma_f32_16x16x32_bf16 v[88:91], v[174:177], v[196:199], v[88:91]
	v_mfma_f32_16x16x32_bf16 v[80:83], v[148:151], v[204:207], v[80:83]
	v_mfma_f32_16x16x32_bf16 v[72:75], v[174:177], v[204:207], v[72:75]
	v_mfma_f32_16x16x32_bf16 v[68:71], v[148:151], v[214:217], v[68:71]
	v_mfma_f32_16x16x32_bf16 v[64:67], v[174:177], v[214:217], v[64:67]
	s_setprio 0
	s_barrier
	s_add_i32 s28, s66, s39
	v_lshl_add_u64 v[218:219], s[34:35], 0, v[154:155]
	s_mov_b32 m0, s28
	ds_read_b128 v[178:181], v193 offset:16384
	ds_read_b128 v[182:185], v193 offset:17408
	ds_read_b128 v[186:189], v193 offset:18432
	ds_read_b128 v[196:199], v193 offset:19456
	ds_read_b128 v[200:203], v193 offset:20480
	ds_read_b128 v[204:207], v193 offset:21504
	ds_read_b128 v[208:211], v193 offset:22528
	ds_read_b128 v[214:217], v193 offset:23552
	global_load_lds_dwordx4 v[218:219], off
	s_add_i32 m0, s28, 0x2000
	s_add_u32 s28, s34, 0xb0000
	v_lshl_add_u64 v[220:221], s[34:35], 0, v[162:163]
	s_addc_u32 s29, s35, 0
	s_add_i32 s96, s67, s39
	global_load_lds_dwordx4 v[220:221], off
	v_lshl_add_u64 v[222:223], s[28:29], 0, v[154:155]
	s_mov_b32 m0, s96
	v_lshl_add_u64 v[224:225], s[36:37], 0, v[160:161]
	global_load_lds_dwordx4 v[222:223], off
	v_lshl_add_u64 v[222:223], s[28:29], 0, v[162:163]
	s_add_i32 m0, s96, 0x2000
	s_nop 0
	global_load_lds_dwordx4 v[222:223], off
	v_lshl_add_u64 v[222:223], s[36:37], 0, v[152:153]
	s_mov_b32 m0, s40
	s_nop 0
	global_load_lds_dwordx4 v[222:223], off
	s_mov_b32 m0, s41
	s_nop 0
	global_load_lds_dwordx4 v[224:225], off
	s_waitcnt vmcnt(8)
	s_waitcnt lgkmcnt(0)
	s_barrier
; #define PG8_STAGE(bufoff, gbase, voff) do { _Pragma("unroll") for (int _i = 0; _i < 2; ++_i) \
;         __builtin_amdgcn_global_load_lds((const unsigned*)((const char*)(gbase) + (voff)[_i]), (PG8_LAS unsigned*)(lds + (bufoff) + ldsw + _i * 8192), 16, 0, 0); } while (0)
; #define PG8_LDA(dst, b, h) do { _Pragma("unroll") for (int m = 0; m < 4; ++m) _Pragma("unroll") for (int k = 0; k < 2; ++k) dst[m][k] = *(const PG8_LAS bf16x8*)(lds + PG8_SA(b, h) + aoff + m * 2048 + k * 1024); } while (0)
; #define PG8_LDB(dst, b, h) do { _Pragma("unroll") for (int n = 0; n < 2; ++n) _Pragma("unroll") for (int k = 0; k < 2; ++k) dst[n][k] = *(const PG8_LAS bf16x8*)(lds + PG8_SB(b, h) + boff + n * 2048 + k * 1024); } while (0)
; #define PG8_MMA(ai, bj, At, Bt) do { __builtin_amdgcn_s_setprio(1); _Pragma("unroll") for (int m = 0; m < 4; ++m) _Pragma("unroll") for (int n = 0; n < 2; ++n) _Pragma("unroll") for (int k = 0; k < 2; ++k) \
;         acc[ai][bj][m][n] = __builtin_amdgcn_mfma_f32_16x16x32_bf16(Bt[n][k], At[m][k], acc[ai][bj][m][n], 0, 0, 0); __builtin_amdgcn_s_setprio(0); } while (0)
; #define PG8_WAIT_V(n) asm volatile("s_waitcnt vmcnt(" #n ")" ::: "memory")
; #define PG8_WAIT_L(n) asm volatile("s_waitcnt lgkmcnt(" #n ")" ::: "memory")
; #define PG8_BAR __builtin_amdgcn_s_barrier()
; #define PG8_SCHED __builtin_amdgcn_sched_barrier(0)
; template <class Epi, class Sched, bool ALIGN_EPI = false, bool SP2 = false>
; __device__ __forceinline__ void gemm_phase(PG8_LAS unsigned char* lds, const Gemm g, const Sched& S, const Epi& E) {
;     ...
;             PG8_WAIT_V(8); PG8_WAIT_L(0); PG8_BAR; PG8_MMA(1, 0, At, B0); PG8_MMA(1, 1, At, B1); PG8_BAR; PG8_SCHED;
;             PG8_LDB(B0, 1, 0); PG8_LDB(B1, 1, 1); PG8_SCHED; PG8_LDA(At, 1, 0); PG8_STAGE(PG8_SA(0, 1), a2 + hstep, voffA);
;             PG8_WAIT_V(8); PG8_WAIT_L(0); PG8_BAR; PG8_MMA(0, 0, At, B0); PG8_MMA(0, 1, At, B1); PG8_BAR; PG8_SCHED;
	s_setprio 1
	v_mfma_f32_16x16x32_bf16 v[60:63], v[128:131], v[178:181], v[60:63]
	v_mfma_f32_16x16x32_bf16 v[56:59], v[136:139], v[178:181], v[56:59]
	v_mfma_f32_16x16x32_bf16 v[52:55], v[128:131], v[186:189], v[52:55]
	v_mfma_f32_16x16x32_bf16 v[44:47], v[136:139], v[186:189], v[44:47]
	v_mfma_f32_16x16x32_bf16 v[36:39], v[128:131], v[200:203], v[36:39]
	v_mfma_f32_16x16x32_bf16 v[28:31], v[136:139], v[200:203], v[28:31]
	v_mfma_f32_16x16x32_bf16 v[20:23], v[128:131], v[208:211], v[20:23]
	v_mfma_f32_16x16x32_bf16 v[12:15], v[136:139], v[208:211], v[12:15]
	v_mfma_f32_16x16x32_bf16 v[60:63], v[132:135], v[182:185], v[60:63]
	v_mfma_f32_16x16x32_bf16 v[56:59], v[140:143], v[182:185], v[56:59]
	v_mfma_f32_16x16x32_bf16 v[52:55], v[132:135], v[196:199], v[52:55]
	v_mfma_f32_16x16x32_bf16 v[44:47], v[140:143], v[196:199], v[44:47]
	v_mfma_f32_16x16x32_bf16 v[36:39], v[132:135], v[204:207], v[36:39]
	v_mfma_f32_16x16x32_bf16 v[28:31], v[140:143], v[204:207], v[28:31]
	v_mfma_f32_16x16x32_bf16 v[20:23], v[132:135], v[214:217], v[20:23]
	v_mfma_f32_16x16x32_bf16 v[12:15], v[140:143], v[214:217], v[12:15]
	s_setprio 0
	s_setprio 1
	v_mfma_f32_16x16x32_bf16 v[48:51], v[144:147], v[178:181], v[48:51]
	v_mfma_f32_16x16x32_bf16 v[40:43], v[170:173], v[178:181], v[40:43]
	v_mfma_f32_16x16x32_bf16 v[32:35], v[144:147], v[186:189], v[32:35]
	v_mfma_f32_16x16x32_bf16 v[24:27], v[170:173], v[186:189], v[24:27]
	v_mfma_f32_16x16x32_bf16 v[16:19], v[144:147], v[200:203], v[16:19]
	v_mfma_f32_16x16x32_bf16 v[8:11], v[170:173], v[200:203], v[8:11]
	v_mfma_f32_16x16x32_bf16 v[4:7], v[144:147], v[208:211], v[4:7]
	v_mfma_f32_16x16x32_bf16 v[0:3], v[170:173], v[208:211], v[0:3]
	v_mfma_f32_16x16x32_bf16 v[48:51], v[148:151], v[182:185], v[48:51]
	v_mfma_f32_16x16x32_bf16 v[40:43], v[174:177], v[182:185], v[40:43]
	v_mfma_f32_16x16x32_bf16 v[32:35], v[148:151], v[196:199], v[32:35]
	v_mfma_f32_16x16x32_bf16 v[24:27], v[174:177], v[196:199], v[24:27]
	v_mfma_f32_16x16x32_bf16 v[16:19], v[148:151], v[204:207], v[16:19]
	v_mfma_f32_16x16x32_bf16 v[8:11], v[174:177], v[204:207], v[8:11]
	v_mfma_f32_16x16x32_bf16 v[4:7], v[148:151], v[214:217], v[4:7]
	v_mfma_f32_16x16x32_bf16 v[0:3], v[174:177], v[214:217], v[0:3]
	s_setprio 0
	s_barrier
	s_add_i32 s96, 0, 0x18000
	s_add_i32 s97, 0, 0x1c000
	v_add_u32_e32 v140, s96, v159
	v_add_u32_e32 v174, s97, v159
	ds_read_b128 v[128:131], v140
	ds_read_b128 v[132:135], v140 offset:1024
	ds_read_b128 v[136:139], v140 offset:2048
	ds_read_b128 v[140:143], v140 offset:3072
	ds_read_b128 v[144:147], v174
	ds_read_b128 v[148:151], v174 offset:1024
	ds_read_b128 v[170:173], v174 offset:2048
	ds_read_b128 v[174:177], v174 offset:3072
	s_add_u32 s28, s36, 0xb0000
	s_addc_u32 s29, s37, 0
	s_mov_b32 m0, s44
	v_lshl_add_u64 v[226:227], s[28:29], 0, v[152:153]
	ds_read_b128 v[178:181], v193 offset:32768
	ds_read_b128 v[182:185], v193 offset:33792
	ds_read_b128 v[186:189], v193 offset:34816
	ds_read_b128 v[196:199], v193 offset:35840
	ds_read_b128 v[200:203], v193 offset:36864
	ds_read_b128 v[204:207], v193 offset:37888
	ds_read_b128 v[208:211], v193 offset:38912
	ds_read_b128 v[214:217], v193 offset:39936
	global_load_lds_dwordx4 v[226:227], off
	v_lshl_add_u64 v[226:227], s[28:29], 0, v[160:161]
	s_mov_b32 m0, s45
	s_nop 0
	global_load_lds_dwordx4 v[226:227], off
	s_waitcnt vmcnt(8)
	s_waitcnt lgkmcnt(0)
	s_barrier
	s_setprio 1
	v_mfma_f32_16x16x32_bf16 v[124:127], v[128:131], v[178:181], v[124:127]
	v_mfma_f32_16x16x32_bf16 v[120:123], v[136:139], v[178:181], v[120:123]
	v_mfma_f32_16x16x32_bf16 v[116:119], v[128:131], v[186:189], v[116:119]
	v_mfma_f32_16x16x32_bf16 v[108:111], v[136:139], v[186:189], v[108:111]
	v_mfma_f32_16x16x32_bf16 v[100:103], v[128:131], v[200:203], v[100:103]
	v_mfma_f32_16x16x32_bf16 v[92:95], v[136:139], v[200:203], v[92:95]
	v_mfma_f32_16x16x32_bf16 v[84:87], v[128:131], v[208:211], v[84:87]
	v_mfma_f32_16x16x32_bf16 v[76:79], v[136:139], v[208:211], v[76:79]
	v_mfma_f32_16x16x32_bf16 v[124:127], v[132:135], v[182:185], v[124:127]
	v_mfma_f32_16x16x32_bf16 v[120:123], v[140:143], v[182:185], v[120:123]
	v_mfma_f32_16x16x32_bf16 v[116:119], v[132:135], v[196:199], v[116:119]
	v_mfma_f32_16x16x32_bf16 v[108:111], v[140:143], v[196:199], v[108:111]
	v_mfma_f32_16x16x32_bf16 v[100:103], v[132:135], v[204:207], v[100:103]
	v_mfma_f32_16x16x32_bf16 v[92:95], v[140:143], v[204:207], v[92:95]
	v_mfma_f32_16x16x32_bf16 v[84:87], v[132:135], v[214:217], v[84:87]
	v_mfma_f32_16x16x32_bf16 v[76:79], v[140:143], v[214:217], v[76:79]
	s_setprio 0
	s_setprio 1
	v_mfma_f32_16x16x32_bf16 v[112:115], v[144:147], v[178:181], v[112:115]
	v_mfma_f32_16x16x32_bf16 v[104:107], v[170:173], v[178:181], v[104:107]
	v_mfma_f32_16x16x32_bf16 v[96:99], v[144:147], v[186:189], v[96:99]
	v_mfma_f32_16x16x32_bf16 v[88:91], v[170:173], v[186:189], v[88:91]
	v_mfma_f32_16x16x32_bf16 v[80:83], v[144:147], v[200:203], v[80:83]
	v_mfma_f32_16x16x32_bf16 v[72:75], v[170:173], v[200:203], v[72:75]
	v_mfma_f32_16x16x32_bf16 v[68:71], v[144:147], v[208:211], v[68:71]
	v_mfma_f32_16x16x32_bf16 v[64:67], v[170:173], v[208:211], v[64:67]
	v_mfma_f32_16x16x32_bf16 v[112:115], v[148:151], v[182:185], v[112:115]
	v_mfma_f32_16x16x32_bf16 v[104:107], v[174:177], v[182:185], v[104:107]
	v_mfma_f32_16x16x32_bf16 v[96:99], v[148:151], v[196:199], v[96:99]
	v_mfma_f32_16x16x32_bf16 v[88:91], v[174:177], v[196:199], v[88:91]
	v_mfma_f32_16x16x32_bf16 v[80:83], v[148:151], v[204:207], v[80:83]
	v_mfma_f32_16x16x32_bf16 v[72:75], v[174:177], v[204:207], v[72:75]
	v_mfma_f32_16x16x32_bf16 v[68:71], v[148:151], v[214:217], v[68:71]
	v_mfma_f32_16x16x32_bf16 v[64:67], v[174:177], v[214:217], v[64:67]
	s_setprio 0
	s_barrier
; #define PG8_STAGE(bufoff, gbase, voff) do { _Pragma("unroll") for (int _i = 0; _i < 2; ++_i) \
;         __builtin_amdgcn_global_load_lds((const unsigned*)((const char*)(gbase) + (voff)[_i]), (PG8_LAS unsigned*)(lds + (bufoff) + ldsw + _i * 8192), 16, 0, 0); } while (0)
; #define PG8_LDA(dst, b, h) do { _Pragma("unroll") for (int m = 0; m < 4; ++m) _Pragma("unroll") for (int k = 0; k < 2; ++k) dst[m][k] = *(const PG8_LAS bf16x8*)(lds + PG8_SA(b, h) + aoff + m * 2048 + k * 1024); } while (0)
; #define PG8_MMA(ai, bj, At, Bt) do { __builtin_amdgcn_s_setprio(1); _Pragma("unroll") for (int m = 0; m < 4; ++m) _Pragma("unroll") for (int n = 0; n < 2; ++n) _Pragma("unroll") for (int k = 0; k < 2; ++k) \
;         acc[ai][bj][m][n] = __builtin_amdgcn_mfma_f32_16x16x32_bf16(Bt[n][k], At[m][k], acc[ai][bj][m][n], 0, 0, 0); __builtin_amdgcn_s_setprio(0); } while (0)
; #define PG8_WAIT_V(n) asm volatile("s_waitcnt vmcnt(" #n ")" ::: "memory")
; #define PG8_WAIT_L(n) asm volatile("s_waitcnt lgkmcnt(" #n ")" ::: "memory")
; #define PG8_BAR __builtin_amdgcn_s_barrier()
; #define PG8_SCHED __builtin_amdgcn_sched_barrier(0)
; template <class Epi, class Sched, bool ALIGN_EPI = false, bool SP2 = false>
; __device__ __forceinline__ void gemm_phase(PG8_LAS unsigned char* lds, const Gemm g, const Sched& S, const Epi& E) {
;     ...
;             PG8_LDA(At, 1, 1); PG8_STAGE(PG8_SB(1, 0), b3, voffB); PG8_STAGE(PG8_SB(1, 1), b3 + hstep, voffB); PG8_STAGE(PG8_SA(1, 0), a3, voffA);
;             PG8_WAIT_V(8); PG8_WAIT_L(0); PG8_BAR; PG8_MMA(1, 0, At, B0); PG8_MMA(1, 1, At, B1); PG8_BAR; PG8_SCHED;
;     ...
;         if constexpr (ALIGN_EPI) { if (wr == 0) PG8_BAR; }
	s_add_i32 s28, s96, s39
	v_lshl_add_u64 v[218:219], v[218:219], 0, s[18:19]
	s_mov_b32 m0, s28
	ds_read_b128 v[178:181], v193 offset:49152
	ds_read_b128 v[182:185], v193 offset:50176
	ds_read_b128 v[186:189], v193 offset:51200
	ds_read_b128 v[196:199], v193 offset:52224
	ds_read_b128 v[200:203], v193 offset:53248
	ds_read_b128 v[204:207], v193 offset:54272
	ds_read_b128 v[208:211], v193 offset:55296
	ds_read_b128 v[214:217], v193 offset:56320
	global_load_lds_dwordx4 v[218:219], off
	s_add_i32 m0, s28, 0x2000
	s_add_u32 s28, s34, 0xb0080
	v_lshl_add_u64 v[218:219], v[220:221], 0, s[18:19]
	s_addc_u32 s29, s35, 0
	s_add_i32 s34, s97, s39
	global_load_lds_dwordx4 v[218:219], off
	v_lshl_add_u64 v[218:219], s[28:29], 0, v[154:155]
	s_mov_b32 m0, s34
	s_nop 0
	global_load_lds_dwordx4 v[218:219], off
	v_lshl_add_u64 v[218:219], s[28:29], 0, v[162:163]
	s_add_i32 m0, s34, 0x2000
	s_nop 0
	global_load_lds_dwordx4 v[218:219], off
	v_lshl_add_u64 v[218:219], v[222:223], 0, s[18:19]
	s_mov_b32 m0, s47
	s_nop 0
	global_load_lds_dwordx4 v[218:219], off
	v_lshl_add_u64 v[218:219], v[224:225], 0, s[18:19]
	s_mov_b32 m0, s49
	s_nop 0
	global_load_lds_dwordx4 v[218:219], off
	s_waitcnt vmcnt(8)
	s_waitcnt lgkmcnt(0)
	s_barrier
	s_setprio 1
	v_mfma_f32_16x16x32_bf16 v[60:63], v[128:131], v[178:181], v[60:63]
	v_mfma_f32_16x16x32_bf16 v[56:59], v[136:139], v[178:181], v[56:59]
	v_mfma_f32_16x16x32_bf16 v[52:55], v[128:131], v[186:189], v[52:55]
	v_mfma_f32_16x16x32_bf16 v[44:47], v[136:139], v[186:189], v[44:47]
	v_mfma_f32_16x16x32_bf16 v[36:39], v[128:131], v[200:203], v[36:39]
	v_mfma_f32_16x16x32_bf16 v[28:31], v[136:139], v[200:203], v[28:31]
	v_mfma_f32_16x16x32_bf16 v[20:23], v[128:131], v[208:211], v[20:23]
	v_mfma_f32_16x16x32_bf16 v[12:15], v[136:139], v[208:211], v[12:15]
	v_mfma_f32_16x16x32_bf16 v[60:63], v[132:135], v[182:185], v[60:63]
	v_mfma_f32_16x16x32_bf16 v[56:59], v[140:143], v[182:185], v[56:59]
	v_mfma_f32_16x16x32_bf16 v[52:55], v[132:135], v[196:199], v[52:55]
	v_mfma_f32_16x16x32_bf16 v[44:47], v[140:143], v[196:199], v[44:47]
	v_mfma_f32_16x16x32_bf16 v[36:39], v[132:135], v[204:207], v[36:39]
	v_mfma_f32_16x16x32_bf16 v[28:31], v[140:143], v[204:207], v[28:31]
	v_mfma_f32_16x16x32_bf16 v[20:23], v[132:135], v[214:217], v[20:23]
	v_mfma_f32_16x16x32_bf16 v[12:15], v[140:143], v[214:217], v[12:15]
	s_setprio 0
	s_setprio 1
	v_mfma_f32_16x16x32_bf16 v[48:51], v[144:147], v[178:181], v[48:51]
	v_mfma_f32_16x16x32_bf16 v[40:43], v[170:173], v[178:181], v[40:43]
	v_mfma_f32_16x16x32_bf16 v[32:35], v[144:147], v[186:189], v[32:35]
	v_mfma_f32_16x16x32_bf16 v[24:27], v[170:173], v[186:189], v[24:27]
	v_mfma_f32_16x16x32_bf16 v[16:19], v[144:147], v[200:203], v[16:19]
	v_mfma_f32_16x16x32_bf16 v[8:11], v[170:173], v[200:203], v[8:11]
	v_mfma_f32_16x16x32_bf16 v[4:7], v[144:147], v[208:211], v[4:7]
	v_mfma_f32_16x16x32_bf16 v[0:3], v[170:173], v[208:211], v[0:3]
	v_mfma_f32_16x16x32_bf16 v[48:51], v[148:151], v[182:185], v[48:51]
	v_mfma_f32_16x16x32_bf16 v[40:43], v[174:177], v[182:185], v[40:43]
	v_mfma_f32_16x16x32_bf16 v[32:35], v[148:151], v[196:199], v[32:35]
	v_mfma_f32_16x16x32_bf16 v[24:27], v[174:177], v[196:199], v[24:27]
	v_mfma_f32_16x16x32_bf16 v[16:19], v[148:151], v[204:207], v[16:19]
	v_mfma_f32_16x16x32_bf16 v[8:11], v[174:177], v[204:207], v[8:11]
	v_mfma_f32_16x16x32_bf16 v[4:7], v[148:151], v[214:217], v[4:7]
	v_mfma_f32_16x16x32_bf16 v[0:3], v[174:177], v[214:217], v[0:3]
	s_setprio 0
	s_barrier
	s_add_u32 s94, s94, 0x100
	s_addc_u32 s86, s86, 0
	s_cmp_ge_i32 s95, s92
	s_mov_b64 s[28:29], s[30:31]
	s_mov_b32 s34, s95
	s_cbranch_scc0 .LBB0_1001
	s_and_b64 vcc, exec, s[20:21]
	s_cbranch_vccz .LBB0_1004
	s_barrier
